# scan phase redesign D1: new-state y, f32 kka/kd in LDS with packed f32 updates, v side area, hand-scheduled consumer
# speedup vs baseline: 1.0393x; 1.0393x over previous
.LBB0_56:
	s_and_b64 s[4:5], s[42:43], exec
	s_mov_b32 s4, 0x1caf0000
	s_cselect_b32 s4, s4, 0x14af0000
	s_add_u32 s4, s30, s4
	s_addc_u32 s5, s31, 0
	s_lshl_b32 s6, s37, 1
	v_lshl_add_u32 v0, s64, 4, v58
	s_add_u32 s4, s4, s6
	s_addc_u32 s5, s5, 0
	v_ashrrev_i32_e32 v1, 31, v0
	s_waitcnt lgkmcnt(0)
	s_barrier
	v_lshl_add_u64 v[0:1], v[0:1], 1, s[4:5]
	s_and_b64 s[4:5], s[42:43], exec
	s_movk_i32 s4, 0x4000
	s_mov_b32 s28, 0
	s_cselect_b32 s85, 0, -1
	s_cselect_b32 s84, s4, 0xffffc000
	s_waitcnt vmcnt(0)
	v_mov_b32_e32 v6, 0
	v_mov_b32_e32 v4, v78
	v_mov_b32_e32 v5, v15
	v_mov_b32_e32 v7, 0
	v_mov_b32_e32 v8, 0
	v_mov_b32_e32 v9, 0
	v_lshlrev_b32_e32 v74, 4, v58
	v_add_u32_e32 v74, 0x20100, v74
.Lscan_cons_chunk:
	s_and_b32 s4, s28, 0x10000
	s_lshr_b32 s5, s4, 4
	v_add_u32_e32 v10, s4, v59
	v_add_u32_e32 v11, s5, v74
	v_cndmask_b32_e64 v2, v4, v5, s[42:43]
	ds_read_b128 v[66:69], v11 offset:0
	ds_read_b128 v[20:23], v10 offset:256
	ds_read_b128 v[16:19], v10 offset:0
	ds_read_b128 v[28:31], v10 offset:768
	ds_read_b128 v[24:27], v10 offset:512
	ds_read_b128 v[36:39], v10 offset:1280
	ds_read_b128 v[32:35], v10 offset:1024
	ds_read_b128 v[44:47], v10 offset:1792
	ds_read_b128 v[40:43], v10 offset:1536
	v_add_lshl_u32 v2, v2, s80, 10
	v_mov_b32_e32 v3, v180
	s_add_i32 s28, s28, 0x10000
	v_lshl_add_u64 v[2:3], v[0:1], 0, v[2:3]
	v_add_u32_e32 v5, 64, v5
	v_subrev_u32_e32 v4, 64, v4
	s_waitcnt lgkmcnt(4)
	v_fma_mix_f32 v12, v6, v20, v180 op_sel_hi:[0,1,0]
	v_fma_mix_f32 v12, v7, v20, v12 op_sel:[0,1,0] op_sel_hi:[0,1,0]
	v_fma_mix_f32 v12, v8, v21, v12 op_sel_hi:[0,1,0]
	v_fma_mix_f32 v12, v9, v21, v12 op_sel:[0,1,0] op_sel_hi:[0,1,0]
	s_nop 1
	v_add_f32_dpp v12, v12, v12 row_ror:1 row_mask:0xf bank_mask:0xf bound_ctrl:1
	s_nop 1
	v_add_f32_dpp v12, v12, v12 row_ror:2 row_mask:0xf bank_mask:0xf bound_ctrl:1
	v_pk_mul_f32 v[48:49], v[6:7], v[16:17]
	v_pk_mul_f32 v[50:51], v[8:9], v[18:19]
	v_add_f32_dpp v12, v12, v12 row_ror:4 row_mask:0xf bank_mask:0xf bound_ctrl:1
	v_pk_fma_f32 v[48:49], v[28:29], v[66:67], v[48:49] op_sel_hi:[1,0,1]
	v_pk_fma_f32 v[50:51], v[30:31], v[66:67], v[50:51] op_sel_hi:[1,0,1]
	v_add_f32_dpp v12, v12, v12 row_ror:8 row_mask:0xf bank_mask:0xf bound_ctrl:1
	v_pk_fma_f32 v[6:7], v[24:25], v[12:13], v[48:49] op_sel_hi:[1,0,1] neg_lo:[1,0,0] neg_hi:[1,0,0]
	v_pk_fma_f32 v[8:9], v[26:27], v[12:13], v[50:51] op_sel_hi:[1,0,1] neg_lo:[1,0,0] neg_hi:[1,0,0]
	ds_read_b128 v[88:91], v10 offset:2304
	ds_read_b128 v[84:87], v10 offset:2048
	ds_read_b128 v[96:99], v10 offset:2816
	ds_read_b128 v[92:95], v10 offset:2560
	s_waitcnt lgkmcnt(4)
	v_fma_mix_f32 v12, v6, v36, v180 op_sel_hi:[0,1,0]
	v_fma_mix_f32 v12, v7, v36, v12 op_sel:[0,1,0] op_sel_hi:[0,1,0]
	v_fma_mix_f32 v12, v8, v37, v12 op_sel_hi:[0,1,0]
	v_fma_mix_f32 v12, v9, v37, v12 op_sel:[0,1,0] op_sel_hi:[0,1,0]
	v_fma_mix_f32 v52, v6, v22, v180 op_sel_hi:[0,1,0]
	v_fma_mix_f32 v52, v7, v22, v52 op_sel:[0,1,0] op_sel_hi:[0,1,0]
	v_add_f32_dpp v12, v12, v12 row_ror:1 row_mask:0xf bank_mask:0xf bound_ctrl:1
	v_fma_mix_f32 v52, v8, v23, v52 op_sel_hi:[0,1,0]
	v_fma_mix_f32 v52, v9, v23, v52 op_sel:[0,1,0] op_sel_hi:[0,1,0]
	v_add_f32_dpp v12, v12, v12 row_ror:2 row_mask:0xf bank_mask:0xf bound_ctrl:1
	v_pk_mul_f32 v[48:49], v[6:7], v[32:33]
	v_pk_mul_f32 v[50:51], v[8:9], v[34:35]
	v_add_f32_dpp v12, v12, v12 row_ror:4 row_mask:0xf bank_mask:0xf bound_ctrl:1
	v_pk_fma_f32 v[48:49], v[44:45], v[66:67], v[48:49] op_sel:[0,1,0]
	v_pk_fma_f32 v[50:51], v[46:47], v[66:67], v[50:51] op_sel:[0,1,0]
	v_add_f32_dpp v12, v12, v12 row_ror:8 row_mask:0xf bank_mask:0xf bound_ctrl:1
	v_pk_fma_f32 v[6:7], v[40:41], v[12:13], v[48:49] op_sel_hi:[1,0,1] neg_lo:[1,0,0] neg_hi:[1,0,0]
	v_pk_fma_f32 v[8:9], v[42:43], v[12:13], v[50:51] op_sel_hi:[1,0,1] neg_lo:[1,0,0] neg_hi:[1,0,0]
	ds_read_b128 v[20:23], v10 offset:3328
	ds_read_b128 v[16:19], v10 offset:3072
	ds_read_b128 v[28:31], v10 offset:3840
	ds_read_b128 v[24:27], v10 offset:3584
	ds_read_b128 v[70:73], v11 offset:256
	s_waitcnt lgkmcnt(5)
	v_fma_mix_f32 v12, v6, v88, v180 op_sel_hi:[0,1,0]
	v_fma_mix_f32 v12, v7, v88, v12 op_sel:[0,1,0] op_sel_hi:[0,1,0]
	v_fma_mix_f32 v12, v8, v89, v12 op_sel_hi:[0,1,0]
	v_fma_mix_f32 v12, v9, v89, v12 op_sel:[0,1,0] op_sel_hi:[0,1,0]
	v_fma_mix_f32 v53, v6, v38, v180 op_sel_hi:[0,1,0]
	v_fma_mix_f32 v53, v7, v38, v53 op_sel:[0,1,0] op_sel_hi:[0,1,0]
	v_add_f32_dpp v12, v12, v12 row_ror:1 row_mask:0xf bank_mask:0xf bound_ctrl:1
	v_fma_mix_f32 v53, v8, v39, v53 op_sel_hi:[0,1,0]
	v_fma_mix_f32 v53, v9, v39, v53 op_sel:[0,1,0] op_sel_hi:[0,1,0]
	v_add_f32_dpp v12, v12, v12 row_ror:2 row_mask:0xf bank_mask:0xf bound_ctrl:1
	v_pk_mul_f32 v[48:49], v[6:7], v[84:85]
	v_pk_mul_f32 v[50:51], v[8:9], v[86:87]
	v_add_f32_dpp v12, v12, v12 row_ror:4 row_mask:0xf bank_mask:0xf bound_ctrl:1
	v_pk_fma_f32 v[48:49], v[96:97], v[68:69], v[48:49] op_sel_hi:[1,0,1]
	v_pk_fma_f32 v[50:51], v[98:99], v[68:69], v[50:51] op_sel_hi:[1,0,1]
	v_add_f32_dpp v12, v12, v12 row_ror:8 row_mask:0xf bank_mask:0xf bound_ctrl:1
	v_pk_fma_f32 v[6:7], v[92:93], v[12:13], v[48:49] op_sel_hi:[1,0,1] neg_lo:[1,0,0] neg_hi:[1,0,0]
	v_pk_fma_f32 v[8:9], v[94:95], v[12:13], v[50:51] op_sel_hi:[1,0,1] neg_lo:[1,0,0] neg_hi:[1,0,0]
	ds_read_b128 v[36:39], v10 offset:4352
	ds_read_b128 v[32:35], v10 offset:4096
	ds_read_b128 v[44:47], v10 offset:4864
	ds_read_b128 v[40:43], v10 offset:4608
	s_waitcnt lgkmcnt(5)
	v_fma_mix_f32 v12, v6, v20, v180 op_sel_hi:[0,1,0]
	v_fma_mix_f32 v12, v7, v20, v12 op_sel:[0,1,0] op_sel_hi:[0,1,0]
	v_fma_mix_f32 v12, v8, v21, v12 op_sel_hi:[0,1,0]
	v_fma_mix_f32 v12, v9, v21, v12 op_sel:[0,1,0] op_sel_hi:[0,1,0]
	v_fma_mix_f32 v54, v6, v90, v180 op_sel_hi:[0,1,0]
	v_fma_mix_f32 v54, v7, v90, v54 op_sel:[0,1,0] op_sel_hi:[0,1,0]
	v_add_f32_dpp v12, v12, v12 row_ror:1 row_mask:0xf bank_mask:0xf bound_ctrl:1
	v_fma_mix_f32 v54, v8, v91, v54 op_sel_hi:[0,1,0]
	v_fma_mix_f32 v54, v9, v91, v54 op_sel:[0,1,0] op_sel_hi:[0,1,0]
	v_add_f32_dpp v12, v12, v12 row_ror:2 row_mask:0xf bank_mask:0xf bound_ctrl:1
	v_pk_mul_f32 v[48:49], v[6:7], v[16:17]
	v_pk_mul_f32 v[50:51], v[8:9], v[18:19]
	v_add_f32_dpp v12, v12, v12 row_ror:4 row_mask:0xf bank_mask:0xf bound_ctrl:1
	v_pk_fma_f32 v[48:49], v[28:29], v[68:69], v[48:49] op_sel:[0,1,0]
	v_pk_fma_f32 v[50:51], v[30:31], v[68:69], v[50:51] op_sel:[0,1,0]
	v_add_f32_dpp v12, v12, v12 row_ror:8 row_mask:0xf bank_mask:0xf bound_ctrl:1
	v_pk_fma_f32 v[6:7], v[24:25], v[12:13], v[48:49] op_sel_hi:[1,0,1] neg_lo:[1,0,0] neg_hi:[1,0,0]
	v_pk_fma_f32 v[8:9], v[26:27], v[12:13], v[50:51] op_sel_hi:[1,0,1] neg_lo:[1,0,0] neg_hi:[1,0,0]
	ds_read_b128 v[88:91], v10 offset:5376
	ds_read_b128 v[84:87], v10 offset:5120
	ds_read_b128 v[96:99], v10 offset:5888
	ds_read_b128 v[92:95], v10 offset:5632
	s_waitcnt lgkmcnt(4)
	v_fma_mix_f32 v12, v6, v36, v180 op_sel_hi:[0,1,0]
	v_fma_mix_f32 v12, v7, v36, v12 op_sel:[0,1,0] op_sel_hi:[0,1,0]
	v_fma_mix_f32 v12, v8, v37, v12 op_sel_hi:[0,1,0]
	v_fma_mix_f32 v12, v9, v37, v12 op_sel:[0,1,0] op_sel_hi:[0,1,0]
	v_fma_mix_f32 v55, v6, v22, v180 op_sel_hi:[0,1,0]
	v_fma_mix_f32 v55, v7, v22, v55 op_sel:[0,1,0] op_sel_hi:[0,1,0]
	v_add_f32_dpp v12, v12, v12 row_ror:1 row_mask:0xf bank_mask:0xf bound_ctrl:1
	v_fma_mix_f32 v55, v8, v23, v55 op_sel_hi:[0,1,0]
	v_fma_mix_f32 v55, v9, v23, v55 op_sel:[0,1,0] op_sel_hi:[0,1,0]
	v_add_f32_dpp v12, v12, v12 row_ror:2 row_mask:0xf bank_mask:0xf bound_ctrl:1
	v_pk_mul_f32 v[48:49], v[6:7], v[32:33]
	v_pk_mul_f32 v[50:51], v[8:9], v[34:35]
	v_add_f32_dpp v12, v12, v12 row_ror:4 row_mask:0xf bank_mask:0xf bound_ctrl:1
	v_pk_fma_f32 v[48:49], v[44:45], v[70:71], v[48:49] op_sel_hi:[1,0,1]
	v_pk_fma_f32 v[50:51], v[46:47], v[70:71], v[50:51] op_sel_hi:[1,0,1]
	v_add_f32_dpp v12, v12, v12 row_ror:8 row_mask:0xf bank_mask:0xf bound_ctrl:1
	v_pk_fma_f32 v[6:7], v[40:41], v[12:13], v[48:49] op_sel_hi:[1,0,1] neg_lo:[1,0,0] neg_hi:[1,0,0]
	v_pk_fma_f32 v[8:9], v[42:43], v[12:13], v[50:51] op_sel_hi:[1,0,1] neg_lo:[1,0,0] neg_hi:[1,0,0]
	ds_read_b128 v[20:23], v10 offset:6400
	ds_read_b128 v[16:19], v10 offset:6144
	ds_read_b128 v[28:31], v10 offset:6912
	ds_read_b128 v[24:27], v10 offset:6656
	s_waitcnt lgkmcnt(4)
	v_fma_mix_f32 v12, v6, v88, v180 op_sel_hi:[0,1,0]
	v_fma_mix_f32 v12, v7, v88, v12 op_sel:[0,1,0] op_sel_hi:[0,1,0]
	v_fma_mix_f32 v12, v8, v89, v12 op_sel_hi:[0,1,0]
	v_fma_mix_f32 v12, v9, v89, v12 op_sel:[0,1,0] op_sel_hi:[0,1,0]
	v_fma_mix_f32 v56, v6, v38, v180 op_sel_hi:[0,1,0]
	v_fma_mix_f32 v56, v7, v38, v56 op_sel:[0,1,0] op_sel_hi:[0,1,0]
	v_add_f32_dpp v12, v12, v12 row_ror:1 row_mask:0xf bank_mask:0xf bound_ctrl:1
	v_fma_mix_f32 v56, v8, v39, v56 op_sel_hi:[0,1,0]
	v_fma_mix_f32 v56, v9, v39, v56 op_sel:[0,1,0] op_sel_hi:[0,1,0]
	v_add_f32_dpp v12, v12, v12 row_ror:2 row_mask:0xf bank_mask:0xf bound_ctrl:1
	v_pk_mul_f32 v[48:49], v[6:7], v[84:85]
	v_pk_mul_f32 v[50:51], v[8:9], v[86:87]
	v_add_f32_dpp v12, v12, v12 row_ror:4 row_mask:0xf bank_mask:0xf bound_ctrl:1
	v_pk_fma_f32 v[48:49], v[96:97], v[70:71], v[48:49] op_sel:[0,1,0]
	v_pk_fma_f32 v[50:51], v[98:99], v[70:71], v[50:51] op_sel:[0,1,0]
	v_add_f32_dpp v12, v12, v12 row_ror:8 row_mask:0xf bank_mask:0xf bound_ctrl:1
	v_pk_fma_f32 v[6:7], v[92:93], v[12:13], v[48:49] op_sel_hi:[1,0,1] neg_lo:[1,0,0] neg_hi:[1,0,0]
	v_pk_fma_f32 v[8:9], v[94:95], v[12:13], v[50:51] op_sel_hi:[1,0,1] neg_lo:[1,0,0] neg_hi:[1,0,0]
	ds_read_b128 v[36:39], v10 offset:7424
	ds_read_b128 v[32:35], v10 offset:7168
	ds_read_b128 v[44:47], v10 offset:7936
	ds_read_b128 v[40:43], v10 offset:7680
	ds_read_b128 v[66:69], v11 offset:512
	s_waitcnt lgkmcnt(5)
	v_fma_mix_f32 v12, v6, v20, v180 op_sel_hi:[0,1,0]
	v_fma_mix_f32 v12, v7, v20, v12 op_sel:[0,1,0] op_sel_hi:[0,1,0]
	v_fma_mix_f32 v12, v8, v21, v12 op_sel_hi:[0,1,0]
	v_fma_mix_f32 v12, v9, v21, v12 op_sel:[0,1,0] op_sel_hi:[0,1,0]
	v_fma_mix_f32 v57, v6, v90, v180 op_sel_hi:[0,1,0]
	v_fma_mix_f32 v57, v7, v90, v57 op_sel:[0,1,0] op_sel_hi:[0,1,0]
	v_add_f32_dpp v12, v12, v12 row_ror:1 row_mask:0xf bank_mask:0xf bound_ctrl:1
	v_fma_mix_f32 v57, v8, v91, v57 op_sel_hi:[0,1,0]
	v_fma_mix_f32 v57, v9, v91, v57 op_sel:[0,1,0] op_sel_hi:[0,1,0]
	v_add_f32_dpp v12, v12, v12 row_ror:2 row_mask:0xf bank_mask:0xf bound_ctrl:1
	v_pk_mul_f32 v[48:49], v[6:7], v[16:17]
	v_pk_mul_f32 v[50:51], v[8:9], v[18:19]
	v_add_f32_dpp v12, v12, v12 row_ror:4 row_mask:0xf bank_mask:0xf bound_ctrl:1
	v_pk_fma_f32 v[48:49], v[28:29], v[72:73], v[48:49] op_sel_hi:[1,0,1]
	v_pk_fma_f32 v[50:51], v[30:31], v[72:73], v[50:51] op_sel_hi:[1,0,1]
	v_add_f32_dpp v12, v12, v12 row_ror:8 row_mask:0xf bank_mask:0xf bound_ctrl:1
	v_pk_fma_f32 v[6:7], v[24:25], v[12:13], v[48:49] op_sel_hi:[1,0,1] neg_lo:[1,0,0] neg_hi:[1,0,0]
	v_pk_fma_f32 v[8:9], v[26:27], v[12:13], v[50:51] op_sel_hi:[1,0,1] neg_lo:[1,0,0] neg_hi:[1,0,0]
	ds_read_b128 v[88:91], v10 offset:8448
	ds_read_b128 v[84:87], v10 offset:8192
	ds_read_b128 v[96:99], v10 offset:8960
	ds_read_b128 v[92:95], v10 offset:8704
	s_waitcnt lgkmcnt(5)
	v_fma_mix_f32 v12, v6, v36, v180 op_sel_hi:[0,1,0]
	v_fma_mix_f32 v12, v7, v36, v12 op_sel:[0,1,0] op_sel_hi:[0,1,0]
	v_fma_mix_f32 v12, v8, v37, v12 op_sel_hi:[0,1,0]
	v_fma_mix_f32 v12, v9, v37, v12 op_sel:[0,1,0] op_sel_hi:[0,1,0]
	v_fma_mix_f32 v81, v6, v22, v180 op_sel_hi:[0,1,0]
	v_fma_mix_f32 v81, v7, v22, v81 op_sel:[0,1,0] op_sel_hi:[0,1,0]
	v_add_f32_dpp v12, v12, v12 row_ror:1 row_mask:0xf bank_mask:0xf bound_ctrl:1
	v_fma_mix_f32 v81, v8, v23, v81 op_sel_hi:[0,1,0]
	v_fma_mix_f32 v81, v9, v23, v81 op_sel:[0,1,0] op_sel_hi:[0,1,0]
	v_add_f32_dpp v12, v12, v12 row_ror:2 row_mask:0xf bank_mask:0xf bound_ctrl:1
	v_pk_mul_f32 v[48:49], v[6:7], v[32:33]
	v_pk_mul_f32 v[50:51], v[8:9], v[34:35]
	v_add_f32_dpp v12, v12, v12 row_ror:4 row_mask:0xf bank_mask:0xf bound_ctrl:1
	v_pk_fma_f32 v[48:49], v[44:45], v[72:73], v[48:49] op_sel:[0,1,0]
	v_pk_fma_f32 v[50:51], v[46:47], v[72:73], v[50:51] op_sel:[0,1,0]
	v_add_f32_dpp v12, v12, v12 row_ror:8 row_mask:0xf bank_mask:0xf bound_ctrl:1
	v_pk_fma_f32 v[6:7], v[40:41], v[12:13], v[48:49] op_sel_hi:[1,0,1] neg_lo:[1,0,0] neg_hi:[1,0,0]
	v_pk_fma_f32 v[8:9], v[42:43], v[12:13], v[50:51] op_sel_hi:[1,0,1] neg_lo:[1,0,0] neg_hi:[1,0,0]
	ds_read_b128 v[20:23], v10 offset:9472
	ds_read_b128 v[16:19], v10 offset:9216
	ds_read_b128 v[28:31], v10 offset:9984
	ds_read_b128 v[24:27], v10 offset:9728
	s_waitcnt lgkmcnt(4)
	v_fma_mix_f32 v12, v6, v88, v180 op_sel_hi:[0,1,0]
	v_fma_mix_f32 v12, v7, v88, v12 op_sel:[0,1,0] op_sel_hi:[0,1,0]
	v_fma_mix_f32 v12, v8, v89, v12 op_sel_hi:[0,1,0]
	v_fma_mix_f32 v12, v9, v89, v12 op_sel:[0,1,0] op_sel_hi:[0,1,0]
	v_fma_mix_f32 v82, v6, v38, v180 op_sel_hi:[0,1,0]
	v_fma_mix_f32 v82, v7, v38, v82 op_sel:[0,1,0] op_sel_hi:[0,1,0]
	v_add_f32_dpp v12, v12, v12 row_ror:1 row_mask:0xf bank_mask:0xf bound_ctrl:1
	v_fma_mix_f32 v82, v8, v39, v82 op_sel_hi:[0,1,0]
	v_fma_mix_f32 v82, v9, v39, v82 op_sel:[0,1,0] op_sel_hi:[0,1,0]
	v_add_f32_dpp v12, v12, v12 row_ror:2 row_mask:0xf bank_mask:0xf bound_ctrl:1
	v_pk_mul_f32 v[48:49], v[6:7], v[84:85]
	v_pk_mul_f32 v[50:51], v[8:9], v[86:87]
	v_add_f32_dpp v12, v12, v12 row_ror:4 row_mask:0xf bank_mask:0xf bound_ctrl:1
	v_pk_fma_f32 v[48:49], v[96:97], v[66:67], v[48:49] op_sel_hi:[1,0,1]
	v_pk_fma_f32 v[50:51], v[98:99], v[66:67], v[50:51] op_sel_hi:[1,0,1]
	v_add_f32_dpp v12, v12, v12 row_ror:8 row_mask:0xf bank_mask:0xf bound_ctrl:1
	v_pk_fma_f32 v[6:7], v[92:93], v[12:13], v[48:49] op_sel_hi:[1,0,1] neg_lo:[1,0,0] neg_hi:[1,0,0]
	v_pk_fma_f32 v[8:9], v[94:95], v[12:13], v[50:51] op_sel_hi:[1,0,1] neg_lo:[1,0,0] neg_hi:[1,0,0]
	ds_read_b128 v[36:39], v10 offset:10496
	ds_read_b128 v[32:35], v10 offset:10240
	ds_read_b128 v[44:47], v10 offset:11008
	ds_read_b128 v[40:43], v10 offset:10752
	s_waitcnt lgkmcnt(4)
	v_fma_mix_f32 v12, v6, v20, v180 op_sel_hi:[0,1,0]
	v_fma_mix_f32 v12, v7, v20, v12 op_sel:[0,1,0] op_sel_hi:[0,1,0]
	v_fma_mix_f32 v12, v8, v21, v12 op_sel_hi:[0,1,0]
	v_fma_mix_f32 v12, v9, v21, v12 op_sel:[0,1,0] op_sel_hi:[0,1,0]
	v_fma_mix_f32 v83, v6, v90, v180 op_sel_hi:[0,1,0]
	v_fma_mix_f32 v83, v7, v90, v83 op_sel:[0,1,0] op_sel_hi:[0,1,0]
	v_add_f32_dpp v12, v12, v12 row_ror:1 row_mask:0xf bank_mask:0xf bound_ctrl:1
	v_fma_mix_f32 v83, v8, v91, v83 op_sel_hi:[0,1,0]
	v_fma_mix_f32 v83, v9, v91, v83 op_sel:[0,1,0] op_sel_hi:[0,1,0]
	v_add_f32_dpp v12, v12, v12 row_ror:2 row_mask:0xf bank_mask:0xf bound_ctrl:1
	v_pk_mul_f32 v[48:49], v[6:7], v[16:17]
	v_pk_mul_f32 v[50:51], v[8:9], v[18:19]
	v_add_f32_dpp v12, v12, v12 row_ror:4 row_mask:0xf bank_mask:0xf bound_ctrl:1
	v_pk_fma_f32 v[48:49], v[28:29], v[66:67], v[48:49] op_sel:[0,1,0]
	v_pk_fma_f32 v[50:51], v[30:31], v[66:67], v[50:51] op_sel:[0,1,0]
	v_add_f32_dpp v12, v12, v12 row_ror:8 row_mask:0xf bank_mask:0xf bound_ctrl:1
	v_pk_fma_f32 v[6:7], v[24:25], v[12:13], v[48:49] op_sel_hi:[1,0,1] neg_lo:[1,0,0] neg_hi:[1,0,0]
	v_pk_fma_f32 v[8:9], v[26:27], v[12:13], v[50:51] op_sel_hi:[1,0,1] neg_lo:[1,0,0] neg_hi:[1,0,0]
	ds_read_b128 v[88:91], v10 offset:11520
	ds_read_b128 v[84:87], v10 offset:11264
	ds_read_b128 v[96:99], v10 offset:12032
	ds_read_b128 v[92:95], v10 offset:11776
	ds_read_b128 v[70:73], v11 offset:768
	s_waitcnt lgkmcnt(5)
	v_fma_mix_f32 v12, v6, v36, v180 op_sel_hi:[0,1,0]
	v_fma_mix_f32 v12, v7, v36, v12 op_sel:[0,1,0] op_sel_hi:[0,1,0]
	v_fma_mix_f32 v12, v8, v37, v12 op_sel_hi:[0,1,0]
	v_fma_mix_f32 v12, v9, v37, v12 op_sel:[0,1,0] op_sel_hi:[0,1,0]
	v_fma_mix_f32 v100, v6, v22, v180 op_sel_hi:[0,1,0]
	v_fma_mix_f32 v100, v7, v22, v100 op_sel:[0,1,0] op_sel_hi:[0,1,0]
	v_add_f32_dpp v12, v12, v12 row_ror:1 row_mask:0xf bank_mask:0xf bound_ctrl:1
	v_fma_mix_f32 v100, v8, v23, v100 op_sel_hi:[0,1,0]
	v_fma_mix_f32 v100, v9, v23, v100 op_sel:[0,1,0] op_sel_hi:[0,1,0]
	v_add_f32_dpp v12, v12, v12 row_ror:2 row_mask:0xf bank_mask:0xf bound_ctrl:1
	v_pk_mul_f32 v[48:49], v[6:7], v[32:33]
	v_pk_mul_f32 v[50:51], v[8:9], v[34:35]
	v_add_f32_dpp v12, v12, v12 row_ror:4 row_mask:0xf bank_mask:0xf bound_ctrl:1
	v_pk_fma_f32 v[48:49], v[44:45], v[68:69], v[48:49] op_sel_hi:[1,0,1]
	v_pk_fma_f32 v[50:51], v[46:47], v[68:69], v[50:51] op_sel_hi:[1,0,1]
	v_add_f32_dpp v12, v12, v12 row_ror:8 row_mask:0xf bank_mask:0xf bound_ctrl:1
	v_pk_fma_f32 v[6:7], v[40:41], v[12:13], v[48:49] op_sel_hi:[1,0,1] neg_lo:[1,0,0] neg_hi:[1,0,0]
	v_pk_fma_f32 v[8:9], v[42:43], v[12:13], v[50:51] op_sel_hi:[1,0,1] neg_lo:[1,0,0] neg_hi:[1,0,0]
	ds_read_b128 v[20:23], v10 offset:12544
	ds_read_b128 v[16:19], v10 offset:12288
	ds_read_b128 v[28:31], v10 offset:13056
	ds_read_b128 v[24:27], v10 offset:12800
	s_waitcnt lgkmcnt(5)
	v_fma_mix_f32 v12, v6, v88, v180 op_sel_hi:[0,1,0]
	v_fma_mix_f32 v12, v7, v88, v12 op_sel:[0,1,0] op_sel_hi:[0,1,0]
	v_fma_mix_f32 v12, v8, v89, v12 op_sel_hi:[0,1,0]
	v_fma_mix_f32 v12, v9, v89, v12 op_sel:[0,1,0] op_sel_hi:[0,1,0]
	v_fma_mix_f32 v101, v6, v38, v180 op_sel_hi:[0,1,0]
	v_fma_mix_f32 v101, v7, v38, v101 op_sel:[0,1,0] op_sel_hi:[0,1,0]
	v_add_f32_dpp v12, v12, v12 row_ror:1 row_mask:0xf bank_mask:0xf bound_ctrl:1
	v_fma_mix_f32 v101, v8, v39, v101 op_sel_hi:[0,1,0]
	v_fma_mix_f32 v101, v9, v39, v101 op_sel:[0,1,0] op_sel_hi:[0,1,0]
	v_add_f32_dpp v12, v12, v12 row_ror:2 row_mask:0xf bank_mask:0xf bound_ctrl:1
	v_pk_mul_f32 v[48:49], v[6:7], v[84:85]
	v_pk_mul_f32 v[50:51], v[8:9], v[86:87]
	v_add_f32_dpp v12, v12, v12 row_ror:4 row_mask:0xf bank_mask:0xf bound_ctrl:1
	v_pk_fma_f32 v[48:49], v[96:97], v[68:69], v[48:49] op_sel:[0,1,0]
	v_pk_fma_f32 v[50:51], v[98:99], v[68:69], v[50:51] op_sel:[0,1,0]
	v_add_f32_dpp v12, v12, v12 row_ror:8 row_mask:0xf bank_mask:0xf bound_ctrl:1
	v_pk_fma_f32 v[6:7], v[92:93], v[12:13], v[48:49] op_sel_hi:[1,0,1] neg_lo:[1,0,0] neg_hi:[1,0,0]
	v_pk_fma_f32 v[8:9], v[94:95], v[12:13], v[50:51] op_sel_hi:[1,0,1] neg_lo:[1,0,0] neg_hi:[1,0,0]
	ds_read_b128 v[36:39], v10 offset:13568
	ds_read_b128 v[32:35], v10 offset:13312
	ds_read_b128 v[44:47], v10 offset:14080
	ds_read_b128 v[40:43], v10 offset:13824
	s_waitcnt lgkmcnt(4)
	v_fma_mix_f32 v12, v6, v20, v180 op_sel_hi:[0,1,0]
	v_fma_mix_f32 v12, v7, v20, v12 op_sel:[0,1,0] op_sel_hi:[0,1,0]
	v_fma_mix_f32 v12, v8, v21, v12 op_sel_hi:[0,1,0]
	v_fma_mix_f32 v12, v9, v21, v12 op_sel:[0,1,0] op_sel_hi:[0,1,0]
	v_fma_mix_f32 v102, v6, v90, v180 op_sel_hi:[0,1,0]
	v_fma_mix_f32 v102, v7, v90, v102 op_sel:[0,1,0] op_sel_hi:[0,1,0]
	v_add_f32_dpp v12, v12, v12 row_ror:1 row_mask:0xf bank_mask:0xf bound_ctrl:1
	v_fma_mix_f32 v102, v8, v91, v102 op_sel_hi:[0,1,0]
	v_fma_mix_f32 v102, v9, v91, v102 op_sel:[0,1,0] op_sel_hi:[0,1,0]
	v_add_f32_dpp v12, v12, v12 row_ror:2 row_mask:0xf bank_mask:0xf bound_ctrl:1
	v_pk_mul_f32 v[48:49], v[6:7], v[16:17]
	v_pk_mul_f32 v[50:51], v[8:9], v[18:19]
	v_add_f32_dpp v12, v12, v12 row_ror:4 row_mask:0xf bank_mask:0xf bound_ctrl:1
	v_pk_fma_f32 v[48:49], v[28:29], v[70:71], v[48:49] op_sel_hi:[1,0,1]
	v_pk_fma_f32 v[50:51], v[30:31], v[70:71], v[50:51] op_sel_hi:[1,0,1]
	v_add_f32_dpp v12, v12, v12 row_ror:8 row_mask:0xf bank_mask:0xf bound_ctrl:1
	v_pk_fma_f32 v[6:7], v[24:25], v[12:13], v[48:49] op_sel_hi:[1,0,1] neg_lo:[1,0,0] neg_hi:[1,0,0]
	v_pk_fma_f32 v[8:9], v[26:27], v[12:13], v[50:51] op_sel_hi:[1,0,1] neg_lo:[1,0,0] neg_hi:[1,0,0]
	ds_read_b128 v[88:91], v10 offset:14592
	ds_read_b128 v[84:87], v10 offset:14336
	ds_read_b128 v[96:99], v10 offset:15104
	ds_read_b128 v[92:95], v10 offset:14848
	s_waitcnt lgkmcnt(4)
	v_fma_mix_f32 v12, v6, v36, v180 op_sel_hi:[0,1,0]
	v_fma_mix_f32 v12, v7, v36, v12 op_sel:[0,1,0] op_sel_hi:[0,1,0]
	v_fma_mix_f32 v12, v8, v37, v12 op_sel_hi:[0,1,0]
	v_fma_mix_f32 v12, v9, v37, v12 op_sel:[0,1,0] op_sel_hi:[0,1,0]
	v_fma_mix_f32 v103, v6, v22, v180 op_sel_hi:[0,1,0]
	v_fma_mix_f32 v103, v7, v22, v103 op_sel:[0,1,0] op_sel_hi:[0,1,0]
	v_add_f32_dpp v12, v12, v12 row_ror:1 row_mask:0xf bank_mask:0xf bound_ctrl:1
	v_fma_mix_f32 v103, v8, v23, v103 op_sel_hi:[0,1,0]
	v_fma_mix_f32 v103, v9, v23, v103 op_sel:[0,1,0] op_sel_hi:[0,1,0]
	v_add_f32_dpp v12, v12, v12 row_ror:2 row_mask:0xf bank_mask:0xf bound_ctrl:1
	v_pk_mul_f32 v[48:49], v[6:7], v[32:33]
	v_pk_mul_f32 v[50:51], v[8:9], v[34:35]
	v_add_f32_dpp v12, v12, v12 row_ror:4 row_mask:0xf bank_mask:0xf bound_ctrl:1
	v_pk_fma_f32 v[48:49], v[44:45], v[70:71], v[48:49] op_sel:[0,1,0]
	v_pk_fma_f32 v[50:51], v[46:47], v[70:71], v[50:51] op_sel:[0,1,0]
	v_add_f32_dpp v12, v12, v12 row_ror:8 row_mask:0xf bank_mask:0xf bound_ctrl:1
	v_pk_fma_f32 v[6:7], v[40:41], v[12:13], v[48:49] op_sel_hi:[1,0,1] neg_lo:[1,0,0] neg_hi:[1,0,0]
	v_pk_fma_f32 v[8:9], v[42:43], v[12:13], v[50:51] op_sel_hi:[1,0,1] neg_lo:[1,0,0] neg_hi:[1,0,0]
	ds_read_b128 v[20:23], v10 offset:15616
	ds_read_b128 v[16:19], v10 offset:15360
	ds_read_b128 v[28:31], v10 offset:16128
	ds_read_b128 v[24:27], v10 offset:15872
	ds_read_b128 v[66:69], v11 offset:1024
	s_waitcnt lgkmcnt(5)
	v_fma_mix_f32 v12, v6, v88, v180 op_sel_hi:[0,1,0]
	v_fma_mix_f32 v12, v7, v88, v12 op_sel:[0,1,0] op_sel_hi:[0,1,0]
	v_fma_mix_f32 v12, v8, v89, v12 op_sel_hi:[0,1,0]
	v_fma_mix_f32 v12, v9, v89, v12 op_sel:[0,1,0] op_sel_hi:[0,1,0]
	v_fma_mix_f32 v104, v6, v38, v180 op_sel_hi:[0,1,0]
	v_fma_mix_f32 v104, v7, v38, v104 op_sel:[0,1,0] op_sel_hi:[0,1,0]
	v_add_f32_dpp v12, v12, v12 row_ror:1 row_mask:0xf bank_mask:0xf bound_ctrl:1
	v_fma_mix_f32 v104, v8, v39, v104 op_sel_hi:[0,1,0]
	v_fma_mix_f32 v104, v9, v39, v104 op_sel:[0,1,0] op_sel_hi:[0,1,0]
	v_add_f32_dpp v12, v12, v12 row_ror:2 row_mask:0xf bank_mask:0xf bound_ctrl:1
	v_pk_mul_f32 v[48:49], v[6:7], v[84:85]
	v_pk_mul_f32 v[50:51], v[8:9], v[86:87]
	v_add_f32_dpp v12, v12, v12 row_ror:4 row_mask:0xf bank_mask:0xf bound_ctrl:1
	v_pk_fma_f32 v[48:49], v[96:97], v[72:73], v[48:49] op_sel_hi:[1,0,1]
	v_pk_fma_f32 v[50:51], v[98:99], v[72:73], v[50:51] op_sel_hi:[1,0,1]
	v_add_f32_dpp v12, v12, v12 row_ror:8 row_mask:0xf bank_mask:0xf bound_ctrl:1
	v_pk_fma_f32 v[6:7], v[92:93], v[12:13], v[48:49] op_sel_hi:[1,0,1] neg_lo:[1,0,0] neg_hi:[1,0,0]
	v_pk_fma_f32 v[8:9], v[94:95], v[12:13], v[50:51] op_sel_hi:[1,0,1] neg_lo:[1,0,0] neg_hi:[1,0,0]
	ds_read_b128 v[36:39], v10 offset:16640
	ds_read_b128 v[32:35], v10 offset:16384
	ds_read_b128 v[44:47], v10 offset:17152
	ds_read_b128 v[40:43], v10 offset:16896
	s_waitcnt lgkmcnt(5)
	v_fma_mix_f32 v12, v6, v20, v180 op_sel_hi:[0,1,0]
	v_fma_mix_f32 v12, v7, v20, v12 op_sel:[0,1,0] op_sel_hi:[0,1,0]
	v_fma_mix_f32 v12, v8, v21, v12 op_sel_hi:[0,1,0]
	v_fma_mix_f32 v12, v9, v21, v12 op_sel:[0,1,0] op_sel_hi:[0,1,0]
	v_fma_mix_f32 v105, v6, v90, v180 op_sel_hi:[0,1,0]
	v_fma_mix_f32 v105, v7, v90, v105 op_sel:[0,1,0] op_sel_hi:[0,1,0]
	v_add_f32_dpp v12, v12, v12 row_ror:1 row_mask:0xf bank_mask:0xf bound_ctrl:1
	v_fma_mix_f32 v105, v8, v91, v105 op_sel_hi:[0,1,0]
	v_fma_mix_f32 v105, v9, v91, v105 op_sel:[0,1,0] op_sel_hi:[0,1,0]
	v_add_f32_dpp v12, v12, v12 row_ror:2 row_mask:0xf bank_mask:0xf bound_ctrl:1
	v_pk_mul_f32 v[48:49], v[6:7], v[16:17]
	v_pk_mul_f32 v[50:51], v[8:9], v[18:19]
	v_add_f32_dpp v12, v12, v12 row_ror:4 row_mask:0xf bank_mask:0xf bound_ctrl:1
	v_pk_fma_f32 v[48:49], v[28:29], v[72:73], v[48:49] op_sel:[0,1,0]
	v_pk_fma_f32 v[50:51], v[30:31], v[72:73], v[50:51] op_sel:[0,1,0]
	v_add_f32_dpp v12, v12, v12 row_ror:8 row_mask:0xf bank_mask:0xf bound_ctrl:1
	v_pk_fma_f32 v[6:7], v[24:25], v[12:13], v[48:49] op_sel_hi:[1,0,1] neg_lo:[1,0,0] neg_hi:[1,0,0]
	v_pk_fma_f32 v[8:9], v[26:27], v[12:13], v[50:51] op_sel_hi:[1,0,1] neg_lo:[1,0,0] neg_hi:[1,0,0]
	ds_read_b128 v[88:91], v10 offset:17664
	ds_read_b128 v[84:87], v10 offset:17408
	ds_read_b128 v[96:99], v10 offset:18176
	ds_read_b128 v[92:95], v10 offset:17920
	s_waitcnt lgkmcnt(4)
	v_fma_mix_f32 v12, v6, v36, v180 op_sel_hi:[0,1,0]
	v_fma_mix_f32 v12, v7, v36, v12 op_sel:[0,1,0] op_sel_hi:[0,1,0]
	v_fma_mix_f32 v12, v8, v37, v12 op_sel_hi:[0,1,0]
	v_fma_mix_f32 v12, v9, v37, v12 op_sel:[0,1,0] op_sel_hi:[0,1,0]
	v_fma_mix_f32 v61, v6, v22, v180 op_sel_hi:[0,1,0]
	v_fma_mix_f32 v61, v7, v22, v61 op_sel:[0,1,0] op_sel_hi:[0,1,0]
	v_add_f32_dpp v12, v12, v12 row_ror:1 row_mask:0xf bank_mask:0xf bound_ctrl:1
	v_fma_mix_f32 v61, v8, v23, v61 op_sel_hi:[0,1,0]
	v_fma_mix_f32 v61, v9, v23, v61 op_sel:[0,1,0] op_sel_hi:[0,1,0]
	v_add_f32_dpp v12, v12, v12 row_ror:2 row_mask:0xf bank_mask:0xf bound_ctrl:1
	v_pk_mul_f32 v[48:49], v[6:7], v[32:33]
	v_pk_mul_f32 v[50:51], v[8:9], v[34:35]
	v_add_f32_dpp v12, v12, v12 row_ror:4 row_mask:0xf bank_mask:0xf bound_ctrl:1
	v_pk_fma_f32 v[48:49], v[44:45], v[66:67], v[48:49] op_sel_hi:[1,0,1]
	v_pk_fma_f32 v[50:51], v[46:47], v[66:67], v[50:51] op_sel_hi:[1,0,1]
	v_add_f32_dpp v12, v12, v12 row_ror:8 row_mask:0xf bank_mask:0xf bound_ctrl:1
	v_pk_fma_f32 v[6:7], v[40:41], v[12:13], v[48:49] op_sel_hi:[1,0,1] neg_lo:[1,0,0] neg_hi:[1,0,0]
	v_pk_fma_f32 v[8:9], v[42:43], v[12:13], v[50:51] op_sel_hi:[1,0,1] neg_lo:[1,0,0] neg_hi:[1,0,0]
	ds_read_b128 v[20:23], v10 offset:18688
	ds_read_b128 v[16:19], v10 offset:18432
	ds_read_b128 v[28:31], v10 offset:19200
	ds_read_b128 v[24:27], v10 offset:18944
	v_add_f32_dpp v83, v83, v83 row_ror:8 row_mask:0xf bank_mask:0xc
	v_add_f32_dpp v83, v52, v52 row_ror:8 row_mask:0xf bank_mask:0x3
	v_add_f32_dpp v100, v100, v100 row_ror:8 row_mask:0xf bank_mask:0xc
	v_add_f32_dpp v100, v53, v53 row_ror:8 row_mask:0xf bank_mask:0x3
	v_add_f32_dpp v101, v101, v101 row_ror:8 row_mask:0xf bank_mask:0xc
	v_add_f32_dpp v101, v54, v54 row_ror:8 row_mask:0xf bank_mask:0x3
	v_add_f32_dpp v102, v102, v102 row_ror:8 row_mask:0xf bank_mask:0xc
	v_add_f32_dpp v102, v55, v55 row_ror:8 row_mask:0xf bank_mask:0x3
	v_add_f32_dpp v103, v103, v103 row_ror:8 row_mask:0xf bank_mask:0xc
	v_add_f32_dpp v103, v56, v56 row_ror:8 row_mask:0xf bank_mask:0x3
	v_add_f32_dpp v104, v104, v104 row_ror:8 row_mask:0xf bank_mask:0xc
	v_add_f32_dpp v104, v57, v57 row_ror:8 row_mask:0xf bank_mask:0x3
	v_add_f32_dpp v105, v105, v105 row_ror:8 row_mask:0xf bank_mask:0xc
	v_add_f32_dpp v105, v81, v81 row_ror:8 row_mask:0xf bank_mask:0x3
	v_add_f32_dpp v61, v61, v61 row_ror:8 row_mask:0xf bank_mask:0xc
	v_add_f32_dpp v61, v82, v82 row_ror:8 row_mask:0xf bank_mask:0x3
	v_add_f32_dpp v103, v103, v103 row_ror:4 row_mask:0xf bank_mask:0xa
	v_add_f32_dpp v103, v83, v83 row_ror:12 row_mask:0xf bank_mask:0x5
	v_add_f32_dpp v104, v104, v104 row_ror:4 row_mask:0xf bank_mask:0xa
	v_add_f32_dpp v104, v100, v100 row_ror:12 row_mask:0xf bank_mask:0x5
	v_add_f32_dpp v105, v105, v105 row_ror:4 row_mask:0xf bank_mask:0xa
	v_add_f32_dpp v105, v101, v101 row_ror:12 row_mask:0xf bank_mask:0x5
	v_add_f32_dpp v61, v61, v61 row_ror:4 row_mask:0xf bank_mask:0xa
	v_add_f32_dpp v61, v102, v102 row_ror:12 row_mask:0xf bank_mask:0x5
	v_cndmask_b32_e64 v62, v105, v103, s[38:39]
	v_cndmask_b32_e64 v63, v103, v105, s[38:39]
	v_cndmask_b32_e64 v64, v61, v104, s[38:39]
	v_cndmask_b32_e64 v65, v104, v61, s[38:39]
	v_add_f32_dpp v62, v63, v62 quad_perm:[2,3,0,1] row_mask:0xf bank_mask:0xf bound_ctrl:1
	s_nop 0
	v_add_f32_dpp v63, v65, v64 quad_perm:[2,3,0,1] row_mask:0xf bank_mask:0xf bound_ctrl:1
	v_cndmask_b32_e64 v65, v63, v62, s[40:41]
	v_cndmask_b32_e64 v62, v62, v63, s[40:41]
	s_nop 1
	v_add_f32_dpp v62, v62, v65 quad_perm:[1,0,3,2] row_mask:0xf bank_mask:0xf bound_ctrl:1
	v_cvt_pk_bf16_f32 v62, v62, v62
	global_store_short v[2:3], v62, off
	v_lshl_add_u64 v[2:3], v[2:3], 0, s[84:85]
	s_waitcnt lgkmcnt(4)
	v_fma_mix_f32 v12, v6, v88, v180 op_sel_hi:[0,1,0]
	v_fma_mix_f32 v12, v7, v88, v12 op_sel:[0,1,0] op_sel_hi:[0,1,0]
	v_fma_mix_f32 v12, v8, v89, v12 op_sel_hi:[0,1,0]
	v_fma_mix_f32 v12, v9, v89, v12 op_sel:[0,1,0] op_sel_hi:[0,1,0]
	v_fma_mix_f32 v52, v6, v38, v180 op_sel_hi:[0,1,0]
	v_fma_mix_f32 v52, v7, v38, v52 op_sel:[0,1,0] op_sel_hi:[0,1,0]
	v_add_f32_dpp v12, v12, v12 row_ror:1 row_mask:0xf bank_mask:0xf bound_ctrl:1
	v_fma_mix_f32 v52, v8, v39, v52 op_sel_hi:[0,1,0]
	v_fma_mix_f32 v52, v9, v39, v52 op_sel:[0,1,0] op_sel_hi:[0,1,0]
	v_add_f32_dpp v12, v12, v12 row_ror:2 row_mask:0xf bank_mask:0xf bound_ctrl:1
	v_pk_mul_f32 v[48:49], v[6:7], v[84:85]
	v_pk_mul_f32 v[50:51], v[8:9], v[86:87]
	v_add_f32_dpp v12, v12, v12 row_ror:4 row_mask:0xf bank_mask:0xf bound_ctrl:1
	v_pk_fma_f32 v[48:49], v[96:97], v[66:67], v[48:49] op_sel:[0,1,0]
	v_pk_fma_f32 v[50:51], v[98:99], v[66:67], v[50:51] op_sel:[0,1,0]
	v_add_f32_dpp v12, v12, v12 row_ror:8 row_mask:0xf bank_mask:0xf bound_ctrl:1
	v_pk_fma_f32 v[6:7], v[92:93], v[12:13], v[48:49] op_sel_hi:[1,0,1] neg_lo:[1,0,0] neg_hi:[1,0,0]
	v_pk_fma_f32 v[8:9], v[94:95], v[12:13], v[50:51] op_sel_hi:[1,0,1] neg_lo:[1,0,0] neg_hi:[1,0,0]
	ds_read_b128 v[36:39], v10 offset:19712
	ds_read_b128 v[32:35], v10 offset:19456
	ds_read_b128 v[44:47], v10 offset:20224
	ds_read_b128 v[40:43], v10 offset:19968
	ds_read_b128 v[70:73], v11 offset:1280
	s_waitcnt lgkmcnt(5)
	v_fma_mix_f32 v12, v6, v20, v180 op_sel_hi:[0,1,0]
	v_fma_mix_f32 v12, v7, v20, v12 op_sel:[0,1,0] op_sel_hi:[0,1,0]
	v_fma_mix_f32 v12, v8, v21, v12 op_sel_hi:[0,1,0]
	v_fma_mix_f32 v12, v9, v21, v12 op_sel:[0,1,0] op_sel_hi:[0,1,0]
	v_fma_mix_f32 v53, v6, v90, v180 op_sel_hi:[0,1,0]
	v_fma_mix_f32 v53, v7, v90, v53 op_sel:[0,1,0] op_sel_hi:[0,1,0]
	v_add_f32_dpp v12, v12, v12 row_ror:1 row_mask:0xf bank_mask:0xf bound_ctrl:1
	v_fma_mix_f32 v53, v8, v91, v53 op_sel_hi:[0,1,0]
	v_fma_mix_f32 v53, v9, v91, v53 op_sel:[0,1,0] op_sel_hi:[0,1,0]
	v_add_f32_dpp v12, v12, v12 row_ror:2 row_mask:0xf bank_mask:0xf bound_ctrl:1
	v_pk_mul_f32 v[48:49], v[6:7], v[16:17]
	v_pk_mul_f32 v[50:51], v[8:9], v[18:19]
	v_add_f32_dpp v12, v12, v12 row_ror:4 row_mask:0xf bank_mask:0xf bound_ctrl:1
	v_pk_fma_f32 v[48:49], v[28:29], v[68:69], v[48:49] op_sel_hi:[1,0,1]
	v_pk_fma_f32 v[50:51], v[30:31], v[68:69], v[50:51] op_sel_hi:[1,0,1]
	v_add_f32_dpp v12, v12, v12 row_ror:8 row_mask:0xf bank_mask:0xf bound_ctrl:1
	v_pk_fma_f32 v[6:7], v[24:25], v[12:13], v[48:49] op_sel_hi:[1,0,1] neg_lo:[1,0,0] neg_hi:[1,0,0]
	v_pk_fma_f32 v[8:9], v[26:27], v[12:13], v[50:51] op_sel_hi:[1,0,1] neg_lo:[1,0,0] neg_hi:[1,0,0]
	ds_read_b128 v[88:91], v10 offset:20736
	ds_read_b128 v[84:87], v10 offset:20480
	ds_read_b128 v[96:99], v10 offset:21248
	ds_read_b128 v[92:95], v10 offset:20992
	s_waitcnt lgkmcnt(5)
	v_fma_mix_f32 v12, v6, v36, v180 op_sel_hi:[0,1,0]
	v_fma_mix_f32 v12, v7, v36, v12 op_sel:[0,1,0] op_sel_hi:[0,1,0]
	v_fma_mix_f32 v12, v8, v37, v12 op_sel_hi:[0,1,0]
	v_fma_mix_f32 v12, v9, v37, v12 op_sel:[0,1,0] op_sel_hi:[0,1,0]
	v_fma_mix_f32 v54, v6, v22, v180 op_sel_hi:[0,1,0]
	v_fma_mix_f32 v54, v7, v22, v54 op_sel:[0,1,0] op_sel_hi:[0,1,0]
	v_add_f32_dpp v12, v12, v12 row_ror:1 row_mask:0xf bank_mask:0xf bound_ctrl:1
	v_fma_mix_f32 v54, v8, v23, v54 op_sel_hi:[0,1,0]
	v_fma_mix_f32 v54, v9, v23, v54 op_sel:[0,1,0] op_sel_hi:[0,1,0]
	v_add_f32_dpp v12, v12, v12 row_ror:2 row_mask:0xf bank_mask:0xf bound_ctrl:1
	v_pk_mul_f32 v[48:49], v[6:7], v[32:33]
	v_pk_mul_f32 v[50:51], v[8:9], v[34:35]
	v_add_f32_dpp v12, v12, v12 row_ror:4 row_mask:0xf bank_mask:0xf bound_ctrl:1
	v_pk_fma_f32 v[48:49], v[44:45], v[68:69], v[48:49] op_sel:[0,1,0]
	v_pk_fma_f32 v[50:51], v[46:47], v[68:69], v[50:51] op_sel:[0,1,0]
	v_add_f32_dpp v12, v12, v12 row_ror:8 row_mask:0xf bank_mask:0xf bound_ctrl:1
	v_pk_fma_f32 v[6:7], v[40:41], v[12:13], v[48:49] op_sel_hi:[1,0,1] neg_lo:[1,0,0] neg_hi:[1,0,0]
	v_pk_fma_f32 v[8:9], v[42:43], v[12:13], v[50:51] op_sel_hi:[1,0,1] neg_lo:[1,0,0] neg_hi:[1,0,0]
	ds_read_b128 v[20:23], v10 offset:21760
	ds_read_b128 v[16:19], v10 offset:21504
	ds_read_b128 v[28:31], v10 offset:22272
	ds_read_b128 v[24:27], v10 offset:22016
	s_waitcnt lgkmcnt(4)
	v_fma_mix_f32 v12, v6, v88, v180 op_sel_hi:[0,1,0]
	v_fma_mix_f32 v12, v7, v88, v12 op_sel:[0,1,0] op_sel_hi:[0,1,0]
	v_fma_mix_f32 v12, v8, v89, v12 op_sel_hi:[0,1,0]
	v_fma_mix_f32 v12, v9, v89, v12 op_sel:[0,1,0] op_sel_hi:[0,1,0]
	v_fma_mix_f32 v55, v6, v38, v180 op_sel_hi:[0,1,0]
	v_fma_mix_f32 v55, v7, v38, v55 op_sel:[0,1,0] op_sel_hi:[0,1,0]
	v_add_f32_dpp v12, v12, v12 row_ror:1 row_mask:0xf bank_mask:0xf bound_ctrl:1
	v_fma_mix_f32 v55, v8, v39, v55 op_sel_hi:[0,1,0]
	v_fma_mix_f32 v55, v9, v39, v55 op_sel:[0,1,0] op_sel_hi:[0,1,0]
	v_add_f32_dpp v12, v12, v12 row_ror:2 row_mask:0xf bank_mask:0xf bound_ctrl:1
	v_pk_mul_f32 v[48:49], v[6:7], v[84:85]
	v_pk_mul_f32 v[50:51], v[8:9], v[86:87]
	v_add_f32_dpp v12, v12, v12 row_ror:4 row_mask:0xf bank_mask:0xf bound_ctrl:1
	v_pk_fma_f32 v[48:49], v[96:97], v[70:71], v[48:49] op_sel_hi:[1,0,1]
	v_pk_fma_f32 v[50:51], v[98:99], v[70:71], v[50:51] op_sel_hi:[1,0,1]
	v_add_f32_dpp v12, v12, v12 row_ror:8 row_mask:0xf bank_mask:0xf bound_ctrl:1
	v_pk_fma_f32 v[6:7], v[92:93], v[12:13], v[48:49] op_sel_hi:[1,0,1] neg_lo:[1,0,0] neg_hi:[1,0,0]
	v_pk_fma_f32 v[8:9], v[94:95], v[12:13], v[50:51] op_sel_hi:[1,0,1] neg_lo:[1,0,0] neg_hi:[1,0,0]
	ds_read_b128 v[36:39], v10 offset:22784
	ds_read_b128 v[32:35], v10 offset:22528
	ds_read_b128 v[44:47], v10 offset:23296
	ds_read_b128 v[40:43], v10 offset:23040
	s_waitcnt lgkmcnt(4)
	v_fma_mix_f32 v12, v6, v20, v180 op_sel_hi:[0,1,0]
	v_fma_mix_f32 v12, v7, v20, v12 op_sel:[0,1,0] op_sel_hi:[0,1,0]
	v_fma_mix_f32 v12, v8, v21, v12 op_sel_hi:[0,1,0]
	v_fma_mix_f32 v12, v9, v21, v12 op_sel:[0,1,0] op_sel_hi:[0,1,0]
	v_fma_mix_f32 v56, v6, v90, v180 op_sel_hi:[0,1,0]
	v_fma_mix_f32 v56, v7, v90, v56 op_sel:[0,1,0] op_sel_hi:[0,1,0]
	v_add_f32_dpp v12, v12, v12 row_ror:1 row_mask:0xf bank_mask:0xf bound_ctrl:1
	v_fma_mix_f32 v56, v8, v91, v56 op_sel_hi:[0,1,0]
	v_fma_mix_f32 v56, v9, v91, v56 op_sel:[0,1,0] op_sel_hi:[0,1,0]
	v_add_f32_dpp v12, v12, v12 row_ror:2 row_mask:0xf bank_mask:0xf bound_ctrl:1
	v_pk_mul_f32 v[48:49], v[6:7], v[16:17]
	v_pk_mul_f32 v[50:51], v[8:9], v[18:19]
	v_add_f32_dpp v12, v12, v12 row_ror:4 row_mask:0xf bank_mask:0xf bound_ctrl:1
	v_pk_fma_f32 v[48:49], v[28:29], v[70:71], v[48:49] op_sel:[0,1,0]
	v_pk_fma_f32 v[50:51], v[30:31], v[70:71], v[50:51] op_sel:[0,1,0]
	v_add_f32_dpp v12, v12, v12 row_ror:8 row_mask:0xf bank_mask:0xf bound_ctrl:1
	v_pk_fma_f32 v[6:7], v[24:25], v[12:13], v[48:49] op_sel_hi:[1,0,1] neg_lo:[1,0,0] neg_hi:[1,0,0]
	v_pk_fma_f32 v[8:9], v[26:27], v[12:13], v[50:51] op_sel_hi:[1,0,1] neg_lo:[1,0,0] neg_hi:[1,0,0]
	ds_read_b128 v[88:91], v10 offset:23808
	ds_read_b128 v[84:87], v10 offset:23552
	ds_read_b128 v[96:99], v10 offset:24320
	ds_read_b128 v[92:95], v10 offset:24064
	ds_read_b128 v[66:69], v11 offset:1536
	s_waitcnt lgkmcnt(5)
	v_fma_mix_f32 v12, v6, v36, v180 op_sel_hi:[0,1,0]
	v_fma_mix_f32 v12, v7, v36, v12 op_sel:[0,1,0] op_sel_hi:[0,1,0]
	v_fma_mix_f32 v12, v8, v37, v12 op_sel_hi:[0,1,0]
	v_fma_mix_f32 v12, v9, v37, v12 op_sel:[0,1,0] op_sel_hi:[0,1,0]
	v_fma_mix_f32 v57, v6, v22, v180 op_sel_hi:[0,1,0]
	v_fma_mix_f32 v57, v7, v22, v57 op_sel:[0,1,0] op_sel_hi:[0,1,0]
	v_add_f32_dpp v12, v12, v12 row_ror:1 row_mask:0xf bank_mask:0xf bound_ctrl:1
	v_fma_mix_f32 v57, v8, v23, v57 op_sel_hi:[0,1,0]
	v_fma_mix_f32 v57, v9, v23, v57 op_sel:[0,1,0] op_sel_hi:[0,1,0]
	v_add_f32_dpp v12, v12, v12 row_ror:2 row_mask:0xf bank_mask:0xf bound_ctrl:1
	v_pk_mul_f32 v[48:49], v[6:7], v[32:33]
	v_pk_mul_f32 v[50:51], v[8:9], v[34:35]
	v_add_f32_dpp v12, v12, v12 row_ror:4 row_mask:0xf bank_mask:0xf bound_ctrl:1
	v_pk_fma_f32 v[48:49], v[44:45], v[72:73], v[48:49] op_sel_hi:[1,0,1]
	v_pk_fma_f32 v[50:51], v[46:47], v[72:73], v[50:51] op_sel_hi:[1,0,1]
	v_add_f32_dpp v12, v12, v12 row_ror:8 row_mask:0xf bank_mask:0xf bound_ctrl:1
	v_pk_fma_f32 v[6:7], v[40:41], v[12:13], v[48:49] op_sel_hi:[1,0,1] neg_lo:[1,0,0] neg_hi:[1,0,0]
	v_pk_fma_f32 v[8:9], v[42:43], v[12:13], v[50:51] op_sel_hi:[1,0,1] neg_lo:[1,0,0] neg_hi:[1,0,0]
	ds_read_b128 v[20:23], v10 offset:24832
	ds_read_b128 v[16:19], v10 offset:24576
	ds_read_b128 v[28:31], v10 offset:25344
	ds_read_b128 v[24:27], v10 offset:25088
	s_waitcnt lgkmcnt(5)
	v_fma_mix_f32 v12, v6, v88, v180 op_sel_hi:[0,1,0]
	v_fma_mix_f32 v12, v7, v88, v12 op_sel:[0,1,0] op_sel_hi:[0,1,0]
	v_fma_mix_f32 v12, v8, v89, v12 op_sel_hi:[0,1,0]
	v_fma_mix_f32 v12, v9, v89, v12 op_sel:[0,1,0] op_sel_hi:[0,1,0]
	v_fma_mix_f32 v81, v6, v38, v180 op_sel_hi:[0,1,0]
	v_fma_mix_f32 v81, v7, v38, v81 op_sel:[0,1,0] op_sel_hi:[0,1,0]
	v_add_f32_dpp v12, v12, v12 row_ror:1 row_mask:0xf bank_mask:0xf bound_ctrl:1
	v_fma_mix_f32 v81, v8, v39, v81 op_sel_hi:[0,1,0]
	v_fma_mix_f32 v81, v9, v39, v81 op_sel:[0,1,0] op_sel_hi:[0,1,0]
	v_add_f32_dpp v12, v12, v12 row_ror:2 row_mask:0xf bank_mask:0xf bound_ctrl:1
	v_pk_mul_f32 v[48:49], v[6:7], v[84:85]
	v_pk_mul_f32 v[50:51], v[8:9], v[86:87]
	v_add_f32_dpp v12, v12, v12 row_ror:4 row_mask:0xf bank_mask:0xf bound_ctrl:1
	v_pk_fma_f32 v[48:49], v[96:97], v[72:73], v[48:49] op_sel:[0,1,0]
	v_pk_fma_f32 v[50:51], v[98:99], v[72:73], v[50:51] op_sel:[0,1,0]
	v_add_f32_dpp v12, v12, v12 row_ror:8 row_mask:0xf bank_mask:0xf bound_ctrl:1
	v_pk_fma_f32 v[6:7], v[92:93], v[12:13], v[48:49] op_sel_hi:[1,0,1] neg_lo:[1,0,0] neg_hi:[1,0,0]
	v_pk_fma_f32 v[8:9], v[94:95], v[12:13], v[50:51] op_sel_hi:[1,0,1] neg_lo:[1,0,0] neg_hi:[1,0,0]
	ds_read_b128 v[36:39], v10 offset:25856
	ds_read_b128 v[32:35], v10 offset:25600
	ds_read_b128 v[44:47], v10 offset:26368
	ds_read_b128 v[40:43], v10 offset:26112
	s_waitcnt lgkmcnt(4)
	v_fma_mix_f32 v12, v6, v20, v180 op_sel_hi:[0,1,0]
	v_fma_mix_f32 v12, v7, v20, v12 op_sel:[0,1,0] op_sel_hi:[0,1,0]
	v_fma_mix_f32 v12, v8, v21, v12 op_sel_hi:[0,1,0]
	v_fma_mix_f32 v12, v9, v21, v12 op_sel:[0,1,0] op_sel_hi:[0,1,0]
	v_fma_mix_f32 v82, v6, v90, v180 op_sel_hi:[0,1,0]
	v_fma_mix_f32 v82, v7, v90, v82 op_sel:[0,1,0] op_sel_hi:[0,1,0]
	v_add_f32_dpp v12, v12, v12 row_ror:1 row_mask:0xf bank_mask:0xf bound_ctrl:1
	v_fma_mix_f32 v82, v8, v91, v82 op_sel_hi:[0,1,0]
	v_fma_mix_f32 v82, v9, v91, v82 op_sel:[0,1,0] op_sel_hi:[0,1,0]
	v_add_f32_dpp v12, v12, v12 row_ror:2 row_mask:0xf bank_mask:0xf bound_ctrl:1
	v_pk_mul_f32 v[48:49], v[6:7], v[16:17]
	v_pk_mul_f32 v[50:51], v[8:9], v[18:19]
	v_add_f32_dpp v12, v12, v12 row_ror:4 row_mask:0xf bank_mask:0xf bound_ctrl:1
	v_pk_fma_f32 v[48:49], v[28:29], v[66:67], v[48:49] op_sel_hi:[1,0,1]
	v_pk_fma_f32 v[50:51], v[30:31], v[66:67], v[50:51] op_sel_hi:[1,0,1]
	v_add_f32_dpp v12, v12, v12 row_ror:8 row_mask:0xf bank_mask:0xf bound_ctrl:1
	v_pk_fma_f32 v[6:7], v[24:25], v[12:13], v[48:49] op_sel_hi:[1,0,1] neg_lo:[1,0,0] neg_hi:[1,0,0]
	v_pk_fma_f32 v[8:9], v[26:27], v[12:13], v[50:51] op_sel_hi:[1,0,1] neg_lo:[1,0,0] neg_hi:[1,0,0]
	ds_read_b128 v[88:91], v10 offset:26880
	ds_read_b128 v[84:87], v10 offset:26624
	ds_read_b128 v[96:99], v10 offset:27392
	ds_read_b128 v[92:95], v10 offset:27136
	s_waitcnt lgkmcnt(4)
	v_fma_mix_f32 v12, v6, v36, v180 op_sel_hi:[0,1,0]
	v_fma_mix_f32 v12, v7, v36, v12 op_sel:[0,1,0] op_sel_hi:[0,1,0]
	v_fma_mix_f32 v12, v8, v37, v12 op_sel_hi:[0,1,0]
	v_fma_mix_f32 v12, v9, v37, v12 op_sel:[0,1,0] op_sel_hi:[0,1,0]
	v_fma_mix_f32 v83, v6, v22, v180 op_sel_hi:[0,1,0]
	v_fma_mix_f32 v83, v7, v22, v83 op_sel:[0,1,0] op_sel_hi:[0,1,0]
	v_add_f32_dpp v12, v12, v12 row_ror:1 row_mask:0xf bank_mask:0xf bound_ctrl:1
	v_fma_mix_f32 v83, v8, v23, v83 op_sel_hi:[0,1,0]
	v_fma_mix_f32 v83, v9, v23, v83 op_sel:[0,1,0] op_sel_hi:[0,1,0]
	v_add_f32_dpp v12, v12, v12 row_ror:2 row_mask:0xf bank_mask:0xf bound_ctrl:1
	v_pk_mul_f32 v[48:49], v[6:7], v[32:33]
	v_pk_mul_f32 v[50:51], v[8:9], v[34:35]
	v_add_f32_dpp v12, v12, v12 row_ror:4 row_mask:0xf bank_mask:0xf bound_ctrl:1
	v_pk_fma_f32 v[48:49], v[44:45], v[66:67], v[48:49] op_sel:[0,1,0]
	v_pk_fma_f32 v[50:51], v[46:47], v[66:67], v[50:51] op_sel:[0,1,0]
	v_add_f32_dpp v12, v12, v12 row_ror:8 row_mask:0xf bank_mask:0xf bound_ctrl:1
	v_pk_fma_f32 v[6:7], v[40:41], v[12:13], v[48:49] op_sel_hi:[1,0,1] neg_lo:[1,0,0] neg_hi:[1,0,0]
	v_pk_fma_f32 v[8:9], v[42:43], v[12:13], v[50:51] op_sel_hi:[1,0,1] neg_lo:[1,0,0] neg_hi:[1,0,0]
	ds_read_b128 v[20:23], v10 offset:27904
	ds_read_b128 v[16:19], v10 offset:27648
	ds_read_b128 v[28:31], v10 offset:28416
	ds_read_b128 v[24:27], v10 offset:28160
	ds_read_b128 v[70:73], v11 offset:1792
	s_waitcnt lgkmcnt(5)
	v_fma_mix_f32 v12, v6, v88, v180 op_sel_hi:[0,1,0]
	v_fma_mix_f32 v12, v7, v88, v12 op_sel:[0,1,0] op_sel_hi:[0,1,0]
	v_fma_mix_f32 v12, v8, v89, v12 op_sel_hi:[0,1,0]
	v_fma_mix_f32 v12, v9, v89, v12 op_sel:[0,1,0] op_sel_hi:[0,1,0]
	v_fma_mix_f32 v100, v6, v38, v180 op_sel_hi:[0,1,0]
	v_fma_mix_f32 v100, v7, v38, v100 op_sel:[0,1,0] op_sel_hi:[0,1,0]
	v_add_f32_dpp v12, v12, v12 row_ror:1 row_mask:0xf bank_mask:0xf bound_ctrl:1
	v_fma_mix_f32 v100, v8, v39, v100 op_sel_hi:[0,1,0]
	v_fma_mix_f32 v100, v9, v39, v100 op_sel:[0,1,0] op_sel_hi:[0,1,0]
	v_add_f32_dpp v12, v12, v12 row_ror:2 row_mask:0xf bank_mask:0xf bound_ctrl:1
	v_pk_mul_f32 v[48:49], v[6:7], v[84:85]
	v_pk_mul_f32 v[50:51], v[8:9], v[86:87]
	v_add_f32_dpp v12, v12, v12 row_ror:4 row_mask:0xf bank_mask:0xf bound_ctrl:1
	v_pk_fma_f32 v[48:49], v[96:97], v[68:69], v[48:49] op_sel_hi:[1,0,1]
	v_pk_fma_f32 v[50:51], v[98:99], v[68:69], v[50:51] op_sel_hi:[1,0,1]
	v_add_f32_dpp v12, v12, v12 row_ror:8 row_mask:0xf bank_mask:0xf bound_ctrl:1
	v_pk_fma_f32 v[6:7], v[92:93], v[12:13], v[48:49] op_sel_hi:[1,0,1] neg_lo:[1,0,0] neg_hi:[1,0,0]
	v_pk_fma_f32 v[8:9], v[94:95], v[12:13], v[50:51] op_sel_hi:[1,0,1] neg_lo:[1,0,0] neg_hi:[1,0,0]
	ds_read_b128 v[36:39], v10 offset:28928
	ds_read_b128 v[32:35], v10 offset:28672
	ds_read_b128 v[44:47], v10 offset:29440
	ds_read_b128 v[40:43], v10 offset:29184
	s_waitcnt lgkmcnt(5)
	v_fma_mix_f32 v12, v6, v20, v180 op_sel_hi:[0,1,0]
	v_fma_mix_f32 v12, v7, v20, v12 op_sel:[0,1,0] op_sel_hi:[0,1,0]
	v_fma_mix_f32 v12, v8, v21, v12 op_sel_hi:[0,1,0]
	v_fma_mix_f32 v12, v9, v21, v12 op_sel:[0,1,0] op_sel_hi:[0,1,0]
	v_fma_mix_f32 v101, v6, v90, v180 op_sel_hi:[0,1,0]
	v_fma_mix_f32 v101, v7, v90, v101 op_sel:[0,1,0] op_sel_hi:[0,1,0]
	v_add_f32_dpp v12, v12, v12 row_ror:1 row_mask:0xf bank_mask:0xf bound_ctrl:1
	v_fma_mix_f32 v101, v8, v91, v101 op_sel_hi:[0,1,0]
	v_fma_mix_f32 v101, v9, v91, v101 op_sel:[0,1,0] op_sel_hi:[0,1,0]
	v_add_f32_dpp v12, v12, v12 row_ror:2 row_mask:0xf bank_mask:0xf bound_ctrl:1
	v_pk_mul_f32 v[48:49], v[6:7], v[16:17]
	v_pk_mul_f32 v[50:51], v[8:9], v[18:19]
	v_add_f32_dpp v12, v12, v12 row_ror:4 row_mask:0xf bank_mask:0xf bound_ctrl:1
	v_pk_fma_f32 v[48:49], v[28:29], v[68:69], v[48:49] op_sel:[0,1,0]
	v_pk_fma_f32 v[50:51], v[30:31], v[68:69], v[50:51] op_sel:[0,1,0]
	v_add_f32_dpp v12, v12, v12 row_ror:8 row_mask:0xf bank_mask:0xf bound_ctrl:1
	v_pk_fma_f32 v[6:7], v[24:25], v[12:13], v[48:49] op_sel_hi:[1,0,1] neg_lo:[1,0,0] neg_hi:[1,0,0]
	v_pk_fma_f32 v[8:9], v[26:27], v[12:13], v[50:51] op_sel_hi:[1,0,1] neg_lo:[1,0,0] neg_hi:[1,0,0]
	ds_read_b128 v[88:91], v10 offset:29952
	ds_read_b128 v[84:87], v10 offset:29696
	ds_read_b128 v[96:99], v10 offset:30464
	ds_read_b128 v[92:95], v10 offset:30208
	s_waitcnt lgkmcnt(4)
	v_fma_mix_f32 v12, v6, v36, v180 op_sel_hi:[0,1,0]
	v_fma_mix_f32 v12, v7, v36, v12 op_sel:[0,1,0] op_sel_hi:[0,1,0]
	v_fma_mix_f32 v12, v8, v37, v12 op_sel_hi:[0,1,0]
	v_fma_mix_f32 v12, v9, v37, v12 op_sel:[0,1,0] op_sel_hi:[0,1,0]
	v_fma_mix_f32 v102, v6, v22, v180 op_sel_hi:[0,1,0]
	v_fma_mix_f32 v102, v7, v22, v102 op_sel:[0,1,0] op_sel_hi:[0,1,0]
	v_add_f32_dpp v12, v12, v12 row_ror:1 row_mask:0xf bank_mask:0xf bound_ctrl:1
	v_fma_mix_f32 v102, v8, v23, v102 op_sel_hi:[0,1,0]
	v_fma_mix_f32 v102, v9, v23, v102 op_sel:[0,1,0] op_sel_hi:[0,1,0]
	v_add_f32_dpp v12, v12, v12 row_ror:2 row_mask:0xf bank_mask:0xf bound_ctrl:1
	v_pk_mul_f32 v[48:49], v[6:7], v[32:33]
	v_pk_mul_f32 v[50:51], v[8:9], v[34:35]
	v_add_f32_dpp v12, v12, v12 row_ror:4 row_mask:0xf bank_mask:0xf bound_ctrl:1
	v_pk_fma_f32 v[48:49], v[44:45], v[70:71], v[48:49] op_sel_hi:[1,0,1]
	v_pk_fma_f32 v[50:51], v[46:47], v[70:71], v[50:51] op_sel_hi:[1,0,1]
	v_add_f32_dpp v12, v12, v12 row_ror:8 row_mask:0xf bank_mask:0xf bound_ctrl:1
	v_pk_fma_f32 v[6:7], v[40:41], v[12:13], v[48:49] op_sel_hi:[1,0,1] neg_lo:[1,0,0] neg_hi:[1,0,0]
	v_pk_fma_f32 v[8:9], v[42:43], v[12:13], v[50:51] op_sel_hi:[1,0,1] neg_lo:[1,0,0] neg_hi:[1,0,0]
	ds_read_b128 v[20:23], v10 offset:30976
	ds_read_b128 v[16:19], v10 offset:30720
	ds_read_b128 v[28:31], v10 offset:31488
	ds_read_b128 v[24:27], v10 offset:31232
	s_waitcnt lgkmcnt(4)
	v_fma_mix_f32 v12, v6, v88, v180 op_sel_hi:[0,1,0]
	v_fma_mix_f32 v12, v7, v88, v12 op_sel:[0,1,0] op_sel_hi:[0,1,0]
	v_fma_mix_f32 v12, v8, v89, v12 op_sel_hi:[0,1,0]
	v_fma_mix_f32 v12, v9, v89, v12 op_sel:[0,1,0] op_sel_hi:[0,1,0]
	v_fma_mix_f32 v103, v6, v38, v180 op_sel_hi:[0,1,0]
	v_fma_mix_f32 v103, v7, v38, v103 op_sel:[0,1,0] op_sel_hi:[0,1,0]
	v_add_f32_dpp v12, v12, v12 row_ror:1 row_mask:0xf bank_mask:0xf bound_ctrl:1
	v_fma_mix_f32 v103, v8, v39, v103 op_sel_hi:[0,1,0]
	v_fma_mix_f32 v103, v9, v39, v103 op_sel:[0,1,0] op_sel_hi:[0,1,0]
	v_add_f32_dpp v12, v12, v12 row_ror:2 row_mask:0xf bank_mask:0xf bound_ctrl:1
	v_pk_mul_f32 v[48:49], v[6:7], v[84:85]
	v_pk_mul_f32 v[50:51], v[8:9], v[86:87]
	v_add_f32_dpp v12, v12, v12 row_ror:4 row_mask:0xf bank_mask:0xf bound_ctrl:1
	v_pk_fma_f32 v[48:49], v[96:97], v[70:71], v[48:49] op_sel:[0,1,0]
	v_pk_fma_f32 v[50:51], v[98:99], v[70:71], v[50:51] op_sel:[0,1,0]
	v_add_f32_dpp v12, v12, v12 row_ror:8 row_mask:0xf bank_mask:0xf bound_ctrl:1
	v_pk_fma_f32 v[6:7], v[92:93], v[12:13], v[48:49] op_sel_hi:[1,0,1] neg_lo:[1,0,0] neg_hi:[1,0,0]
	v_pk_fma_f32 v[8:9], v[94:95], v[12:13], v[50:51] op_sel_hi:[1,0,1] neg_lo:[1,0,0] neg_hi:[1,0,0]
	ds_read_b128 v[36:39], v10 offset:32000
	ds_read_b128 v[32:35], v10 offset:31744
	ds_read_b128 v[44:47], v10 offset:32512
	ds_read_b128 v[40:43], v10 offset:32256
	ds_read_b128 v[66:69], v11 offset:2048
	s_waitcnt lgkmcnt(5)
	v_fma_mix_f32 v12, v6, v20, v180 op_sel_hi:[0,1,0]
	v_fma_mix_f32 v12, v7, v20, v12 op_sel:[0,1,0] op_sel_hi:[0,1,0]
	v_fma_mix_f32 v12, v8, v21, v12 op_sel_hi:[0,1,0]
	v_fma_mix_f32 v12, v9, v21, v12 op_sel:[0,1,0] op_sel_hi:[0,1,0]
	v_fma_mix_f32 v104, v6, v90, v180 op_sel_hi:[0,1,0]
	v_fma_mix_f32 v104, v7, v90, v104 op_sel:[0,1,0] op_sel_hi:[0,1,0]
	v_add_f32_dpp v12, v12, v12 row_ror:1 row_mask:0xf bank_mask:0xf bound_ctrl:1
	v_fma_mix_f32 v104, v8, v91, v104 op_sel_hi:[0,1,0]
	v_fma_mix_f32 v104, v9, v91, v104 op_sel:[0,1,0] op_sel_hi:[0,1,0]
	v_add_f32_dpp v12, v12, v12 row_ror:2 row_mask:0xf bank_mask:0xf bound_ctrl:1
	v_pk_mul_f32 v[48:49], v[6:7], v[16:17]
	v_pk_mul_f32 v[50:51], v[8:9], v[18:19]
	v_add_f32_dpp v12, v12, v12 row_ror:4 row_mask:0xf bank_mask:0xf bound_ctrl:1
	v_pk_fma_f32 v[48:49], v[28:29], v[72:73], v[48:49] op_sel_hi:[1,0,1]
	v_pk_fma_f32 v[50:51], v[30:31], v[72:73], v[50:51] op_sel_hi:[1,0,1]
	v_add_f32_dpp v12, v12, v12 row_ror:8 row_mask:0xf bank_mask:0xf bound_ctrl:1
	v_pk_fma_f32 v[6:7], v[24:25], v[12:13], v[48:49] op_sel_hi:[1,0,1] neg_lo:[1,0,0] neg_hi:[1,0,0]
	v_pk_fma_f32 v[8:9], v[26:27], v[12:13], v[50:51] op_sel_hi:[1,0,1] neg_lo:[1,0,0] neg_hi:[1,0,0]
	ds_read_b128 v[88:91], v10 offset:33024
	ds_read_b128 v[84:87], v10 offset:32768
	ds_read_b128 v[96:99], v10 offset:33536
	ds_read_b128 v[92:95], v10 offset:33280
	s_waitcnt lgkmcnt(5)
	v_fma_mix_f32 v12, v6, v36, v180 op_sel_hi:[0,1,0]
	v_fma_mix_f32 v12, v7, v36, v12 op_sel:[0,1,0] op_sel_hi:[0,1,0]
	v_fma_mix_f32 v12, v8, v37, v12 op_sel_hi:[0,1,0]
	v_fma_mix_f32 v12, v9, v37, v12 op_sel:[0,1,0] op_sel_hi:[0,1,0]
	v_fma_mix_f32 v105, v6, v22, v180 op_sel_hi:[0,1,0]
	v_fma_mix_f32 v105, v7, v22, v105 op_sel:[0,1,0] op_sel_hi:[0,1,0]
	v_add_f32_dpp v12, v12, v12 row_ror:1 row_mask:0xf bank_mask:0xf bound_ctrl:1
	v_fma_mix_f32 v105, v8, v23, v105 op_sel_hi:[0,1,0]
	v_fma_mix_f32 v105, v9, v23, v105 op_sel:[0,1,0] op_sel_hi:[0,1,0]
	v_add_f32_dpp v12, v12, v12 row_ror:2 row_mask:0xf bank_mask:0xf bound_ctrl:1
	v_pk_mul_f32 v[48:49], v[6:7], v[32:33]
	v_pk_mul_f32 v[50:51], v[8:9], v[34:35]
	v_add_f32_dpp v12, v12, v12 row_ror:4 row_mask:0xf bank_mask:0xf bound_ctrl:1
	v_pk_fma_f32 v[48:49], v[44:45], v[72:73], v[48:49] op_sel:[0,1,0]
	v_pk_fma_f32 v[50:51], v[46:47], v[72:73], v[50:51] op_sel:[0,1,0]
	v_add_f32_dpp v12, v12, v12 row_ror:8 row_mask:0xf bank_mask:0xf bound_ctrl:1
	v_pk_fma_f32 v[6:7], v[40:41], v[12:13], v[48:49] op_sel_hi:[1,0,1] neg_lo:[1,0,0] neg_hi:[1,0,0]
	v_pk_fma_f32 v[8:9], v[42:43], v[12:13], v[50:51] op_sel_hi:[1,0,1] neg_lo:[1,0,0] neg_hi:[1,0,0]
	ds_read_b128 v[20:23], v10 offset:34048
	ds_read_b128 v[16:19], v10 offset:33792
	ds_read_b128 v[28:31], v10 offset:34560
	ds_read_b128 v[24:27], v10 offset:34304
	s_waitcnt lgkmcnt(4)
	v_fma_mix_f32 v12, v6, v88, v180 op_sel_hi:[0,1,0]
	v_fma_mix_f32 v12, v7, v88, v12 op_sel:[0,1,0] op_sel_hi:[0,1,0]
	v_fma_mix_f32 v12, v8, v89, v12 op_sel_hi:[0,1,0]
	v_fma_mix_f32 v12, v9, v89, v12 op_sel:[0,1,0] op_sel_hi:[0,1,0]
	v_fma_mix_f32 v61, v6, v38, v180 op_sel_hi:[0,1,0]
	v_fma_mix_f32 v61, v7, v38, v61 op_sel:[0,1,0] op_sel_hi:[0,1,0]
	v_add_f32_dpp v12, v12, v12 row_ror:1 row_mask:0xf bank_mask:0xf bound_ctrl:1
	v_fma_mix_f32 v61, v8, v39, v61 op_sel_hi:[0,1,0]
	v_fma_mix_f32 v61, v9, v39, v61 op_sel:[0,1,0] op_sel_hi:[0,1,0]
	v_add_f32_dpp v12, v12, v12 row_ror:2 row_mask:0xf bank_mask:0xf bound_ctrl:1
	v_pk_mul_f32 v[48:49], v[6:7], v[84:85]
	v_pk_mul_f32 v[50:51], v[8:9], v[86:87]
	v_add_f32_dpp v12, v12, v12 row_ror:4 row_mask:0xf bank_mask:0xf bound_ctrl:1
	v_pk_fma_f32 v[48:49], v[96:97], v[66:67], v[48:49] op_sel_hi:[1,0,1]
	v_pk_fma_f32 v[50:51], v[98:99], v[66:67], v[50:51] op_sel_hi:[1,0,1]
	v_add_f32_dpp v12, v12, v12 row_ror:8 row_mask:0xf bank_mask:0xf bound_ctrl:1
	v_pk_fma_f32 v[6:7], v[92:93], v[12:13], v[48:49] op_sel_hi:[1,0,1] neg_lo:[1,0,0] neg_hi:[1,0,0]
	v_pk_fma_f32 v[8:9], v[94:95], v[12:13], v[50:51] op_sel_hi:[1,0,1] neg_lo:[1,0,0] neg_hi:[1,0,0]
	ds_read_b128 v[36:39], v10 offset:35072
	ds_read_b128 v[32:35], v10 offset:34816
	ds_read_b128 v[44:47], v10 offset:35584
	ds_read_b128 v[40:43], v10 offset:35328
	v_add_f32_dpp v83, v83, v83 row_ror:8 row_mask:0xf bank_mask:0xc
	v_add_f32_dpp v83, v52, v52 row_ror:8 row_mask:0xf bank_mask:0x3
	v_add_f32_dpp v100, v100, v100 row_ror:8 row_mask:0xf bank_mask:0xc
	v_add_f32_dpp v100, v53, v53 row_ror:8 row_mask:0xf bank_mask:0x3
	v_add_f32_dpp v101, v101, v101 row_ror:8 row_mask:0xf bank_mask:0xc
	v_add_f32_dpp v101, v54, v54 row_ror:8 row_mask:0xf bank_mask:0x3
	v_add_f32_dpp v102, v102, v102 row_ror:8 row_mask:0xf bank_mask:0xc
	v_add_f32_dpp v102, v55, v55 row_ror:8 row_mask:0xf bank_mask:0x3
	v_add_f32_dpp v103, v103, v103 row_ror:8 row_mask:0xf bank_mask:0xc
	v_add_f32_dpp v103, v56, v56 row_ror:8 row_mask:0xf bank_mask:0x3
	v_add_f32_dpp v104, v104, v104 row_ror:8 row_mask:0xf bank_mask:0xc
	v_add_f32_dpp v104, v57, v57 row_ror:8 row_mask:0xf bank_mask:0x3
	v_add_f32_dpp v105, v105, v105 row_ror:8 row_mask:0xf bank_mask:0xc
	v_add_f32_dpp v105, v81, v81 row_ror:8 row_mask:0xf bank_mask:0x3
	v_add_f32_dpp v61, v61, v61 row_ror:8 row_mask:0xf bank_mask:0xc
	v_add_f32_dpp v61, v82, v82 row_ror:8 row_mask:0xf bank_mask:0x3
	v_add_f32_dpp v103, v103, v103 row_ror:4 row_mask:0xf bank_mask:0xa
	v_add_f32_dpp v103, v83, v83 row_ror:12 row_mask:0xf bank_mask:0x5
	v_add_f32_dpp v104, v104, v104 row_ror:4 row_mask:0xf bank_mask:0xa
	v_add_f32_dpp v104, v100, v100 row_ror:12 row_mask:0xf bank_mask:0x5
	v_add_f32_dpp v105, v105, v105 row_ror:4 row_mask:0xf bank_mask:0xa
	v_add_f32_dpp v105, v101, v101 row_ror:12 row_mask:0xf bank_mask:0x5
	v_add_f32_dpp v61, v61, v61 row_ror:4 row_mask:0xf bank_mask:0xa
	v_add_f32_dpp v61, v102, v102 row_ror:12 row_mask:0xf bank_mask:0x5
	v_cndmask_b32_e64 v62, v105, v103, s[38:39]
	v_cndmask_b32_e64 v63, v103, v105, s[38:39]
	v_cndmask_b32_e64 v64, v61, v104, s[38:39]
	v_cndmask_b32_e64 v65, v104, v61, s[38:39]
	v_add_f32_dpp v62, v63, v62 quad_perm:[2,3,0,1] row_mask:0xf bank_mask:0xf bound_ctrl:1
	s_nop 0
	v_add_f32_dpp v63, v65, v64 quad_perm:[2,3,0,1] row_mask:0xf bank_mask:0xf bound_ctrl:1
	v_cndmask_b32_e64 v65, v63, v62, s[40:41]
	v_cndmask_b32_e64 v62, v62, v63, s[40:41]
	s_nop 1
	v_add_f32_dpp v62, v62, v65 quad_perm:[1,0,3,2] row_mask:0xf bank_mask:0xf bound_ctrl:1
	v_cvt_pk_bf16_f32 v62, v62, v62
	global_store_short v[2:3], v62, off
	v_lshl_add_u64 v[2:3], v[2:3], 0, s[84:85]
	s_waitcnt lgkmcnt(4)
	v_fma_mix_f32 v12, v6, v20, v180 op_sel_hi:[0,1,0]
	v_fma_mix_f32 v12, v7, v20, v12 op_sel:[0,1,0] op_sel_hi:[0,1,0]
	v_fma_mix_f32 v12, v8, v21, v12 op_sel_hi:[0,1,0]
	v_fma_mix_f32 v12, v9, v21, v12 op_sel:[0,1,0] op_sel_hi:[0,1,0]
	v_fma_mix_f32 v52, v6, v90, v180 op_sel_hi:[0,1,0]
	v_fma_mix_f32 v52, v7, v90, v52 op_sel:[0,1,0] op_sel_hi:[0,1,0]
	v_add_f32_dpp v12, v12, v12 row_ror:1 row_mask:0xf bank_mask:0xf bound_ctrl:1
	v_fma_mix_f32 v52, v8, v91, v52 op_sel_hi:[0,1,0]
	v_fma_mix_f32 v52, v9, v91, v52 op_sel:[0,1,0] op_sel_hi:[0,1,0]
	v_add_f32_dpp v12, v12, v12 row_ror:2 row_mask:0xf bank_mask:0xf bound_ctrl:1
	v_pk_mul_f32 v[48:49], v[6:7], v[16:17]
	v_pk_mul_f32 v[50:51], v[8:9], v[18:19]
	v_add_f32_dpp v12, v12, v12 row_ror:4 row_mask:0xf bank_mask:0xf bound_ctrl:1
	v_pk_fma_f32 v[48:49], v[28:29], v[66:67], v[48:49] op_sel:[0,1,0]
	v_pk_fma_f32 v[50:51], v[30:31], v[66:67], v[50:51] op_sel:[0,1,0]
	v_add_f32_dpp v12, v12, v12 row_ror:8 row_mask:0xf bank_mask:0xf bound_ctrl:1
	v_pk_fma_f32 v[6:7], v[24:25], v[12:13], v[48:49] op_sel_hi:[1,0,1] neg_lo:[1,0,0] neg_hi:[1,0,0]
	v_pk_fma_f32 v[8:9], v[26:27], v[12:13], v[50:51] op_sel_hi:[1,0,1] neg_lo:[1,0,0] neg_hi:[1,0,0]
	ds_read_b128 v[88:91], v10 offset:36096
	ds_read_b128 v[84:87], v10 offset:35840
	ds_read_b128 v[96:99], v10 offset:36608
	ds_read_b128 v[92:95], v10 offset:36352
	ds_read_b128 v[70:73], v11 offset:2304
	s_waitcnt lgkmcnt(5)
	v_fma_mix_f32 v12, v6, v36, v180 op_sel_hi:[0,1,0]
	v_fma_mix_f32 v12, v7, v36, v12 op_sel:[0,1,0] op_sel_hi:[0,1,0]
	v_fma_mix_f32 v12, v8, v37, v12 op_sel_hi:[0,1,0]
	v_fma_mix_f32 v12, v9, v37, v12 op_sel:[0,1,0] op_sel_hi:[0,1,0]
	v_fma_mix_f32 v53, v6, v22, v180 op_sel_hi:[0,1,0]
	v_fma_mix_f32 v53, v7, v22, v53 op_sel:[0,1,0] op_sel_hi:[0,1,0]
	v_add_f32_dpp v12, v12, v12 row_ror:1 row_mask:0xf bank_mask:0xf bound_ctrl:1
	v_fma_mix_f32 v53, v8, v23, v53 op_sel_hi:[0,1,0]
	v_fma_mix_f32 v53, v9, v23, v53 op_sel:[0,1,0] op_sel_hi:[0,1,0]
	v_add_f32_dpp v12, v12, v12 row_ror:2 row_mask:0xf bank_mask:0xf bound_ctrl:1
	v_pk_mul_f32 v[48:49], v[6:7], v[32:33]
	v_pk_mul_f32 v[50:51], v[8:9], v[34:35]
	v_add_f32_dpp v12, v12, v12 row_ror:4 row_mask:0xf bank_mask:0xf bound_ctrl:1
	v_pk_fma_f32 v[48:49], v[44:45], v[68:69], v[48:49] op_sel_hi:[1,0,1]
	v_pk_fma_f32 v[50:51], v[46:47], v[68:69], v[50:51] op_sel_hi:[1,0,1]
	v_add_f32_dpp v12, v12, v12 row_ror:8 row_mask:0xf bank_mask:0xf bound_ctrl:1
	v_pk_fma_f32 v[6:7], v[40:41], v[12:13], v[48:49] op_sel_hi:[1,0,1] neg_lo:[1,0,0] neg_hi:[1,0,0]
	v_pk_fma_f32 v[8:9], v[42:43], v[12:13], v[50:51] op_sel_hi:[1,0,1] neg_lo:[1,0,0] neg_hi:[1,0,0]
	ds_read_b128 v[20:23], v10 offset:37120
	ds_read_b128 v[16:19], v10 offset:36864
	ds_read_b128 v[28:31], v10 offset:37632
	ds_read_b128 v[24:27], v10 offset:37376
	s_waitcnt lgkmcnt(5)
	v_fma_mix_f32 v12, v6, v88, v180 op_sel_hi:[0,1,0]
	v_fma_mix_f32 v12, v7, v88, v12 op_sel:[0,1,0] op_sel_hi:[0,1,0]
	v_fma_mix_f32 v12, v8, v89, v12 op_sel_hi:[0,1,0]
	v_fma_mix_f32 v12, v9, v89, v12 op_sel:[0,1,0] op_sel_hi:[0,1,0]
	v_fma_mix_f32 v54, v6, v38, v180 op_sel_hi:[0,1,0]
	v_fma_mix_f32 v54, v7, v38, v54 op_sel:[0,1,0] op_sel_hi:[0,1,0]
	v_add_f32_dpp v12, v12, v12 row_ror:1 row_mask:0xf bank_mask:0xf bound_ctrl:1
	v_fma_mix_f32 v54, v8, v39, v54 op_sel_hi:[0,1,0]
	v_fma_mix_f32 v54, v9, v39, v54 op_sel:[0,1,0] op_sel_hi:[0,1,0]
	v_add_f32_dpp v12, v12, v12 row_ror:2 row_mask:0xf bank_mask:0xf bound_ctrl:1
	v_pk_mul_f32 v[48:49], v[6:7], v[84:85]
	v_pk_mul_f32 v[50:51], v[8:9], v[86:87]
	v_add_f32_dpp v12, v12, v12 row_ror:4 row_mask:0xf bank_mask:0xf bound_ctrl:1
	v_pk_fma_f32 v[48:49], v[96:97], v[68:69], v[48:49] op_sel:[0,1,0]
	v_pk_fma_f32 v[50:51], v[98:99], v[68:69], v[50:51] op_sel:[0,1,0]
	v_add_f32_dpp v12, v12, v12 row_ror:8 row_mask:0xf bank_mask:0xf bound_ctrl:1
	v_pk_fma_f32 v[6:7], v[92:93], v[12:13], v[48:49] op_sel_hi:[1,0,1] neg_lo:[1,0,0] neg_hi:[1,0,0]
	v_pk_fma_f32 v[8:9], v[94:95], v[12:13], v[50:51] op_sel_hi:[1,0,1] neg_lo:[1,0,0] neg_hi:[1,0,0]
	ds_read_b128 v[36:39], v10 offset:38144
	ds_read_b128 v[32:35], v10 offset:37888
	ds_read_b128 v[44:47], v10 offset:38656
	ds_read_b128 v[40:43], v10 offset:38400
	s_waitcnt lgkmcnt(4)
	v_fma_mix_f32 v12, v6, v20, v180 op_sel_hi:[0,1,0]
	v_fma_mix_f32 v12, v7, v20, v12 op_sel:[0,1,0] op_sel_hi:[0,1,0]
	v_fma_mix_f32 v12, v8, v21, v12 op_sel_hi:[0,1,0]
	v_fma_mix_f32 v12, v9, v21, v12 op_sel:[0,1,0] op_sel_hi:[0,1,0]
	v_fma_mix_f32 v55, v6, v90, v180 op_sel_hi:[0,1,0]
	v_fma_mix_f32 v55, v7, v90, v55 op_sel:[0,1,0] op_sel_hi:[0,1,0]
	v_add_f32_dpp v12, v12, v12 row_ror:1 row_mask:0xf bank_mask:0xf bound_ctrl:1
	v_fma_mix_f32 v55, v8, v91, v55 op_sel_hi:[0,1,0]
	v_fma_mix_f32 v55, v9, v91, v55 op_sel:[0,1,0] op_sel_hi:[0,1,0]
	v_add_f32_dpp v12, v12, v12 row_ror:2 row_mask:0xf bank_mask:0xf bound_ctrl:1
	v_pk_mul_f32 v[48:49], v[6:7], v[16:17]
	v_pk_mul_f32 v[50:51], v[8:9], v[18:19]
	v_add_f32_dpp v12, v12, v12 row_ror:4 row_mask:0xf bank_mask:0xf bound_ctrl:1
	v_pk_fma_f32 v[48:49], v[28:29], v[70:71], v[48:49] op_sel_hi:[1,0,1]
	v_pk_fma_f32 v[50:51], v[30:31], v[70:71], v[50:51] op_sel_hi:[1,0,1]
	v_add_f32_dpp v12, v12, v12 row_ror:8 row_mask:0xf bank_mask:0xf bound_ctrl:1
	v_pk_fma_f32 v[6:7], v[24:25], v[12:13], v[48:49] op_sel_hi:[1,0,1] neg_lo:[1,0,0] neg_hi:[1,0,0]
	v_pk_fma_f32 v[8:9], v[26:27], v[12:13], v[50:51] op_sel_hi:[1,0,1] neg_lo:[1,0,0] neg_hi:[1,0,0]
	ds_read_b128 v[88:91], v10 offset:39168
	ds_read_b128 v[84:87], v10 offset:38912
	ds_read_b128 v[96:99], v10 offset:39680
	ds_read_b128 v[92:95], v10 offset:39424
	s_waitcnt lgkmcnt(4)
	v_fma_mix_f32 v12, v6, v36, v180 op_sel_hi:[0,1,0]
	v_fma_mix_f32 v12, v7, v36, v12 op_sel:[0,1,0] op_sel_hi:[0,1,0]
	v_fma_mix_f32 v12, v8, v37, v12 op_sel_hi:[0,1,0]
	v_fma_mix_f32 v12, v9, v37, v12 op_sel:[0,1,0] op_sel_hi:[0,1,0]
	v_fma_mix_f32 v56, v6, v22, v180 op_sel_hi:[0,1,0]
	v_fma_mix_f32 v56, v7, v22, v56 op_sel:[0,1,0] op_sel_hi:[0,1,0]
	v_add_f32_dpp v12, v12, v12 row_ror:1 row_mask:0xf bank_mask:0xf bound_ctrl:1
	v_fma_mix_f32 v56, v8, v23, v56 op_sel_hi:[0,1,0]
	v_fma_mix_f32 v56, v9, v23, v56 op_sel:[0,1,0] op_sel_hi:[0,1,0]
	v_add_f32_dpp v12, v12, v12 row_ror:2 row_mask:0xf bank_mask:0xf bound_ctrl:1
	v_pk_mul_f32 v[48:49], v[6:7], v[32:33]
	v_pk_mul_f32 v[50:51], v[8:9], v[34:35]
	v_add_f32_dpp v12, v12, v12 row_ror:4 row_mask:0xf bank_mask:0xf bound_ctrl:1
	v_pk_fma_f32 v[48:49], v[44:45], v[70:71], v[48:49] op_sel:[0,1,0]
	v_pk_fma_f32 v[50:51], v[46:47], v[70:71], v[50:51] op_sel:[0,1,0]
	v_add_f32_dpp v12, v12, v12 row_ror:8 row_mask:0xf bank_mask:0xf bound_ctrl:1
	v_pk_fma_f32 v[6:7], v[40:41], v[12:13], v[48:49] op_sel_hi:[1,0,1] neg_lo:[1,0,0] neg_hi:[1,0,0]
	v_pk_fma_f32 v[8:9], v[42:43], v[12:13], v[50:51] op_sel_hi:[1,0,1] neg_lo:[1,0,0] neg_hi:[1,0,0]
	ds_read_b128 v[20:23], v10 offset:40192
	ds_read_b128 v[16:19], v10 offset:39936
	ds_read_b128 v[28:31], v10 offset:40704
	ds_read_b128 v[24:27], v10 offset:40448
	ds_read_b128 v[66:69], v11 offset:2560
	s_waitcnt lgkmcnt(5)
	v_fma_mix_f32 v12, v6, v88, v180 op_sel_hi:[0,1,0]
	v_fma_mix_f32 v12, v7, v88, v12 op_sel:[0,1,0] op_sel_hi:[0,1,0]
	v_fma_mix_f32 v12, v8, v89, v12 op_sel_hi:[0,1,0]
	v_fma_mix_f32 v12, v9, v89, v12 op_sel:[0,1,0] op_sel_hi:[0,1,0]
	v_fma_mix_f32 v57, v6, v38, v180 op_sel_hi:[0,1,0]
	v_fma_mix_f32 v57, v7, v38, v57 op_sel:[0,1,0] op_sel_hi:[0,1,0]
	v_add_f32_dpp v12, v12, v12 row_ror:1 row_mask:0xf bank_mask:0xf bound_ctrl:1
	v_fma_mix_f32 v57, v8, v39, v57 op_sel_hi:[0,1,0]
	v_fma_mix_f32 v57, v9, v39, v57 op_sel:[0,1,0] op_sel_hi:[0,1,0]
	v_add_f32_dpp v12, v12, v12 row_ror:2 row_mask:0xf bank_mask:0xf bound_ctrl:1
	v_pk_mul_f32 v[48:49], v[6:7], v[84:85]
	v_pk_mul_f32 v[50:51], v[8:9], v[86:87]
	v_add_f32_dpp v12, v12, v12 row_ror:4 row_mask:0xf bank_mask:0xf bound_ctrl:1
	v_pk_fma_f32 v[48:49], v[96:97], v[72:73], v[48:49] op_sel_hi:[1,0,1]
	v_pk_fma_f32 v[50:51], v[98:99], v[72:73], v[50:51] op_sel_hi:[1,0,1]
	v_add_f32_dpp v12, v12, v12 row_ror:8 row_mask:0xf bank_mask:0xf bound_ctrl:1
	v_pk_fma_f32 v[6:7], v[92:93], v[12:13], v[48:49] op_sel_hi:[1,0,1] neg_lo:[1,0,0] neg_hi:[1,0,0]
	v_pk_fma_f32 v[8:9], v[94:95], v[12:13], v[50:51] op_sel_hi:[1,0,1] neg_lo:[1,0,0] neg_hi:[1,0,0]
	ds_read_b128 v[36:39], v10 offset:41216
	ds_read_b128 v[32:35], v10 offset:40960
	ds_read_b128 v[44:47], v10 offset:41728
	ds_read_b128 v[40:43], v10 offset:41472
	s_waitcnt lgkmcnt(5)
	v_fma_mix_f32 v12, v6, v20, v180 op_sel_hi:[0,1,0]
	v_fma_mix_f32 v12, v7, v20, v12 op_sel:[0,1,0] op_sel_hi:[0,1,0]
	v_fma_mix_f32 v12, v8, v21, v12 op_sel_hi:[0,1,0]
	v_fma_mix_f32 v12, v9, v21, v12 op_sel:[0,1,0] op_sel_hi:[0,1,0]
	v_fma_mix_f32 v81, v6, v90, v180 op_sel_hi:[0,1,0]
	v_fma_mix_f32 v81, v7, v90, v81 op_sel:[0,1,0] op_sel_hi:[0,1,0]
	v_add_f32_dpp v12, v12, v12 row_ror:1 row_mask:0xf bank_mask:0xf bound_ctrl:1
	v_fma_mix_f32 v81, v8, v91, v81 op_sel_hi:[0,1,0]
	v_fma_mix_f32 v81, v9, v91, v81 op_sel:[0,1,0] op_sel_hi:[0,1,0]
	v_add_f32_dpp v12, v12, v12 row_ror:2 row_mask:0xf bank_mask:0xf bound_ctrl:1
	v_pk_mul_f32 v[48:49], v[6:7], v[16:17]
	v_pk_mul_f32 v[50:51], v[8:9], v[18:19]
	v_add_f32_dpp v12, v12, v12 row_ror:4 row_mask:0xf bank_mask:0xf bound_ctrl:1
	v_pk_fma_f32 v[48:49], v[28:29], v[72:73], v[48:49] op_sel:[0,1,0]
	v_pk_fma_f32 v[50:51], v[30:31], v[72:73], v[50:51] op_sel:[0,1,0]
	v_add_f32_dpp v12, v12, v12 row_ror:8 row_mask:0xf bank_mask:0xf bound_ctrl:1
	v_pk_fma_f32 v[6:7], v[24:25], v[12:13], v[48:49] op_sel_hi:[1,0,1] neg_lo:[1,0,0] neg_hi:[1,0,0]
	v_pk_fma_f32 v[8:9], v[26:27], v[12:13], v[50:51] op_sel_hi:[1,0,1] neg_lo:[1,0,0] neg_hi:[1,0,0]
	ds_read_b128 v[88:91], v10 offset:42240
	ds_read_b128 v[84:87], v10 offset:41984
	ds_read_b128 v[96:99], v10 offset:42752
	ds_read_b128 v[92:95], v10 offset:42496
	s_waitcnt lgkmcnt(4)
	v_fma_mix_f32 v12, v6, v36, v180 op_sel_hi:[0,1,0]
	v_fma_mix_f32 v12, v7, v36, v12 op_sel:[0,1,0] op_sel_hi:[0,1,0]
	v_fma_mix_f32 v12, v8, v37, v12 op_sel_hi:[0,1,0]
	v_fma_mix_f32 v12, v9, v37, v12 op_sel:[0,1,0] op_sel_hi:[0,1,0]
	v_fma_mix_f32 v82, v6, v22, v180 op_sel_hi:[0,1,0]
	v_fma_mix_f32 v82, v7, v22, v82 op_sel:[0,1,0] op_sel_hi:[0,1,0]
	v_add_f32_dpp v12, v12, v12 row_ror:1 row_mask:0xf bank_mask:0xf bound_ctrl:1
	v_fma_mix_f32 v82, v8, v23, v82 op_sel_hi:[0,1,0]
	v_fma_mix_f32 v82, v9, v23, v82 op_sel:[0,1,0] op_sel_hi:[0,1,0]
	v_add_f32_dpp v12, v12, v12 row_ror:2 row_mask:0xf bank_mask:0xf bound_ctrl:1
	v_pk_mul_f32 v[48:49], v[6:7], v[32:33]
	v_pk_mul_f32 v[50:51], v[8:9], v[34:35]
	v_add_f32_dpp v12, v12, v12 row_ror:4 row_mask:0xf bank_mask:0xf bound_ctrl:1
	v_pk_fma_f32 v[48:49], v[44:45], v[66:67], v[48:49] op_sel_hi:[1,0,1]
	v_pk_fma_f32 v[50:51], v[46:47], v[66:67], v[50:51] op_sel_hi:[1,0,1]
	v_add_f32_dpp v12, v12, v12 row_ror:8 row_mask:0xf bank_mask:0xf bound_ctrl:1
	v_pk_fma_f32 v[6:7], v[40:41], v[12:13], v[48:49] op_sel_hi:[1,0,1] neg_lo:[1,0,0] neg_hi:[1,0,0]
	v_pk_fma_f32 v[8:9], v[42:43], v[12:13], v[50:51] op_sel_hi:[1,0,1] neg_lo:[1,0,0] neg_hi:[1,0,0]
	ds_read_b128 v[20:23], v10 offset:43264
	ds_read_b128 v[16:19], v10 offset:43008
	ds_read_b128 v[28:31], v10 offset:43776
	ds_read_b128 v[24:27], v10 offset:43520
	s_waitcnt lgkmcnt(4)
	v_fma_mix_f32 v12, v6, v88, v180 op_sel_hi:[0,1,0]
	v_fma_mix_f32 v12, v7, v88, v12 op_sel:[0,1,0] op_sel_hi:[0,1,0]
	v_fma_mix_f32 v12, v8, v89, v12 op_sel_hi:[0,1,0]
	v_fma_mix_f32 v12, v9, v89, v12 op_sel:[0,1,0] op_sel_hi:[0,1,0]
	v_fma_mix_f32 v83, v6, v38, v180 op_sel_hi:[0,1,0]
	v_fma_mix_f32 v83, v7, v38, v83 op_sel:[0,1,0] op_sel_hi:[0,1,0]
	v_add_f32_dpp v12, v12, v12 row_ror:1 row_mask:0xf bank_mask:0xf bound_ctrl:1
	v_fma_mix_f32 v83, v8, v39, v83 op_sel_hi:[0,1,0]
	v_fma_mix_f32 v83, v9, v39, v83 op_sel:[0,1,0] op_sel_hi:[0,1,0]
	v_add_f32_dpp v12, v12, v12 row_ror:2 row_mask:0xf bank_mask:0xf bound_ctrl:1
	v_pk_mul_f32 v[48:49], v[6:7], v[84:85]
	v_pk_mul_f32 v[50:51], v[8:9], v[86:87]
	v_add_f32_dpp v12, v12, v12 row_ror:4 row_mask:0xf bank_mask:0xf bound_ctrl:1
	v_pk_fma_f32 v[48:49], v[96:97], v[66:67], v[48:49] op_sel:[0,1,0]
	v_pk_fma_f32 v[50:51], v[98:99], v[66:67], v[50:51] op_sel:[0,1,0]
	v_add_f32_dpp v12, v12, v12 row_ror:8 row_mask:0xf bank_mask:0xf bound_ctrl:1
	v_pk_fma_f32 v[6:7], v[92:93], v[12:13], v[48:49] op_sel_hi:[1,0,1] neg_lo:[1,0,0] neg_hi:[1,0,0]
	v_pk_fma_f32 v[8:9], v[94:95], v[12:13], v[50:51] op_sel_hi:[1,0,1] neg_lo:[1,0,0] neg_hi:[1,0,0]
	ds_read_b128 v[36:39], v10 offset:44288
	ds_read_b128 v[32:35], v10 offset:44032
	ds_read_b128 v[44:47], v10 offset:44800
	ds_read_b128 v[40:43], v10 offset:44544
	ds_read_b128 v[70:73], v11 offset:2816
	s_waitcnt lgkmcnt(5)
	v_fma_mix_f32 v12, v6, v20, v180 op_sel_hi:[0,1,0]
	v_fma_mix_f32 v12, v7, v20, v12 op_sel:[0,1,0] op_sel_hi:[0,1,0]
	v_fma_mix_f32 v12, v8, v21, v12 op_sel_hi:[0,1,0]
	v_fma_mix_f32 v12, v9, v21, v12 op_sel:[0,1,0] op_sel_hi:[0,1,0]
	v_fma_mix_f32 v100, v6, v90, v180 op_sel_hi:[0,1,0]
	v_fma_mix_f32 v100, v7, v90, v100 op_sel:[0,1,0] op_sel_hi:[0,1,0]
	v_add_f32_dpp v12, v12, v12 row_ror:1 row_mask:0xf bank_mask:0xf bound_ctrl:1
	v_fma_mix_f32 v100, v8, v91, v100 op_sel_hi:[0,1,0]
	v_fma_mix_f32 v100, v9, v91, v100 op_sel:[0,1,0] op_sel_hi:[0,1,0]
	v_add_f32_dpp v12, v12, v12 row_ror:2 row_mask:0xf bank_mask:0xf bound_ctrl:1
	v_pk_mul_f32 v[48:49], v[6:7], v[16:17]
	v_pk_mul_f32 v[50:51], v[8:9], v[18:19]
	v_add_f32_dpp v12, v12, v12 row_ror:4 row_mask:0xf bank_mask:0xf bound_ctrl:1
	v_pk_fma_f32 v[48:49], v[28:29], v[68:69], v[48:49] op_sel_hi:[1,0,1]
	v_pk_fma_f32 v[50:51], v[30:31], v[68:69], v[50:51] op_sel_hi:[1,0,1]
	v_add_f32_dpp v12, v12, v12 row_ror:8 row_mask:0xf bank_mask:0xf bound_ctrl:1
	v_pk_fma_f32 v[6:7], v[24:25], v[12:13], v[48:49] op_sel_hi:[1,0,1] neg_lo:[1,0,0] neg_hi:[1,0,0]
	v_pk_fma_f32 v[8:9], v[26:27], v[12:13], v[50:51] op_sel_hi:[1,0,1] neg_lo:[1,0,0] neg_hi:[1,0,0]
	ds_read_b128 v[88:91], v10 offset:45312
	ds_read_b128 v[84:87], v10 offset:45056
	ds_read_b128 v[96:99], v10 offset:45824
	ds_read_b128 v[92:95], v10 offset:45568
	s_waitcnt lgkmcnt(5)
	v_fma_mix_f32 v12, v6, v36, v180 op_sel_hi:[0,1,0]
	v_fma_mix_f32 v12, v7, v36, v12 op_sel:[0,1,0] op_sel_hi:[0,1,0]
	v_fma_mix_f32 v12, v8, v37, v12 op_sel_hi:[0,1,0]
	v_fma_mix_f32 v12, v9, v37, v12 op_sel:[0,1,0] op_sel_hi:[0,1,0]
	v_fma_mix_f32 v101, v6, v22, v180 op_sel_hi:[0,1,0]
	v_fma_mix_f32 v101, v7, v22, v101 op_sel:[0,1,0] op_sel_hi:[0,1,0]
	v_add_f32_dpp v12, v12, v12 row_ror:1 row_mask:0xf bank_mask:0xf bound_ctrl:1
	v_fma_mix_f32 v101, v8, v23, v101 op_sel_hi:[0,1,0]
	v_fma_mix_f32 v101, v9, v23, v101 op_sel:[0,1,0] op_sel_hi:[0,1,0]
	v_add_f32_dpp v12, v12, v12 row_ror:2 row_mask:0xf bank_mask:0xf bound_ctrl:1
	v_pk_mul_f32 v[48:49], v[6:7], v[32:33]
	v_pk_mul_f32 v[50:51], v[8:9], v[34:35]
	v_add_f32_dpp v12, v12, v12 row_ror:4 row_mask:0xf bank_mask:0xf bound_ctrl:1
	v_pk_fma_f32 v[48:49], v[44:45], v[68:69], v[48:49] op_sel:[0,1,0]
	v_pk_fma_f32 v[50:51], v[46:47], v[68:69], v[50:51] op_sel:[0,1,0]
	v_add_f32_dpp v12, v12, v12 row_ror:8 row_mask:0xf bank_mask:0xf bound_ctrl:1
	v_pk_fma_f32 v[6:7], v[40:41], v[12:13], v[48:49] op_sel_hi:[1,0,1] neg_lo:[1,0,0] neg_hi:[1,0,0]
	v_pk_fma_f32 v[8:9], v[42:43], v[12:13], v[50:51] op_sel_hi:[1,0,1] neg_lo:[1,0,0] neg_hi:[1,0,0]
	ds_read_b128 v[20:23], v10 offset:46336
	ds_read_b128 v[16:19], v10 offset:46080
	ds_read_b128 v[28:31], v10 offset:46848
	ds_read_b128 v[24:27], v10 offset:46592
	s_waitcnt lgkmcnt(4)
	v_fma_mix_f32 v12, v6, v88, v180 op_sel_hi:[0,1,0]
	v_fma_mix_f32 v12, v7, v88, v12 op_sel:[0,1,0] op_sel_hi:[0,1,0]
	v_fma_mix_f32 v12, v8, v89, v12 op_sel_hi:[0,1,0]
	v_fma_mix_f32 v12, v9, v89, v12 op_sel:[0,1,0] op_sel_hi:[0,1,0]
	v_fma_mix_f32 v102, v6, v38, v180 op_sel_hi:[0,1,0]
	v_fma_mix_f32 v102, v7, v38, v102 op_sel:[0,1,0] op_sel_hi:[0,1,0]
	v_add_f32_dpp v12, v12, v12 row_ror:1 row_mask:0xf bank_mask:0xf bound_ctrl:1
	v_fma_mix_f32 v102, v8, v39, v102 op_sel_hi:[0,1,0]
	v_fma_mix_f32 v102, v9, v39, v102 op_sel:[0,1,0] op_sel_hi:[0,1,0]
	v_add_f32_dpp v12, v12, v12 row_ror:2 row_mask:0xf bank_mask:0xf bound_ctrl:1
	v_pk_mul_f32 v[48:49], v[6:7], v[84:85]
	v_pk_mul_f32 v[50:51], v[8:9], v[86:87]
	v_add_f32_dpp v12, v12, v12 row_ror:4 row_mask:0xf bank_mask:0xf bound_ctrl:1
	v_pk_fma_f32 v[48:49], v[96:97], v[70:71], v[48:49] op_sel_hi:[1,0,1]
	v_pk_fma_f32 v[50:51], v[98:99], v[70:71], v[50:51] op_sel_hi:[1,0,1]
	v_add_f32_dpp v12, v12, v12 row_ror:8 row_mask:0xf bank_mask:0xf bound_ctrl:1
	v_pk_fma_f32 v[6:7], v[92:93], v[12:13], v[48:49] op_sel_hi:[1,0,1] neg_lo:[1,0,0] neg_hi:[1,0,0]
	v_pk_fma_f32 v[8:9], v[94:95], v[12:13], v[50:51] op_sel_hi:[1,0,1] neg_lo:[1,0,0] neg_hi:[1,0,0]
	ds_read_b128 v[36:39], v10 offset:47360
	ds_read_b128 v[32:35], v10 offset:47104
	ds_read_b128 v[44:47], v10 offset:47872
	ds_read_b128 v[40:43], v10 offset:47616
	s_waitcnt lgkmcnt(4)
	v_fma_mix_f32 v12, v6, v20, v180 op_sel_hi:[0,1,0]
	v_fma_mix_f32 v12, v7, v20, v12 op_sel:[0,1,0] op_sel_hi:[0,1,0]
	v_fma_mix_f32 v12, v8, v21, v12 op_sel_hi:[0,1,0]
	v_fma_mix_f32 v12, v9, v21, v12 op_sel:[0,1,0] op_sel_hi:[0,1,0]
	v_fma_mix_f32 v103, v6, v90, v180 op_sel_hi:[0,1,0]
	v_fma_mix_f32 v103, v7, v90, v103 op_sel:[0,1,0] op_sel_hi:[0,1,0]
	v_add_f32_dpp v12, v12, v12 row_ror:1 row_mask:0xf bank_mask:0xf bound_ctrl:1
	v_fma_mix_f32 v103, v8, v91, v103 op_sel_hi:[0,1,0]
	v_fma_mix_f32 v103, v9, v91, v103 op_sel:[0,1,0] op_sel_hi:[0,1,0]
	v_add_f32_dpp v12, v12, v12 row_ror:2 row_mask:0xf bank_mask:0xf bound_ctrl:1
	v_pk_mul_f32 v[48:49], v[6:7], v[16:17]
	v_pk_mul_f32 v[50:51], v[8:9], v[18:19]
	v_add_f32_dpp v12, v12, v12 row_ror:4 row_mask:0xf bank_mask:0xf bound_ctrl:1
	v_pk_fma_f32 v[48:49], v[28:29], v[70:71], v[48:49] op_sel:[0,1,0]
	v_pk_fma_f32 v[50:51], v[30:31], v[70:71], v[50:51] op_sel:[0,1,0]
	v_add_f32_dpp v12, v12, v12 row_ror:8 row_mask:0xf bank_mask:0xf bound_ctrl:1
	v_pk_fma_f32 v[6:7], v[24:25], v[12:13], v[48:49] op_sel_hi:[1,0,1] neg_lo:[1,0,0] neg_hi:[1,0,0]
	v_pk_fma_f32 v[8:9], v[26:27], v[12:13], v[50:51] op_sel_hi:[1,0,1] neg_lo:[1,0,0] neg_hi:[1,0,0]
	ds_read_b128 v[88:91], v10 offset:48384
	ds_read_b128 v[84:87], v10 offset:48128
	ds_read_b128 v[96:99], v10 offset:48896
	ds_read_b128 v[92:95], v10 offset:48640
	ds_read_b128 v[66:69], v11 offset:3072
	s_waitcnt lgkmcnt(5)
	v_fma_mix_f32 v12, v6, v36, v180 op_sel_hi:[0,1,0]
	v_fma_mix_f32 v12, v7, v36, v12 op_sel:[0,1,0] op_sel_hi:[0,1,0]
	v_fma_mix_f32 v12, v8, v37, v12 op_sel_hi:[0,1,0]
	v_fma_mix_f32 v12, v9, v37, v12 op_sel:[0,1,0] op_sel_hi:[0,1,0]
	v_fma_mix_f32 v104, v6, v22, v180 op_sel_hi:[0,1,0]
	v_fma_mix_f32 v104, v7, v22, v104 op_sel:[0,1,0] op_sel_hi:[0,1,0]
	v_add_f32_dpp v12, v12, v12 row_ror:1 row_mask:0xf bank_mask:0xf bound_ctrl:1
	v_fma_mix_f32 v104, v8, v23, v104 op_sel_hi:[0,1,0]
	v_fma_mix_f32 v104, v9, v23, v104 op_sel:[0,1,0] op_sel_hi:[0,1,0]
	v_add_f32_dpp v12, v12, v12 row_ror:2 row_mask:0xf bank_mask:0xf bound_ctrl:1
	v_pk_mul_f32 v[48:49], v[6:7], v[32:33]
	v_pk_mul_f32 v[50:51], v[8:9], v[34:35]
	v_add_f32_dpp v12, v12, v12 row_ror:4 row_mask:0xf bank_mask:0xf bound_ctrl:1
	v_pk_fma_f32 v[48:49], v[44:45], v[72:73], v[48:49] op_sel_hi:[1,0,1]
	v_pk_fma_f32 v[50:51], v[46:47], v[72:73], v[50:51] op_sel_hi:[1,0,1]
	v_add_f32_dpp v12, v12, v12 row_ror:8 row_mask:0xf bank_mask:0xf bound_ctrl:1
	v_pk_fma_f32 v[6:7], v[40:41], v[12:13], v[48:49] op_sel_hi:[1,0,1] neg_lo:[1,0,0] neg_hi:[1,0,0]
	v_pk_fma_f32 v[8:9], v[42:43], v[12:13], v[50:51] op_sel_hi:[1,0,1] neg_lo:[1,0,0] neg_hi:[1,0,0]
	ds_read_b128 v[20:23], v10 offset:49408
	ds_read_b128 v[16:19], v10 offset:49152
	ds_read_b128 v[28:31], v10 offset:49920
	ds_read_b128 v[24:27], v10 offset:49664
	s_waitcnt lgkmcnt(5)
	v_fma_mix_f32 v12, v6, v88, v180 op_sel_hi:[0,1,0]
	v_fma_mix_f32 v12, v7, v88, v12 op_sel:[0,1,0] op_sel_hi:[0,1,0]
	v_fma_mix_f32 v12, v8, v89, v12 op_sel_hi:[0,1,0]
	v_fma_mix_f32 v12, v9, v89, v12 op_sel:[0,1,0] op_sel_hi:[0,1,0]
	v_fma_mix_f32 v105, v6, v38, v180 op_sel_hi:[0,1,0]
	v_fma_mix_f32 v105, v7, v38, v105 op_sel:[0,1,0] op_sel_hi:[0,1,0]
	v_add_f32_dpp v12, v12, v12 row_ror:1 row_mask:0xf bank_mask:0xf bound_ctrl:1
	v_fma_mix_f32 v105, v8, v39, v105 op_sel_hi:[0,1,0]
	v_fma_mix_f32 v105, v9, v39, v105 op_sel:[0,1,0] op_sel_hi:[0,1,0]
	v_add_f32_dpp v12, v12, v12 row_ror:2 row_mask:0xf bank_mask:0xf bound_ctrl:1
	v_pk_mul_f32 v[48:49], v[6:7], v[84:85]
	v_pk_mul_f32 v[50:51], v[8:9], v[86:87]
	v_add_f32_dpp v12, v12, v12 row_ror:4 row_mask:0xf bank_mask:0xf bound_ctrl:1
	v_pk_fma_f32 v[48:49], v[96:97], v[72:73], v[48:49] op_sel:[0,1,0]
	v_pk_fma_f32 v[50:51], v[98:99], v[72:73], v[50:51] op_sel:[0,1,0]
	v_add_f32_dpp v12, v12, v12 row_ror:8 row_mask:0xf bank_mask:0xf bound_ctrl:1
	v_pk_fma_f32 v[6:7], v[92:93], v[12:13], v[48:49] op_sel_hi:[1,0,1] neg_lo:[1,0,0] neg_hi:[1,0,0]
	v_pk_fma_f32 v[8:9], v[94:95], v[12:13], v[50:51] op_sel_hi:[1,0,1] neg_lo:[1,0,0] neg_hi:[1,0,0]
	ds_read_b128 v[36:39], v10 offset:50432
	ds_read_b128 v[32:35], v10 offset:50176
	ds_read_b128 v[44:47], v10 offset:50944
	ds_read_b128 v[40:43], v10 offset:50688
	s_waitcnt lgkmcnt(4)
	v_fma_mix_f32 v12, v6, v20, v180 op_sel_hi:[0,1,0]
	v_fma_mix_f32 v12, v7, v20, v12 op_sel:[0,1,0] op_sel_hi:[0,1,0]
	v_fma_mix_f32 v12, v8, v21, v12 op_sel_hi:[0,1,0]
	v_fma_mix_f32 v12, v9, v21, v12 op_sel:[0,1,0] op_sel_hi:[0,1,0]
	v_fma_mix_f32 v61, v6, v90, v180 op_sel_hi:[0,1,0]
	v_fma_mix_f32 v61, v7, v90, v61 op_sel:[0,1,0] op_sel_hi:[0,1,0]
	v_add_f32_dpp v12, v12, v12 row_ror:1 row_mask:0xf bank_mask:0xf bound_ctrl:1
	v_fma_mix_f32 v61, v8, v91, v61 op_sel_hi:[0,1,0]
	v_fma_mix_f32 v61, v9, v91, v61 op_sel:[0,1,0] op_sel_hi:[0,1,0]
	v_add_f32_dpp v12, v12, v12 row_ror:2 row_mask:0xf bank_mask:0xf bound_ctrl:1
	v_pk_mul_f32 v[48:49], v[6:7], v[16:17]
	v_pk_mul_f32 v[50:51], v[8:9], v[18:19]
	v_add_f32_dpp v12, v12, v12 row_ror:4 row_mask:0xf bank_mask:0xf bound_ctrl:1
	v_pk_fma_f32 v[48:49], v[28:29], v[66:67], v[48:49] op_sel_hi:[1,0,1]
	v_pk_fma_f32 v[50:51], v[30:31], v[66:67], v[50:51] op_sel_hi:[1,0,1]
	v_add_f32_dpp v12, v12, v12 row_ror:8 row_mask:0xf bank_mask:0xf bound_ctrl:1
	v_pk_fma_f32 v[6:7], v[24:25], v[12:13], v[48:49] op_sel_hi:[1,0,1] neg_lo:[1,0,0] neg_hi:[1,0,0]
	v_pk_fma_f32 v[8:9], v[26:27], v[12:13], v[50:51] op_sel_hi:[1,0,1] neg_lo:[1,0,0] neg_hi:[1,0,0]
	ds_read_b128 v[88:91], v10 offset:51456
	ds_read_b128 v[84:87], v10 offset:51200
	ds_read_b128 v[96:99], v10 offset:51968
	ds_read_b128 v[92:95], v10 offset:51712
	v_add_f32_dpp v83, v83, v83 row_ror:8 row_mask:0xf bank_mask:0xc
	v_add_f32_dpp v83, v52, v52 row_ror:8 row_mask:0xf bank_mask:0x3
	v_add_f32_dpp v100, v100, v100 row_ror:8 row_mask:0xf bank_mask:0xc
	v_add_f32_dpp v100, v53, v53 row_ror:8 row_mask:0xf bank_mask:0x3
	v_add_f32_dpp v101, v101, v101 row_ror:8 row_mask:0xf bank_mask:0xc
	v_add_f32_dpp v101, v54, v54 row_ror:8 row_mask:0xf bank_mask:0x3
	v_add_f32_dpp v102, v102, v102 row_ror:8 row_mask:0xf bank_mask:0xc
	v_add_f32_dpp v102, v55, v55 row_ror:8 row_mask:0xf bank_mask:0x3
	v_add_f32_dpp v103, v103, v103 row_ror:8 row_mask:0xf bank_mask:0xc
	v_add_f32_dpp v103, v56, v56 row_ror:8 row_mask:0xf bank_mask:0x3
	v_add_f32_dpp v104, v104, v104 row_ror:8 row_mask:0xf bank_mask:0xc
	v_add_f32_dpp v104, v57, v57 row_ror:8 row_mask:0xf bank_mask:0x3
	v_add_f32_dpp v105, v105, v105 row_ror:8 row_mask:0xf bank_mask:0xc
	v_add_f32_dpp v105, v81, v81 row_ror:8 row_mask:0xf bank_mask:0x3
	v_add_f32_dpp v61, v61, v61 row_ror:8 row_mask:0xf bank_mask:0xc
	v_add_f32_dpp v61, v82, v82 row_ror:8 row_mask:0xf bank_mask:0x3
	v_add_f32_dpp v103, v103, v103 row_ror:4 row_mask:0xf bank_mask:0xa
	v_add_f32_dpp v103, v83, v83 row_ror:12 row_mask:0xf bank_mask:0x5
	v_add_f32_dpp v104, v104, v104 row_ror:4 row_mask:0xf bank_mask:0xa
	v_add_f32_dpp v104, v100, v100 row_ror:12 row_mask:0xf bank_mask:0x5
	v_add_f32_dpp v105, v105, v105 row_ror:4 row_mask:0xf bank_mask:0xa
	v_add_f32_dpp v105, v101, v101 row_ror:12 row_mask:0xf bank_mask:0x5
	v_add_f32_dpp v61, v61, v61 row_ror:4 row_mask:0xf bank_mask:0xa
	v_add_f32_dpp v61, v102, v102 row_ror:12 row_mask:0xf bank_mask:0x5
	v_cndmask_b32_e64 v62, v105, v103, s[38:39]
	v_cndmask_b32_e64 v63, v103, v105, s[38:39]
	v_cndmask_b32_e64 v64, v61, v104, s[38:39]
	v_cndmask_b32_e64 v65, v104, v61, s[38:39]
	v_add_f32_dpp v62, v63, v62 quad_perm:[2,3,0,1] row_mask:0xf bank_mask:0xf bound_ctrl:1
	s_nop 0
	v_add_f32_dpp v63, v65, v64 quad_perm:[2,3,0,1] row_mask:0xf bank_mask:0xf bound_ctrl:1
	v_cndmask_b32_e64 v65, v63, v62, s[40:41]
	v_cndmask_b32_e64 v62, v62, v63, s[40:41]
	s_nop 1
	v_add_f32_dpp v62, v62, v65 quad_perm:[1,0,3,2] row_mask:0xf bank_mask:0xf bound_ctrl:1
	v_cvt_pk_bf16_f32 v62, v62, v62
	global_store_short v[2:3], v62, off
	v_lshl_add_u64 v[2:3], v[2:3], 0, s[84:85]
	s_waitcnt lgkmcnt(4)
	v_fma_mix_f32 v12, v6, v36, v180 op_sel_hi:[0,1,0]
	v_fma_mix_f32 v12, v7, v36, v12 op_sel:[0,1,0] op_sel_hi:[0,1,0]
	v_fma_mix_f32 v12, v8, v37, v12 op_sel_hi:[0,1,0]
	v_fma_mix_f32 v12, v9, v37, v12 op_sel:[0,1,0] op_sel_hi:[0,1,0]
	v_fma_mix_f32 v52, v6, v22, v180 op_sel_hi:[0,1,0]
	v_fma_mix_f32 v52, v7, v22, v52 op_sel:[0,1,0] op_sel_hi:[0,1,0]
	v_add_f32_dpp v12, v12, v12 row_ror:1 row_mask:0xf bank_mask:0xf bound_ctrl:1
	v_fma_mix_f32 v52, v8, v23, v52 op_sel_hi:[0,1,0]
	v_fma_mix_f32 v52, v9, v23, v52 op_sel:[0,1,0] op_sel_hi:[0,1,0]
	v_add_f32_dpp v12, v12, v12 row_ror:2 row_mask:0xf bank_mask:0xf bound_ctrl:1
	v_pk_mul_f32 v[48:49], v[6:7], v[32:33]
	v_pk_mul_f32 v[50:51], v[8:9], v[34:35]
	v_add_f32_dpp v12, v12, v12 row_ror:4 row_mask:0xf bank_mask:0xf bound_ctrl:1
	v_pk_fma_f32 v[48:49], v[44:45], v[66:67], v[48:49] op_sel:[0,1,0]
	v_pk_fma_f32 v[50:51], v[46:47], v[66:67], v[50:51] op_sel:[0,1,0]
	v_add_f32_dpp v12, v12, v12 row_ror:8 row_mask:0xf bank_mask:0xf bound_ctrl:1
	v_pk_fma_f32 v[6:7], v[40:41], v[12:13], v[48:49] op_sel_hi:[1,0,1] neg_lo:[1,0,0] neg_hi:[1,0,0]
	v_pk_fma_f32 v[8:9], v[42:43], v[12:13], v[50:51] op_sel_hi:[1,0,1] neg_lo:[1,0,0] neg_hi:[1,0,0]
	ds_read_b128 v[20:23], v10 offset:52480
	ds_read_b128 v[16:19], v10 offset:52224
	ds_read_b128 v[28:31], v10 offset:52992
	ds_read_b128 v[24:27], v10 offset:52736
	ds_read_b128 v[70:73], v11 offset:3328
	s_waitcnt lgkmcnt(5)
	v_fma_mix_f32 v12, v6, v88, v180 op_sel_hi:[0,1,0]
	v_fma_mix_f32 v12, v7, v88, v12 op_sel:[0,1,0] op_sel_hi:[0,1,0]
	v_fma_mix_f32 v12, v8, v89, v12 op_sel_hi:[0,1,0]
	v_fma_mix_f32 v12, v9, v89, v12 op_sel:[0,1,0] op_sel_hi:[0,1,0]
	v_fma_mix_f32 v53, v6, v38, v180 op_sel_hi:[0,1,0]
	v_fma_mix_f32 v53, v7, v38, v53 op_sel:[0,1,0] op_sel_hi:[0,1,0]
	v_add_f32_dpp v12, v12, v12 row_ror:1 row_mask:0xf bank_mask:0xf bound_ctrl:1
	v_fma_mix_f32 v53, v8, v39, v53 op_sel_hi:[0,1,0]
	v_fma_mix_f32 v53, v9, v39, v53 op_sel:[0,1,0] op_sel_hi:[0,1,0]
	v_add_f32_dpp v12, v12, v12 row_ror:2 row_mask:0xf bank_mask:0xf bound_ctrl:1
	v_pk_mul_f32 v[48:49], v[6:7], v[84:85]
	v_pk_mul_f32 v[50:51], v[8:9], v[86:87]
	v_add_f32_dpp v12, v12, v12 row_ror:4 row_mask:0xf bank_mask:0xf bound_ctrl:1
	v_pk_fma_f32 v[48:49], v[96:97], v[68:69], v[48:49] op_sel_hi:[1,0,1]
	v_pk_fma_f32 v[50:51], v[98:99], v[68:69], v[50:51] op_sel_hi:[1,0,1]
	v_add_f32_dpp v12, v12, v12 row_ror:8 row_mask:0xf bank_mask:0xf bound_ctrl:1
	v_pk_fma_f32 v[6:7], v[92:93], v[12:13], v[48:49] op_sel_hi:[1,0,1] neg_lo:[1,0,0] neg_hi:[1,0,0]
	v_pk_fma_f32 v[8:9], v[94:95], v[12:13], v[50:51] op_sel_hi:[1,0,1] neg_lo:[1,0,0] neg_hi:[1,0,0]
	ds_read_b128 v[36:39], v10 offset:53504
	ds_read_b128 v[32:35], v10 offset:53248
	ds_read_b128 v[44:47], v10 offset:54016
	ds_read_b128 v[40:43], v10 offset:53760
	s_waitcnt lgkmcnt(5)
	v_fma_mix_f32 v12, v6, v20, v180 op_sel_hi:[0,1,0]
	v_fma_mix_f32 v12, v7, v20, v12 op_sel:[0,1,0] op_sel_hi:[0,1,0]
	v_fma_mix_f32 v12, v8, v21, v12 op_sel_hi:[0,1,0]
	v_fma_mix_f32 v12, v9, v21, v12 op_sel:[0,1,0] op_sel_hi:[0,1,0]
	v_fma_mix_f32 v54, v6, v90, v180 op_sel_hi:[0,1,0]
	v_fma_mix_f32 v54, v7, v90, v54 op_sel:[0,1,0] op_sel_hi:[0,1,0]
	v_add_f32_dpp v12, v12, v12 row_ror:1 row_mask:0xf bank_mask:0xf bound_ctrl:1
	v_fma_mix_f32 v54, v8, v91, v54 op_sel_hi:[0,1,0]
	v_fma_mix_f32 v54, v9, v91, v54 op_sel:[0,1,0] op_sel_hi:[0,1,0]
	v_add_f32_dpp v12, v12, v12 row_ror:2 row_mask:0xf bank_mask:0xf bound_ctrl:1
	v_pk_mul_f32 v[48:49], v[6:7], v[16:17]
	v_pk_mul_f32 v[50:51], v[8:9], v[18:19]
	v_add_f32_dpp v12, v12, v12 row_ror:4 row_mask:0xf bank_mask:0xf bound_ctrl:1
	v_pk_fma_f32 v[48:49], v[28:29], v[68:69], v[48:49] op_sel:[0,1,0]
	v_pk_fma_f32 v[50:51], v[30:31], v[68:69], v[50:51] op_sel:[0,1,0]
	v_add_f32_dpp v12, v12, v12 row_ror:8 row_mask:0xf bank_mask:0xf bound_ctrl:1
	v_pk_fma_f32 v[6:7], v[24:25], v[12:13], v[48:49] op_sel_hi:[1,0,1] neg_lo:[1,0,0] neg_hi:[1,0,0]
	v_pk_fma_f32 v[8:9], v[26:27], v[12:13], v[50:51] op_sel_hi:[1,0,1] neg_lo:[1,0,0] neg_hi:[1,0,0]
	ds_read_b128 v[88:91], v10 offset:54528
	ds_read_b128 v[84:87], v10 offset:54272
	ds_read_b128 v[96:99], v10 offset:55040
	ds_read_b128 v[92:95], v10 offset:54784
	s_waitcnt lgkmcnt(4)
	v_fma_mix_f32 v12, v6, v36, v180 op_sel_hi:[0,1,0]
	v_fma_mix_f32 v12, v7, v36, v12 op_sel:[0,1,0] op_sel_hi:[0,1,0]
	v_fma_mix_f32 v12, v8, v37, v12 op_sel_hi:[0,1,0]
	v_fma_mix_f32 v12, v9, v37, v12 op_sel:[0,1,0] op_sel_hi:[0,1,0]
	v_fma_mix_f32 v55, v6, v22, v180 op_sel_hi:[0,1,0]
	v_fma_mix_f32 v55, v7, v22, v55 op_sel:[0,1,0] op_sel_hi:[0,1,0]
	v_add_f32_dpp v12, v12, v12 row_ror:1 row_mask:0xf bank_mask:0xf bound_ctrl:1
	v_fma_mix_f32 v55, v8, v23, v55 op_sel_hi:[0,1,0]
	v_fma_mix_f32 v55, v9, v23, v55 op_sel:[0,1,0] op_sel_hi:[0,1,0]
	v_add_f32_dpp v12, v12, v12 row_ror:2 row_mask:0xf bank_mask:0xf bound_ctrl:1
	v_pk_mul_f32 v[48:49], v[6:7], v[32:33]
	v_pk_mul_f32 v[50:51], v[8:9], v[34:35]
	v_add_f32_dpp v12, v12, v12 row_ror:4 row_mask:0xf bank_mask:0xf bound_ctrl:1
	v_pk_fma_f32 v[48:49], v[44:45], v[70:71], v[48:49] op_sel_hi:[1,0,1]
	v_pk_fma_f32 v[50:51], v[46:47], v[70:71], v[50:51] op_sel_hi:[1,0,1]
	v_add_f32_dpp v12, v12, v12 row_ror:8 row_mask:0xf bank_mask:0xf bound_ctrl:1
	v_pk_fma_f32 v[6:7], v[40:41], v[12:13], v[48:49] op_sel_hi:[1,0,1] neg_lo:[1,0,0] neg_hi:[1,0,0]
	v_pk_fma_f32 v[8:9], v[42:43], v[12:13], v[50:51] op_sel_hi:[1,0,1] neg_lo:[1,0,0] neg_hi:[1,0,0]
	ds_read_b128 v[20:23], v10 offset:55552
	ds_read_b128 v[16:19], v10 offset:55296
	ds_read_b128 v[28:31], v10 offset:56064
	ds_read_b128 v[24:27], v10 offset:55808
	s_waitcnt lgkmcnt(4)
	v_fma_mix_f32 v12, v6, v88, v180 op_sel_hi:[0,1,0]
	v_fma_mix_f32 v12, v7, v88, v12 op_sel:[0,1,0] op_sel_hi:[0,1,0]
	v_fma_mix_f32 v12, v8, v89, v12 op_sel_hi:[0,1,0]
	v_fma_mix_f32 v12, v9, v89, v12 op_sel:[0,1,0] op_sel_hi:[0,1,0]
	v_fma_mix_f32 v56, v6, v38, v180 op_sel_hi:[0,1,0]
	v_fma_mix_f32 v56, v7, v38, v56 op_sel:[0,1,0] op_sel_hi:[0,1,0]
	v_add_f32_dpp v12, v12, v12 row_ror:1 row_mask:0xf bank_mask:0xf bound_ctrl:1
	v_fma_mix_f32 v56, v8, v39, v56 op_sel_hi:[0,1,0]
	v_fma_mix_f32 v56, v9, v39, v56 op_sel:[0,1,0] op_sel_hi:[0,1,0]
	v_add_f32_dpp v12, v12, v12 row_ror:2 row_mask:0xf bank_mask:0xf bound_ctrl:1
	v_pk_mul_f32 v[48:49], v[6:7], v[84:85]
	v_pk_mul_f32 v[50:51], v[8:9], v[86:87]
	v_add_f32_dpp v12, v12, v12 row_ror:4 row_mask:0xf bank_mask:0xf bound_ctrl:1
	v_pk_fma_f32 v[48:49], v[96:97], v[70:71], v[48:49] op_sel:[0,1,0]
	v_pk_fma_f32 v[50:51], v[98:99], v[70:71], v[50:51] op_sel:[0,1,0]
	v_add_f32_dpp v12, v12, v12 row_ror:8 row_mask:0xf bank_mask:0xf bound_ctrl:1
	v_pk_fma_f32 v[6:7], v[92:93], v[12:13], v[48:49] op_sel_hi:[1,0,1] neg_lo:[1,0,0] neg_hi:[1,0,0]
	v_pk_fma_f32 v[8:9], v[94:95], v[12:13], v[50:51] op_sel_hi:[1,0,1] neg_lo:[1,0,0] neg_hi:[1,0,0]
	ds_read_b128 v[36:39], v10 offset:56576
	ds_read_b128 v[32:35], v10 offset:56320
	ds_read_b128 v[44:47], v10 offset:57088
	ds_read_b128 v[40:43], v10 offset:56832
	ds_read_b128 v[66:69], v11 offset:3584
	s_waitcnt lgkmcnt(5)
	v_fma_mix_f32 v12, v6, v20, v180 op_sel_hi:[0,1,0]
	v_fma_mix_f32 v12, v7, v20, v12 op_sel:[0,1,0] op_sel_hi:[0,1,0]
	v_fma_mix_f32 v12, v8, v21, v12 op_sel_hi:[0,1,0]
	v_fma_mix_f32 v12, v9, v21, v12 op_sel:[0,1,0] op_sel_hi:[0,1,0]
	v_fma_mix_f32 v57, v6, v90, v180 op_sel_hi:[0,1,0]
	v_fma_mix_f32 v57, v7, v90, v57 op_sel:[0,1,0] op_sel_hi:[0,1,0]
	v_add_f32_dpp v12, v12, v12 row_ror:1 row_mask:0xf bank_mask:0xf bound_ctrl:1
	v_fma_mix_f32 v57, v8, v91, v57 op_sel_hi:[0,1,0]
	v_fma_mix_f32 v57, v9, v91, v57 op_sel:[0,1,0] op_sel_hi:[0,1,0]
	v_add_f32_dpp v12, v12, v12 row_ror:2 row_mask:0xf bank_mask:0xf bound_ctrl:1
	v_pk_mul_f32 v[48:49], v[6:7], v[16:17]
	v_pk_mul_f32 v[50:51], v[8:9], v[18:19]
	v_add_f32_dpp v12, v12, v12 row_ror:4 row_mask:0xf bank_mask:0xf bound_ctrl:1
	v_pk_fma_f32 v[48:49], v[28:29], v[72:73], v[48:49] op_sel_hi:[1,0,1]
	v_pk_fma_f32 v[50:51], v[30:31], v[72:73], v[50:51] op_sel_hi:[1,0,1]
	v_add_f32_dpp v12, v12, v12 row_ror:8 row_mask:0xf bank_mask:0xf bound_ctrl:1
	v_pk_fma_f32 v[6:7], v[24:25], v[12:13], v[48:49] op_sel_hi:[1,0,1] neg_lo:[1,0,0] neg_hi:[1,0,0]
	v_pk_fma_f32 v[8:9], v[26:27], v[12:13], v[50:51] op_sel_hi:[1,0,1] neg_lo:[1,0,0] neg_hi:[1,0,0]
	ds_read_b128 v[88:91], v10 offset:57600
	ds_read_b128 v[84:87], v10 offset:57344
	ds_read_b128 v[96:99], v10 offset:58112
	ds_read_b128 v[92:95], v10 offset:57856
	s_waitcnt lgkmcnt(5)
	v_fma_mix_f32 v12, v6, v36, v180 op_sel_hi:[0,1,0]
	v_fma_mix_f32 v12, v7, v36, v12 op_sel:[0,1,0] op_sel_hi:[0,1,0]
	v_fma_mix_f32 v12, v8, v37, v12 op_sel_hi:[0,1,0]
	v_fma_mix_f32 v12, v9, v37, v12 op_sel:[0,1,0] op_sel_hi:[0,1,0]
	v_fma_mix_f32 v81, v6, v22, v180 op_sel_hi:[0,1,0]
	v_fma_mix_f32 v81, v7, v22, v81 op_sel:[0,1,0] op_sel_hi:[0,1,0]
	v_add_f32_dpp v12, v12, v12 row_ror:1 row_mask:0xf bank_mask:0xf bound_ctrl:1
	v_fma_mix_f32 v81, v8, v23, v81 op_sel_hi:[0,1,0]
	v_fma_mix_f32 v81, v9, v23, v81 op_sel:[0,1,0] op_sel_hi:[0,1,0]
	v_add_f32_dpp v12, v12, v12 row_ror:2 row_mask:0xf bank_mask:0xf bound_ctrl:1
	v_pk_mul_f32 v[48:49], v[6:7], v[32:33]
	v_pk_mul_f32 v[50:51], v[8:9], v[34:35]
	v_add_f32_dpp v12, v12, v12 row_ror:4 row_mask:0xf bank_mask:0xf bound_ctrl:1
	v_pk_fma_f32 v[48:49], v[44:45], v[72:73], v[48:49] op_sel:[0,1,0]
	v_pk_fma_f32 v[50:51], v[46:47], v[72:73], v[50:51] op_sel:[0,1,0]
	v_add_f32_dpp v12, v12, v12 row_ror:8 row_mask:0xf bank_mask:0xf bound_ctrl:1
	v_pk_fma_f32 v[6:7], v[40:41], v[12:13], v[48:49] op_sel_hi:[1,0,1] neg_lo:[1,0,0] neg_hi:[1,0,0]
	v_pk_fma_f32 v[8:9], v[42:43], v[12:13], v[50:51] op_sel_hi:[1,0,1] neg_lo:[1,0,0] neg_hi:[1,0,0]
	ds_read_b128 v[20:23], v10 offset:58624
	ds_read_b128 v[16:19], v10 offset:58368
	ds_read_b128 v[28:31], v10 offset:59136
	ds_read_b128 v[24:27], v10 offset:58880
	s_waitcnt lgkmcnt(4)
	v_fma_mix_f32 v12, v6, v88, v180 op_sel_hi:[0,1,0]
	v_fma_mix_f32 v12, v7, v88, v12 op_sel:[0,1,0] op_sel_hi:[0,1,0]
	v_fma_mix_f32 v12, v8, v89, v12 op_sel_hi:[0,1,0]
	v_fma_mix_f32 v12, v9, v89, v12 op_sel:[0,1,0] op_sel_hi:[0,1,0]
	v_fma_mix_f32 v82, v6, v38, v180 op_sel_hi:[0,1,0]
	v_fma_mix_f32 v82, v7, v38, v82 op_sel:[0,1,0] op_sel_hi:[0,1,0]
	v_add_f32_dpp v12, v12, v12 row_ror:1 row_mask:0xf bank_mask:0xf bound_ctrl:1
	v_fma_mix_f32 v82, v8, v39, v82 op_sel_hi:[0,1,0]
	v_fma_mix_f32 v82, v9, v39, v82 op_sel:[0,1,0] op_sel_hi:[0,1,0]
	v_add_f32_dpp v12, v12, v12 row_ror:2 row_mask:0xf bank_mask:0xf bound_ctrl:1
	v_pk_mul_f32 v[48:49], v[6:7], v[84:85]
	v_pk_mul_f32 v[50:51], v[8:9], v[86:87]
	v_add_f32_dpp v12, v12, v12 row_ror:4 row_mask:0xf bank_mask:0xf bound_ctrl:1
	v_pk_fma_f32 v[48:49], v[96:97], v[66:67], v[48:49] op_sel_hi:[1,0,1]
	v_pk_fma_f32 v[50:51], v[98:99], v[66:67], v[50:51] op_sel_hi:[1,0,1]
	v_add_f32_dpp v12, v12, v12 row_ror:8 row_mask:0xf bank_mask:0xf bound_ctrl:1
	v_pk_fma_f32 v[6:7], v[92:93], v[12:13], v[48:49] op_sel_hi:[1,0,1] neg_lo:[1,0,0] neg_hi:[1,0,0]
	v_pk_fma_f32 v[8:9], v[94:95], v[12:13], v[50:51] op_sel_hi:[1,0,1] neg_lo:[1,0,0] neg_hi:[1,0,0]
	ds_read_b128 v[36:39], v10 offset:59648
	ds_read_b128 v[32:35], v10 offset:59392
	ds_read_b128 v[44:47], v10 offset:60160
	ds_read_b128 v[40:43], v10 offset:59904
	s_waitcnt lgkmcnt(4)
	v_fma_mix_f32 v12, v6, v20, v180 op_sel_hi:[0,1,0]
	v_fma_mix_f32 v12, v7, v20, v12 op_sel:[0,1,0] op_sel_hi:[0,1,0]
	v_fma_mix_f32 v12, v8, v21, v12 op_sel_hi:[0,1,0]
	v_fma_mix_f32 v12, v9, v21, v12 op_sel:[0,1,0] op_sel_hi:[0,1,0]
	v_fma_mix_f32 v83, v6, v90, v180 op_sel_hi:[0,1,0]
	v_fma_mix_f32 v83, v7, v90, v83 op_sel:[0,1,0] op_sel_hi:[0,1,0]
	v_add_f32_dpp v12, v12, v12 row_ror:1 row_mask:0xf bank_mask:0xf bound_ctrl:1
	v_fma_mix_f32 v83, v8, v91, v83 op_sel_hi:[0,1,0]
	v_fma_mix_f32 v83, v9, v91, v83 op_sel:[0,1,0] op_sel_hi:[0,1,0]
	v_add_f32_dpp v12, v12, v12 row_ror:2 row_mask:0xf bank_mask:0xf bound_ctrl:1
	v_pk_mul_f32 v[48:49], v[6:7], v[16:17]
	v_pk_mul_f32 v[50:51], v[8:9], v[18:19]
	v_add_f32_dpp v12, v12, v12 row_ror:4 row_mask:0xf bank_mask:0xf bound_ctrl:1
	v_pk_fma_f32 v[48:49], v[28:29], v[66:67], v[48:49] op_sel:[0,1,0]
	v_pk_fma_f32 v[50:51], v[30:31], v[66:67], v[50:51] op_sel:[0,1,0]
	v_add_f32_dpp v12, v12, v12 row_ror:8 row_mask:0xf bank_mask:0xf bound_ctrl:1
	v_pk_fma_f32 v[6:7], v[24:25], v[12:13], v[48:49] op_sel_hi:[1,0,1] neg_lo:[1,0,0] neg_hi:[1,0,0]
	v_pk_fma_f32 v[8:9], v[26:27], v[12:13], v[50:51] op_sel_hi:[1,0,1] neg_lo:[1,0,0] neg_hi:[1,0,0]
	ds_read_b128 v[88:91], v10 offset:60672
	ds_read_b128 v[84:87], v10 offset:60416
	ds_read_b128 v[96:99], v10 offset:61184
	ds_read_b128 v[92:95], v10 offset:60928
	ds_read_b128 v[70:73], v11 offset:3840
	s_waitcnt lgkmcnt(5)
	v_fma_mix_f32 v12, v6, v36, v180 op_sel_hi:[0,1,0]
	v_fma_mix_f32 v12, v7, v36, v12 op_sel:[0,1,0] op_sel_hi:[0,1,0]
	v_fma_mix_f32 v12, v8, v37, v12 op_sel_hi:[0,1,0]
	v_fma_mix_f32 v12, v9, v37, v12 op_sel:[0,1,0] op_sel_hi:[0,1,0]
	v_fma_mix_f32 v100, v6, v22, v180 op_sel_hi:[0,1,0]
	v_fma_mix_f32 v100, v7, v22, v100 op_sel:[0,1,0] op_sel_hi:[0,1,0]
	v_add_f32_dpp v12, v12, v12 row_ror:1 row_mask:0xf bank_mask:0xf bound_ctrl:1
	v_fma_mix_f32 v100, v8, v23, v100 op_sel_hi:[0,1,0]
	v_fma_mix_f32 v100, v9, v23, v100 op_sel:[0,1,0] op_sel_hi:[0,1,0]
	v_add_f32_dpp v12, v12, v12 row_ror:2 row_mask:0xf bank_mask:0xf bound_ctrl:1
	v_pk_mul_f32 v[48:49], v[6:7], v[32:33]
	v_pk_mul_f32 v[50:51], v[8:9], v[34:35]
	v_add_f32_dpp v12, v12, v12 row_ror:4 row_mask:0xf bank_mask:0xf bound_ctrl:1
	v_pk_fma_f32 v[48:49], v[44:45], v[68:69], v[48:49] op_sel_hi:[1,0,1]
	v_pk_fma_f32 v[50:51], v[46:47], v[68:69], v[50:51] op_sel_hi:[1,0,1]
	v_add_f32_dpp v12, v12, v12 row_ror:8 row_mask:0xf bank_mask:0xf bound_ctrl:1
	v_pk_fma_f32 v[6:7], v[40:41], v[12:13], v[48:49] op_sel_hi:[1,0,1] neg_lo:[1,0,0] neg_hi:[1,0,0]
	v_pk_fma_f32 v[8:9], v[42:43], v[12:13], v[50:51] op_sel_hi:[1,0,1] neg_lo:[1,0,0] neg_hi:[1,0,0]
	ds_read_b128 v[20:23], v10 offset:61696
	ds_read_b128 v[16:19], v10 offset:61440
	ds_read_b128 v[28:31], v10 offset:62208
	ds_read_b128 v[24:27], v10 offset:61952
	s_waitcnt lgkmcnt(5)
	v_fma_mix_f32 v12, v6, v88, v180 op_sel_hi:[0,1,0]
	v_fma_mix_f32 v12, v7, v88, v12 op_sel:[0,1,0] op_sel_hi:[0,1,0]
	v_fma_mix_f32 v12, v8, v89, v12 op_sel_hi:[0,1,0]
	v_fma_mix_f32 v12, v9, v89, v12 op_sel:[0,1,0] op_sel_hi:[0,1,0]
	v_fma_mix_f32 v101, v6, v38, v180 op_sel_hi:[0,1,0]
	v_fma_mix_f32 v101, v7, v38, v101 op_sel:[0,1,0] op_sel_hi:[0,1,0]
	v_add_f32_dpp v12, v12, v12 row_ror:1 row_mask:0xf bank_mask:0xf bound_ctrl:1
	v_fma_mix_f32 v101, v8, v39, v101 op_sel_hi:[0,1,0]
	v_fma_mix_f32 v101, v9, v39, v101 op_sel:[0,1,0] op_sel_hi:[0,1,0]
	v_add_f32_dpp v12, v12, v12 row_ror:2 row_mask:0xf bank_mask:0xf bound_ctrl:1
	v_pk_mul_f32 v[48:49], v[6:7], v[84:85]
	v_pk_mul_f32 v[50:51], v[8:9], v[86:87]
	v_add_f32_dpp v12, v12, v12 row_ror:4 row_mask:0xf bank_mask:0xf bound_ctrl:1
	v_pk_fma_f32 v[48:49], v[96:97], v[68:69], v[48:49] op_sel:[0,1,0]
	v_pk_fma_f32 v[50:51], v[98:99], v[68:69], v[50:51] op_sel:[0,1,0]
	v_add_f32_dpp v12, v12, v12 row_ror:8 row_mask:0xf bank_mask:0xf bound_ctrl:1
	v_pk_fma_f32 v[6:7], v[92:93], v[12:13], v[48:49] op_sel_hi:[1,0,1] neg_lo:[1,0,0] neg_hi:[1,0,0]
	v_pk_fma_f32 v[8:9], v[94:95], v[12:13], v[50:51] op_sel_hi:[1,0,1] neg_lo:[1,0,0] neg_hi:[1,0,0]
	ds_read_b128 v[36:39], v10 offset:62720
	ds_read_b128 v[32:35], v10 offset:62464
	ds_read_b128 v[44:47], v10 offset:63232
	ds_read_b128 v[40:43], v10 offset:62976
	s_waitcnt lgkmcnt(4)
	v_fma_mix_f32 v12, v6, v20, v180 op_sel_hi:[0,1,0]
	v_fma_mix_f32 v12, v7, v20, v12 op_sel:[0,1,0] op_sel_hi:[0,1,0]
	v_fma_mix_f32 v12, v8, v21, v12 op_sel_hi:[0,1,0]
	v_fma_mix_f32 v12, v9, v21, v12 op_sel:[0,1,0] op_sel_hi:[0,1,0]
	v_fma_mix_f32 v102, v6, v90, v180 op_sel_hi:[0,1,0]
	v_fma_mix_f32 v102, v7, v90, v102 op_sel:[0,1,0] op_sel_hi:[0,1,0]
	v_add_f32_dpp v12, v12, v12 row_ror:1 row_mask:0xf bank_mask:0xf bound_ctrl:1
	v_fma_mix_f32 v102, v8, v91, v102 op_sel_hi:[0,1,0]
	v_fma_mix_f32 v102, v9, v91, v102 op_sel:[0,1,0] op_sel_hi:[0,1,0]
	v_add_f32_dpp v12, v12, v12 row_ror:2 row_mask:0xf bank_mask:0xf bound_ctrl:1
	v_pk_mul_f32 v[48:49], v[6:7], v[16:17]
	v_pk_mul_f32 v[50:51], v[8:9], v[18:19]
	v_add_f32_dpp v12, v12, v12 row_ror:4 row_mask:0xf bank_mask:0xf bound_ctrl:1
	v_pk_fma_f32 v[48:49], v[28:29], v[70:71], v[48:49] op_sel_hi:[1,0,1]
	v_pk_fma_f32 v[50:51], v[30:31], v[70:71], v[50:51] op_sel_hi:[1,0,1]
	v_add_f32_dpp v12, v12, v12 row_ror:8 row_mask:0xf bank_mask:0xf bound_ctrl:1
	v_pk_fma_f32 v[6:7], v[24:25], v[12:13], v[48:49] op_sel_hi:[1,0,1] neg_lo:[1,0,0] neg_hi:[1,0,0]
	v_pk_fma_f32 v[8:9], v[26:27], v[12:13], v[50:51] op_sel_hi:[1,0,1] neg_lo:[1,0,0] neg_hi:[1,0,0]
	ds_read_b128 v[88:91], v10 offset:63744
	ds_read_b128 v[84:87], v10 offset:63488
	ds_read_b128 v[96:99], v10 offset:64256
	ds_read_b128 v[92:95], v10 offset:64000
	s_waitcnt lgkmcnt(4)
	v_fma_mix_f32 v12, v6, v36, v180 op_sel_hi:[0,1,0]
	v_fma_mix_f32 v12, v7, v36, v12 op_sel:[0,1,0] op_sel_hi:[0,1,0]
	v_fma_mix_f32 v12, v8, v37, v12 op_sel_hi:[0,1,0]
	v_fma_mix_f32 v12, v9, v37, v12 op_sel:[0,1,0] op_sel_hi:[0,1,0]
	v_fma_mix_f32 v103, v6, v22, v180 op_sel_hi:[0,1,0]
	v_fma_mix_f32 v103, v7, v22, v103 op_sel:[0,1,0] op_sel_hi:[0,1,0]
	v_add_f32_dpp v12, v12, v12 row_ror:1 row_mask:0xf bank_mask:0xf bound_ctrl:1
	v_fma_mix_f32 v103, v8, v23, v103 op_sel_hi:[0,1,0]
	v_fma_mix_f32 v103, v9, v23, v103 op_sel:[0,1,0] op_sel_hi:[0,1,0]
	v_add_f32_dpp v12, v12, v12 row_ror:2 row_mask:0xf bank_mask:0xf bound_ctrl:1
	v_pk_mul_f32 v[48:49], v[6:7], v[32:33]
	v_pk_mul_f32 v[50:51], v[8:9], v[34:35]
	v_add_f32_dpp v12, v12, v12 row_ror:4 row_mask:0xf bank_mask:0xf bound_ctrl:1
	v_pk_fma_f32 v[48:49], v[44:45], v[70:71], v[48:49] op_sel:[0,1,0]
	v_pk_fma_f32 v[50:51], v[46:47], v[70:71], v[50:51] op_sel:[0,1,0]
	v_add_f32_dpp v12, v12, v12 row_ror:8 row_mask:0xf bank_mask:0xf bound_ctrl:1
	v_pk_fma_f32 v[6:7], v[40:41], v[12:13], v[48:49] op_sel_hi:[1,0,1] neg_lo:[1,0,0] neg_hi:[1,0,0]
	v_pk_fma_f32 v[8:9], v[42:43], v[12:13], v[50:51] op_sel_hi:[1,0,1] neg_lo:[1,0,0] neg_hi:[1,0,0]
	ds_read_b128 v[20:23], v10 offset:64768
	ds_read_b128 v[16:19], v10 offset:64512
	ds_read_b128 v[28:31], v10 offset:65280
	ds_read_b128 v[24:27], v10 offset:65024
	s_waitcnt lgkmcnt(4)
	v_fma_mix_f32 v12, v6, v88, v180 op_sel_hi:[0,1,0]
	v_fma_mix_f32 v12, v7, v88, v12 op_sel:[0,1,0] op_sel_hi:[0,1,0]
	v_fma_mix_f32 v12, v8, v89, v12 op_sel_hi:[0,1,0]
	v_fma_mix_f32 v12, v9, v89, v12 op_sel:[0,1,0] op_sel_hi:[0,1,0]
	v_fma_mix_f32 v104, v6, v38, v180 op_sel_hi:[0,1,0]
	v_fma_mix_f32 v104, v7, v38, v104 op_sel:[0,1,0] op_sel_hi:[0,1,0]
	v_add_f32_dpp v12, v12, v12 row_ror:1 row_mask:0xf bank_mask:0xf bound_ctrl:1
	v_fma_mix_f32 v104, v8, v39, v104 op_sel_hi:[0,1,0]
	v_fma_mix_f32 v104, v9, v39, v104 op_sel:[0,1,0] op_sel_hi:[0,1,0]
	v_add_f32_dpp v12, v12, v12 row_ror:2 row_mask:0xf bank_mask:0xf bound_ctrl:1
	v_pk_mul_f32 v[48:49], v[6:7], v[84:85]
	v_pk_mul_f32 v[50:51], v[8:9], v[86:87]
	v_add_f32_dpp v12, v12, v12 row_ror:4 row_mask:0xf bank_mask:0xf bound_ctrl:1
	v_pk_fma_f32 v[48:49], v[96:97], v[72:73], v[48:49] op_sel_hi:[1,0,1]
	v_pk_fma_f32 v[50:51], v[98:99], v[72:73], v[50:51] op_sel_hi:[1,0,1]
	v_add_f32_dpp v12, v12, v12 row_ror:8 row_mask:0xf bank_mask:0xf bound_ctrl:1
	v_pk_fma_f32 v[6:7], v[92:93], v[12:13], v[48:49] op_sel_hi:[1,0,1] neg_lo:[1,0,0] neg_hi:[1,0,0]
	v_pk_fma_f32 v[8:9], v[94:95], v[12:13], v[50:51] op_sel_hi:[1,0,1] neg_lo:[1,0,0] neg_hi:[1,0,0]
	s_waitcnt lgkmcnt(0)
	v_fma_mix_f32 v12, v6, v20, v180 op_sel_hi:[0,1,0]
	v_fma_mix_f32 v12, v7, v20, v12 op_sel:[0,1,0] op_sel_hi:[0,1,0]
	v_fma_mix_f32 v12, v8, v21, v12 op_sel_hi:[0,1,0]
	v_fma_mix_f32 v12, v9, v21, v12 op_sel:[0,1,0] op_sel_hi:[0,1,0]
	v_fma_mix_f32 v105, v6, v90, v180 op_sel_hi:[0,1,0]
	v_fma_mix_f32 v105, v7, v90, v105 op_sel:[0,1,0] op_sel_hi:[0,1,0]
	v_add_f32_dpp v12, v12, v12 row_ror:1 row_mask:0xf bank_mask:0xf bound_ctrl:1
	v_fma_mix_f32 v105, v8, v91, v105 op_sel_hi:[0,1,0]
	v_fma_mix_f32 v105, v9, v91, v105 op_sel:[0,1,0] op_sel_hi:[0,1,0]
	v_add_f32_dpp v12, v12, v12 row_ror:2 row_mask:0xf bank_mask:0xf bound_ctrl:1
	v_pk_mul_f32 v[48:49], v[6:7], v[16:17]
	v_pk_mul_f32 v[50:51], v[8:9], v[18:19]
	v_add_f32_dpp v12, v12, v12 row_ror:4 row_mask:0xf bank_mask:0xf bound_ctrl:1
	v_pk_fma_f32 v[48:49], v[28:29], v[72:73], v[48:49] op_sel:[0,1,0]
	v_pk_fma_f32 v[50:51], v[30:31], v[72:73], v[50:51] op_sel:[0,1,0]
	v_add_f32_dpp v12, v12, v12 row_ror:8 row_mask:0xf bank_mask:0xf bound_ctrl:1
	v_pk_fma_f32 v[6:7], v[24:25], v[12:13], v[48:49] op_sel_hi:[1,0,1] neg_lo:[1,0,0] neg_hi:[1,0,0]
	v_pk_fma_f32 v[8:9], v[26:27], v[12:13], v[50:51] op_sel_hi:[1,0,1] neg_lo:[1,0,0] neg_hi:[1,0,0]
	v_fma_mix_f32 v61, v6, v22, v180 op_sel_hi:[0,1,0]
	v_fma_mix_f32 v61, v7, v22, v61 op_sel:[0,1,0] op_sel_hi:[0,1,0]
	v_fma_mix_f32 v61, v8, v23, v61 op_sel_hi:[0,1,0]
	v_fma_mix_f32 v61, v9, v23, v61 op_sel:[0,1,0] op_sel_hi:[0,1,0]
	v_add_f32_dpp v83, v83, v83 row_ror:8 row_mask:0xf bank_mask:0xc
	v_add_f32_dpp v83, v52, v52 row_ror:8 row_mask:0xf bank_mask:0x3
	v_add_f32_dpp v100, v100, v100 row_ror:8 row_mask:0xf bank_mask:0xc
	v_add_f32_dpp v100, v53, v53 row_ror:8 row_mask:0xf bank_mask:0x3
	v_add_f32_dpp v101, v101, v101 row_ror:8 row_mask:0xf bank_mask:0xc
	v_add_f32_dpp v101, v54, v54 row_ror:8 row_mask:0xf bank_mask:0x3
	v_add_f32_dpp v102, v102, v102 row_ror:8 row_mask:0xf bank_mask:0xc
	v_add_f32_dpp v102, v55, v55 row_ror:8 row_mask:0xf bank_mask:0x3
	v_add_f32_dpp v103, v103, v103 row_ror:8 row_mask:0xf bank_mask:0xc
	v_add_f32_dpp v103, v56, v56 row_ror:8 row_mask:0xf bank_mask:0x3
	v_add_f32_dpp v104, v104, v104 row_ror:8 row_mask:0xf bank_mask:0xc
	v_add_f32_dpp v104, v57, v57 row_ror:8 row_mask:0xf bank_mask:0x3
	v_add_f32_dpp v105, v105, v105 row_ror:8 row_mask:0xf bank_mask:0xc
	v_add_f32_dpp v105, v81, v81 row_ror:8 row_mask:0xf bank_mask:0x3
	v_add_f32_dpp v61, v61, v61 row_ror:8 row_mask:0xf bank_mask:0xc
	v_add_f32_dpp v61, v82, v82 row_ror:8 row_mask:0xf bank_mask:0x3
	v_add_f32_dpp v103, v103, v103 row_ror:4 row_mask:0xf bank_mask:0xa
	v_add_f32_dpp v103, v83, v83 row_ror:12 row_mask:0xf bank_mask:0x5
	v_add_f32_dpp v104, v104, v104 row_ror:4 row_mask:0xf bank_mask:0xa
	v_add_f32_dpp v104, v100, v100 row_ror:12 row_mask:0xf bank_mask:0x5
	v_add_f32_dpp v105, v105, v105 row_ror:4 row_mask:0xf bank_mask:0xa
	v_add_f32_dpp v105, v101, v101 row_ror:12 row_mask:0xf bank_mask:0x5
	v_add_f32_dpp v61, v61, v61 row_ror:4 row_mask:0xf bank_mask:0xa
	v_add_f32_dpp v61, v102, v102 row_ror:12 row_mask:0xf bank_mask:0x5
	v_cndmask_b32_e64 v62, v105, v103, s[38:39]
	v_cndmask_b32_e64 v63, v103, v105, s[38:39]
	v_cndmask_b32_e64 v64, v61, v104, s[38:39]
	v_cndmask_b32_e64 v65, v104, v61, s[38:39]
	v_add_f32_dpp v62, v63, v62 quad_perm:[2,3,0,1] row_mask:0xf bank_mask:0xf bound_ctrl:1
	s_nop 0
	v_add_f32_dpp v63, v65, v64 quad_perm:[2,3,0,1] row_mask:0xf bank_mask:0xf bound_ctrl:1
	v_cndmask_b32_e64 v65, v63, v62, s[40:41]
	v_cndmask_b32_e64 v62, v62, v63, s[40:41]
	s_nop 1
	v_add_f32_dpp v62, v62, v65 quad_perm:[1,0,3,2] row_mask:0xf bank_mask:0xf bound_ctrl:1
	v_cvt_pk_bf16_f32 v62, v62, v62
	global_store_short v[2:3], v62, off
	s_cmp_lg_u32 s28, 0x800000
	s_waitcnt lgkmcnt(0)
	s_barrier
	s_cbranch_scc1 .Lscan_cons_chunk
	s_branch .LBB0_53
.LBB0_59:
	v_lshrrev_b32_e32 v59, 2, v61
	v_lshlrev_b32_e32 v59, 8, v59
	v_lshl_or_b32 v59, v15, 4, v59
	v_and_b32_e32 v60, 3, v61
	v_lshl_or_b32 v59, v60, 2, v59
	v_add_u32_e32 v59, 0x20100, v59
	s_ashr_i32 s4, s34, 5
	s_ashr_i32 s5, s4, 31
	s_lshl_b64 s[4:5], s[4:5], 25
	v_readlane_b32 s6, v243, 21
	v_readlane_b32 s7, v243, 22
	s_add_u32 s28, s6, s4
	s_addc_u32 s29, s7, s5
	v_readlane_b32 s4, v241, 16
	v_readlane_b32 s5, v241, 17
	s_waitcnt vmcnt(0)
	v_lshlrev_b32_e32 v4, 1, v15
	v_readlane_b32 s4, v243, 7
	v_lshl_or_b32 v4, s64, 5, v4
	v_mov_b32_e32 v5, v180
	v_readlane_b32 s5, v243, 8
	v_readlane_b32 s8, v241, 20
	v_readlane_b32 s9, v241, 21
	v_lshl_add_u64 v[16:17], s[4:5], 0, v[4:5]
	v_cndmask_b32_e64 v4, v63, v61, s[42:43]
	v_ashrrev_i32_e32 v5, 31, v4
	v_lshl_add_u64 v[4:5], v[4:5], 0, s[80:81]
	v_lshlrev_b64 v[6:7], 9, v[4:5]
	v_or_b32_e32 v6, s37, v6
	v_or_b32_e32 v4, v6, v14
	v_mov_b32_e32 v5, v7
	v_lshlrev_b64 v[4:5], 1, v[4:5]
	v_readlane_b32 s8, v243, 17
	s_add_u32 s34, s28, 0x4000000
	v_lshl_add_u64 v[8:9], s[44:45], 0, v[4:5]
	v_lshl_add_u64 v[10:11], s[46:47], 0, v[4:5]
	v_readlane_b32 s9, v243, 18
	s_addc_u32 s35, s29, 0
	global_load_dwordx2 v[8:9], v[8:9], off
	v_or_b32_e32 v0, s37, v14
	global_load_dwordx2 v[54:55], v[10:11], off
	v_lshl_add_u64 v[10:11], s[8:9], 0, v[4:5]
	global_load_dwordx2 v[86:87], v[10:11], off
	v_lshl_add_u64 v[10:11], s[34:35], 0, v[4:5]
	global_load_dwordx2 v[56:57], v[10:11], off
	v_lshlrev_b32_e32 v0, 2, v0
	v_readlane_b32 s10, v241, 22
	v_readlane_b32 s11, v241, 23
	v_lshl_add_u64 v[10:11], v[6:7], 1, v[16:17]
	v_cndmask_b32_e64 v6, v65, v64, s[42:43]
	v_ashrrev_i32_e32 v7, 31, v6
	v_lshl_add_u64 v[6:7], v[6:7], 0, s[80:81]
	v_lshlrev_b64 v[6:7], 9, v[6:7]
	global_load_dwordx4 v[0:3], v0, s[10:11]
	v_or_b32_e32 v6, s37, v6
	v_or_b32_e32 v12, v6, v14
	v_mov_b32_e32 v13, v7
	v_lshl_add_u64 v[50:51], v[6:7], 1, v[16:17]
	v_cndmask_b32_e64 v6, v67, v66, s[42:43]
	v_lshlrev_b64 v[12:13], 1, v[12:13]
	v_ashrrev_i32_e32 v7, 31, v6
	v_lshl_add_u64 v[18:19], s[44:45], 0, v[12:13]
	v_lshl_add_u64 v[6:7], v[6:7], 0, s[80:81]
	global_load_dwordx2 v[34:35], v[18:19], off
	v_lshl_add_u64 v[18:19], s[46:47], 0, v[12:13]
	v_lshlrev_b64 v[6:7], 9, v[6:7]
	global_load_dwordx2 v[38:39], v[18:19], off
	v_lshl_add_u64 v[18:19], s[8:9], 0, v[12:13]
	v_or_b32_e32 v6, s37, v6
	global_load_dwordx2 v[40:41], v[18:19], off
	v_lshl_add_u64 v[18:19], s[34:35], 0, v[12:13]
	v_lshl_add_u64 v[52:53], s[28:29], 0, v[12:13]
	v_or_b32_e32 v12, v6, v14
	v_mov_b32_e32 v13, v7
	v_lshlrev_b64 v[12:13], 1, v[12:13]
	v_lshl_add_u64 v[44:45], v[6:7], 1, v[16:17]
	v_cndmask_b32_e64 v6, v69, v68, s[42:43]
	global_load_dwordx2 v[36:37], v[18:19], off
	v_lshl_add_u64 v[18:19], s[44:45], 0, v[12:13]
	v_ashrrev_i32_e32 v7, 31, v6
	global_load_dwordx2 v[26:27], v[18:19], off
	v_lshl_add_u64 v[18:19], s[46:47], 0, v[12:13]
	v_lshl_add_u64 v[6:7], v[6:7], 0, s[80:81]
	global_load_dwordx2 v[30:31], v[18:19], off
	v_lshl_add_u64 v[18:19], s[8:9], 0, v[12:13]
	v_lshlrev_b64 v[6:7], 9, v[6:7]
	v_lshl_add_u64 v[4:5], s[28:29], 0, v[4:5]
	global_load_dwordx2 v[32:33], v[18:19], off
	v_lshl_add_u64 v[18:19], s[34:35], 0, v[12:13]
	v_or_b32_e32 v6, s37, v6
	global_load_dwordx2 v[28:29], v[18:19], off
	v_or_b32_e32 v18, v6, v14
	v_mov_b32_e32 v19, v7
	v_lshl_add_u64 v[48:49], v[6:7], 1, v[16:17]
	global_load_dwordx2 v[6:7], v[4:5], off
	v_lshlrev_b64 v[42:43], 1, v[18:19]
	v_lshl_add_u64 v[18:19], s[44:45], 0, v[42:43]
	v_lshl_add_u64 v[20:21], s[46:47], 0, v[42:43]
	v_lshl_add_u64 v[22:23], s[8:9], 0, v[42:43]
	global_load_dwordx2 v[18:19], v[18:19], off
	v_lshl_add_u64 v[46:47], s[28:29], 0, v[42:43]
	global_load_dwordx2 v[20:21], v[20:21], off
	v_lshl_add_u64 v[12:13], s[28:29], 0, v[12:13]
	global_load_dwordx2 v[24:25], v[22:23], off
	v_lshl_add_u64 v[22:23], s[34:35], 0, v[42:43]
	global_load_dwordx2 v[22:23], v[22:23], off
	s_mov_b32 s10, 0x3d800000
	v_readlane_b32 s6, v241, 18
	s_mov_b32 s4, 0
	s_mov_b32 s5, 0x10000
	s_mov_b32 s6, 0
	v_readlane_b32 s7, v241, 19
	v_readlane_b32 s12, v241, 24
	v_readlane_b32 s13, v241, 25
	v_readlane_b32 s14, v241, 26
	v_readlane_b32 s15, v241, 27
	v_readlane_b32 s16, v241, 28
	v_readlane_b32 s17, v241, 29
	s_waitcnt vmcnt(0)
	v_lshlrev_b32_e32 v43, 16, v8
	v_and_b32_e32 v42, 0xffff0000, v8
	global_load_ushort v8, v[10:11], off
	v_readlane_b32 s18, v241, 30
	s_waitcnt vmcnt(16)
	v_lshlrev_b32_e32 v84, 16, v86
	v_and_b32_e32 v83, 0xffff0000, v86
	s_waitcnt vmcnt(15)
	v_cvt_f32_f16_e32 v88, v56
	v_cvt_f32_f16_sdwa v89, v56 dst_sel:DWORD dst_unused:UNUSED_PAD src0_sel:WORD_1
	v_lshlrev_b32_e32 v82, 16, v87
	v_and_b32_e32 v81, 0xffff0000, v87
	v_lshlrev_b32_e32 v86, 16, v54
	v_pk_add_f32 v[90:91], v[88:89], -1.0 op_sel_hi:[1,0]
	v_and_b32_e32 v87, 0xffff0000, v54
	v_cvt_pk_f16_f32 v10, v84, v83
	v_mul_f32_e32 v85, v88, v84
	s_waitcnt vmcnt(14)
	v_pk_fma_f32 v[90:91], v[0:1], v[90:91], 1.0 op_sel_hi:[1,1,0]
	v_mul_f32_e32 v83, v89, v83
	v_pk_mul_f32 v[86:87], v[90:91], v[86:87]
	v_cvt_f32_f16_e32 v90, v57
	v_cvt_f32_f16_sdwa v91, v57 dst_sel:DWORD dst_unused:UNUSED_PAD src0_sel:WORD_1
	v_lshlrev_b32_e32 v88, 16, v55
	v_and_b32_e32 v89, 0xffff0000, v55
	v_cvt_pk_f16_f32 v11, v82, v81
	v_pk_add_f32 v[94:95], v[90:91], -1.0 op_sel_hi:[1,0]
	v_mul_f32_e32 v93, v90, v82
	v_pk_fma_f32 v[94:95], v[2:3], v[94:95], 1.0 op_sel_hi:[1,1,0]
	v_mul_f32_e32 v81, v91, v81
	v_pk_mul_f32 v[88:89], v[94:95], v[88:89]
	global_load_dwordx2 v[52:53], v[52:53], off
	s_nop 0
	global_load_ushort v90, v[50:51], off
	s_nop 0
	global_load_dwordx2 v[50:51], v[12:13], off
	global_load_ushort v91, v[44:45], off
	s_nop 0
	global_load_dwordx2 v[44:45], v[46:47], off
	global_load_ushort v94, v[48:49], off
	v_cvt_pk_f16_f32 v54, v85, v83
	v_cvt_pk_f16_f32 v56, v86, v87
	v_cvt_pk_f16_f32 v55, v93, v81
	v_cvt_pk_f16_f32 v57, v88, v89
	v_and_b32_e32 v46, 0xffff0000, v9
	v_lshlrev_b32_e32 v47, 16, v9
	v_mov_b32_e32 v84, v87
	v_pk_mov_b32 v[48:49], v[46:47], v[42:43] op_sel:[1,0]
	v_mov_b32_e32 v82, v88
	v_mov_b32_e32 v92, v89
	v_readlane_b32 s19, v241, 31
	s_waitcnt vmcnt(11)
	v_cvt_f32_f16_e64 v4, -v6
	v_cvt_f32_f16_sdwa v5, -v6 dst_sel:DWORD dst_unused:UNUSED_PAD src0_sel:WORD_1
	v_cvt_f32_f16_e64 v6, -v7
	v_cvt_f32_f16_sdwa v7, -v7 dst_sel:DWORD dst_unused:UNUSED_PAD src0_sel:WORD_1
	v_exp_f32_e32 v4, v4
	v_exp_f32_e32 v5, v5
	v_exp_f32_e32 v6, v6
	v_exp_f32_e32 v7, v7
	ds_write_b128 v70, v[4:7]
	ds_write_b32 v70, v85 offset:512
	ds_write_b32 v70, v83 offset:516
	ds_write_b32 v70, v93 offset:520
	ds_write_b32 v70, v81 offset:524
	ds_write_b64 v70, v[86:87] offset:768
	ds_write_b64 v70, v[88:89] offset:776
	v_mul_f32_e32 v4, v4, v43
	v_mul_f32_e32 v5, v5, v42
	v_cvt_pk_f16_f32 v12, v43, v42
	v_fma_f32 v4, v86, v43, 0
	v_mov_b32_e32 v5, v180
	v_pk_fma_f32 v[4:5], v[84:85], v[42:43], v[4:5]
	v_mul_f32_e32 v6, v6, v47
	v_mul_f32_e32 v7, v7, v46
	v_pk_fma_f32 v[4:5], v[82:83], v[48:49], v[4:5]
	v_cvt_pk_f16_f32 v13, v47, v46
	v_pk_fma_f32 v[4:5], v[92:93], v[46:47], v[4:5]
	v_mov_b32_e32 v6, v180
	v_mul_f32_e32 v7, v81, v46
	ds_write_b128 v70, v[10:13] offset:256
	v_mov_b32_dpp v6, v4 row_ror:1 row_mask:0xf bank_mask:0xf
	v_pk_add_f32 v[4:5], v[4:5], v[6:7]
	v_mov_b32_e32 v7, v180
	v_mov_b32_e32 v6, v180
	s_waitcnt vmcnt(0)
	v_lshlrev_b32_e32 v8, 16, v8
	v_mov_b32_dpp v7, v5 row_ror:1 row_mask:0xf bank_mask:0xf
	v_mov_b32_dpp v6, v4 row_ror:2 row_mask:0xf bank_mask:0xf
	v_pk_add_f32 v[4:5], v[4:5], v[6:7]
	v_mov_b32_e32 v7, v180
	v_mov_b32_e32 v6, v180
	v_lshlrev_b32_e32 v43, 16, v34
	v_mov_b32_dpp v7, v5 row_ror:2 row_mask:0xf bank_mask:0xf
	v_mov_b32_dpp v6, v4 row_ror:4 row_mask:0xf bank_mask:0xf
	v_pk_add_f32 v[4:5], v[4:5], v[6:7]
	v_mov_b32_e32 v7, v180
	v_mov_b32_e32 v6, v180
	v_and_b32_e32 v42, 0xffff0000, v34
	v_mov_b32_dpp v7, v5 row_ror:4 row_mask:0xf bank_mask:0xf
	v_mov_b32_dpp v6, v4 row_ror:8 row_mask:0xf bank_mask:0xf
	v_pk_add_f32 v[4:5], v[4:5], v[6:7]
	v_mov_b32_e32 v7, v180
	v_pk_mul_f32 v[10:11], v[4:5], v[8:9]
	v_and_b32_e32 v34, 0xffff0000, v40
	v_mov_b32_dpp v7, v5 row_ror:8 row_mask:0xf bank_mask:0xf
	v_pk_add_f32 v[4:5], v[4:5], v[6:7]
	v_lshlrev_b32_e32 v46, 16, v41
	v_mov_b32_e32 v11, v5
	v_pk_mul_f32 v[4:5], v[10:11], s[10:11] op_sel_hi:[1,0]
	v_mov_b32_e32 v11, v180
	v_mov_b32_e32 v9, v4
	v_mov_b32_e32 v10, v5
	ds_write_b32 v59, v8 offset:0
	v_lshlrev_b32_e32 v9, 16, v40
	v_and_b32_e32 v54, 0xffff0000, v41
	s_waitcnt vmcnt(5)
	v_cvt_f32_f16_e64 v4, -v52
	v_cvt_f32_f16_sdwa v5, -v52 dst_sel:DWORD dst_unused:UNUSED_PAD src0_sel:WORD_1
	v_cvt_f32_f16_e64 v6, -v53
	v_cvt_f32_f16_sdwa v7, -v53 dst_sel:DWORD dst_unused:UNUSED_PAD src0_sel:WORD_1
	v_cvt_f32_f16_e32 v40, v36
	v_cvt_f32_f16_sdwa v41, v36 dst_sel:DWORD dst_unused:UNUSED_PAD src0_sel:WORD_1
	v_cvt_f32_f16_e32 v52, v37
	v_cvt_f32_f16_sdwa v53, v37 dst_sel:DWORD dst_unused:UNUSED_PAD src0_sel:WORD_1
	v_exp_f32_e32 v4, v4
	v_exp_f32_e32 v5, v5
	v_exp_f32_e32 v6, v6
	v_exp_f32_e32 v7, v7
	v_pk_add_f32 v[48:49], v[40:41], -1.0 op_sel_hi:[1,0]
	v_lshlrev_b32_e32 v12, 16, v38
	v_and_b32_e32 v13, 0xffff0000, v38
	v_pk_fma_f32 v[48:49], v[0:1], v[48:49], 1.0 op_sel_hi:[1,1,0]
	v_pk_add_f32 v[56:57], v[52:53], -1.0 op_sel_hi:[1,0]
	v_pk_mul_f32 v[48:49], v[48:49], v[12:13]
	v_lshlrev_b32_e32 v12, 16, v39
	v_and_b32_e32 v13, 0xffff0000, v39
	v_pk_fma_f32 v[56:57], v[2:3], v[56:57], 1.0 op_sel_hi:[1,1,0]
	v_cvt_pk_f16_f32 v10, v9, v34
	v_mul_f32_e32 v47, v40, v9
	v_mul_f32_e32 v41, v41, v34
	v_mul_f32_e32 v55, v52, v46
	v_pk_mul_f32 v[56:57], v[56:57], v[12:13]
	v_mul_f32_e32 v9, v53, v54
	v_cvt_pk_f16_f32 v36, v47, v41
	v_cvt_pk_f16_f32 v38, v48, v49
	v_cvt_pk_f16_f32 v37, v55, v9
	v_cvt_pk_f16_f32 v39, v56, v57
	ds_write_b128 v70, v[4:7] offset:16384
	ds_write_b32 v70, v47 offset:16896
	ds_write_b32 v70, v41 offset:16900
	ds_write_b32 v70, v55 offset:16904
	ds_write_b32 v70, v9 offset:16908
	ds_write_b64 v70, v[48:49] offset:17152
	ds_write_b64 v70, v[56:57] offset:17160
	v_mul_f32_e32 v4, v4, v43
	v_mul_f32_e32 v5, v5, v42
	v_cvt_pk_f16_f32 v11, v46, v54
	v_and_b32_e32 v34, 0xffff0000, v35
	v_lshlrev_b32_e32 v35, 16, v35
	v_cvt_pk_f16_f32 v12, v43, v42
	v_fma_f32 v4, v48, v43, 0
	v_mov_b32_e32 v46, v49
	v_mov_b32_e32 v5, v180
	v_pk_mov_b32 v[36:37], v[34:35], v[42:43] op_sel:[1,0]
	v_pk_fma_f32 v[4:5], v[46:47], v[42:43], v[4:5]
	v_mov_b32_e32 v40, v56
	v_mul_f32_e32 v6, v6, v35
	v_mul_f32_e32 v7, v7, v34
	v_pk_fma_f32 v[4:5], v[40:41], v[36:37], v[4:5]
	v_mov_b32_e32 v54, v57
	v_cvt_pk_f16_f32 v13, v35, v34
	v_pk_fma_f32 v[4:5], v[54:55], v[34:35], v[4:5]
	v_mov_b32_e32 v6, v180
	v_mul_f32_e32 v7, v9, v34
	s_waitcnt vmcnt(4)
	v_lshlrev_b32_e32 v8, 16, v90
	v_mov_b32_dpp v6, v4 row_ror:1 row_mask:0xf bank_mask:0xf
	v_pk_add_f32 v[4:5], v[4:5], v[6:7]
	v_mov_b32_e32 v7, v180
	v_mov_b32_e32 v6, v180
	ds_write_b128 v70, v[10:13] offset:16640
	v_mov_b32_dpp v7, v5 row_ror:1 row_mask:0xf bank_mask:0xf
	v_mov_b32_dpp v6, v4 row_ror:2 row_mask:0xf bank_mask:0xf
	v_pk_add_f32 v[4:5], v[4:5], v[6:7]
	v_mov_b32_e32 v7, v180
	v_mov_b32_e32 v6, v180
	v_lshlrev_b32_e32 v35, 16, v26
	v_mov_b32_dpp v7, v5 row_ror:2 row_mask:0xf bank_mask:0xf
	v_mov_b32_dpp v6, v4 row_ror:4 row_mask:0xf bank_mask:0xf
	v_pk_add_f32 v[4:5], v[4:5], v[6:7]
	v_mov_b32_e32 v7, v180
	v_mov_b32_e32 v6, v180
	v_and_b32_e32 v34, 0xffff0000, v26
	v_mov_b32_dpp v7, v5 row_ror:4 row_mask:0xf bank_mask:0xf
	v_mov_b32_dpp v6, v4 row_ror:8 row_mask:0xf bank_mask:0xf
	v_pk_add_f32 v[4:5], v[4:5], v[6:7]
	v_mov_b32_e32 v7, v180
	v_pk_mul_f32 v[10:11], v[4:5], v[8:9]
	v_and_b32_e32 v26, 0xffff0000, v32
	v_mov_b32_dpp v7, v5 row_ror:8 row_mask:0xf bank_mask:0xf
	v_pk_add_f32 v[4:5], v[4:5], v[6:7]
	v_lshlrev_b32_e32 v36, 16, v33
	v_mov_b32_e32 v11, v5
	v_pk_mul_f32 v[4:5], v[10:11], s[10:11] op_sel_hi:[1,0]
	v_mov_b32_e32 v11, v180
	v_mov_b32_e32 v9, v4
	v_mov_b32_e32 v10, v5
	ds_write_b32 v59, v8 offset:1024
	v_lshlrev_b32_e32 v9, 16, v32
	v_and_b32_e32 v42, 0xffff0000, v33
	s_waitcnt vmcnt(3)
	v_cvt_f32_f16_e64 v4, -v50
	v_cvt_f32_f16_sdwa v5, -v50 dst_sel:DWORD dst_unused:UNUSED_PAD src0_sel:WORD_1
	v_cvt_f32_f16_e64 v6, -v51
	v_cvt_f32_f16_sdwa v7, -v51 dst_sel:DWORD dst_unused:UNUSED_PAD src0_sel:WORD_1
	v_cvt_f32_f16_e32 v32, v28
	v_cvt_f32_f16_sdwa v33, v28 dst_sel:DWORD dst_unused:UNUSED_PAD src0_sel:WORD_1
	v_cvt_f32_f16_e32 v40, v29
	v_cvt_f32_f16_sdwa v41, v29 dst_sel:DWORD dst_unused:UNUSED_PAD src0_sel:WORD_1
	v_exp_f32_e32 v4, v4
	v_exp_f32_e32 v5, v5
	v_exp_f32_e32 v6, v6
	v_exp_f32_e32 v7, v7
	v_pk_add_f32 v[38:39], v[32:33], -1.0 op_sel_hi:[1,0]
	v_lshlrev_b32_e32 v12, 16, v30
	v_and_b32_e32 v13, 0xffff0000, v30
	v_pk_fma_f32 v[38:39], v[0:1], v[38:39], 1.0 op_sel_hi:[1,1,0]
	v_pk_add_f32 v[46:47], v[40:41], -1.0 op_sel_hi:[1,0]
	v_pk_mul_f32 v[38:39], v[38:39], v[12:13]
	v_lshlrev_b32_e32 v12, 16, v31
	v_and_b32_e32 v13, 0xffff0000, v31
	v_pk_fma_f32 v[46:47], v[2:3], v[46:47], 1.0 op_sel_hi:[1,1,0]
	v_cvt_pk_f16_f32 v10, v9, v26
	v_mul_f32_e32 v37, v32, v9
	v_mul_f32_e32 v33, v33, v26
	v_mul_f32_e32 v43, v40, v36
	v_pk_mul_f32 v[46:47], v[46:47], v[12:13]
	v_mul_f32_e32 v9, v41, v42
	v_cvt_pk_f16_f32 v28, v37, v33
	v_cvt_pk_f16_f32 v30, v38, v39
	v_cvt_pk_f16_f32 v29, v43, v9
	v_cvt_pk_f16_f32 v31, v46, v47
	ds_write_b128 v70, v[4:7] offset:32768
	ds_write_b32 v70, v37 offset:33280
	ds_write_b32 v70, v33 offset:33284
	ds_write_b32 v70, v43 offset:33288
	ds_write_b32 v70, v9 offset:33292
	ds_write_b64 v70, v[38:39] offset:33536
	ds_write_b64 v70, v[46:47] offset:33544
	v_mul_f32_e32 v4, v4, v35
	v_mul_f32_e32 v5, v5, v34
	v_cvt_pk_f16_f32 v11, v36, v42
	v_and_b32_e32 v26, 0xffff0000, v27
	v_lshlrev_b32_e32 v27, 16, v27
	v_cvt_pk_f16_f32 v12, v35, v34
	v_fma_f32 v4, v38, v35, 0
	v_mov_b32_e32 v36, v39
	v_mov_b32_e32 v5, v180
	v_pk_mov_b32 v[28:29], v[26:27], v[34:35] op_sel:[1,0]
	v_pk_fma_f32 v[4:5], v[36:37], v[34:35], v[4:5]
	v_mov_b32_e32 v32, v46
	v_mul_f32_e32 v6, v6, v27
	v_mul_f32_e32 v7, v7, v26
	v_pk_fma_f32 v[4:5], v[32:33], v[28:29], v[4:5]
	v_mov_b32_e32 v42, v47
	v_cvt_pk_f16_f32 v13, v27, v26
	v_pk_fma_f32 v[4:5], v[42:43], v[26:27], v[4:5]
	v_mov_b32_e32 v6, v180
	v_mul_f32_e32 v7, v9, v26
	s_waitcnt vmcnt(2)
	v_lshlrev_b32_e32 v8, 16, v91
	v_mov_b32_dpp v6, v4 row_ror:1 row_mask:0xf bank_mask:0xf
	v_pk_add_f32 v[4:5], v[4:5], v[6:7]
	v_mov_b32_e32 v7, v180
	v_mov_b32_e32 v6, v180
	ds_write_b128 v70, v[10:13] offset:33024
	v_mov_b32_dpp v7, v5 row_ror:1 row_mask:0xf bank_mask:0xf
	v_mov_b32_dpp v6, v4 row_ror:2 row_mask:0xf bank_mask:0xf
	v_pk_add_f32 v[4:5], v[4:5], v[6:7]
	v_mov_b32_e32 v7, v180
	v_mov_b32_e32 v6, v180
	v_lshlrev_b32_e32 v27, 16, v18
	v_mov_b32_dpp v7, v5 row_ror:2 row_mask:0xf bank_mask:0xf
	v_mov_b32_dpp v6, v4 row_ror:4 row_mask:0xf bank_mask:0xf
	v_pk_add_f32 v[4:5], v[4:5], v[6:7]
	v_mov_b32_e32 v7, v180
	v_mov_b32_e32 v6, v180
	v_and_b32_e32 v26, 0xffff0000, v18
	v_mov_b32_dpp v7, v5 row_ror:4 row_mask:0xf bank_mask:0xf
	v_mov_b32_dpp v6, v4 row_ror:8 row_mask:0xf bank_mask:0xf
	v_pk_add_f32 v[4:5], v[4:5], v[6:7]
	v_mov_b32_e32 v7, v180
	v_pk_mul_f32 v[10:11], v[4:5], v[8:9]
	v_and_b32_e32 v18, 0xffff0000, v24
	v_mov_b32_dpp v7, v5 row_ror:8 row_mask:0xf bank_mask:0xf
	v_pk_add_f32 v[4:5], v[4:5], v[6:7]
	v_lshlrev_b32_e32 v28, 16, v25
	v_mov_b32_e32 v11, v5
	v_pk_mul_f32 v[4:5], v[10:11], s[10:11] op_sel_hi:[1,0]
	v_mov_b32_e32 v11, v180
	v_mov_b32_e32 v9, v4
	v_mov_b32_e32 v10, v5
	ds_write_b32 v59, v8 offset:2048
	v_lshlrev_b32_e32 v9, 16, v24
	v_and_b32_e32 v34, 0xffff0000, v25
	s_waitcnt vmcnt(1)
	v_cvt_f32_f16_e64 v4, -v44
	v_cvt_f32_f16_sdwa v5, -v44 dst_sel:DWORD dst_unused:UNUSED_PAD src0_sel:WORD_1
	v_cvt_f32_f16_e64 v6, -v45
	v_cvt_f32_f16_sdwa v7, -v45 dst_sel:DWORD dst_unused:UNUSED_PAD src0_sel:WORD_1
	v_cvt_f32_f16_e32 v24, v22
	v_cvt_f32_f16_sdwa v25, v22 dst_sel:DWORD dst_unused:UNUSED_PAD src0_sel:WORD_1
	v_cvt_f32_f16_e32 v32, v23
	v_cvt_f32_f16_sdwa v33, v23 dst_sel:DWORD dst_unused:UNUSED_PAD src0_sel:WORD_1
	v_exp_f32_e32 v4, v4
	v_exp_f32_e32 v5, v5
	v_exp_f32_e32 v6, v6
	v_exp_f32_e32 v7, v7
	v_pk_add_f32 v[30:31], v[24:25], -1.0 op_sel_hi:[1,0]
	v_lshlrev_b32_e32 v12, 16, v20
	v_and_b32_e32 v13, 0xffff0000, v20
	v_pk_fma_f32 v[30:31], v[0:1], v[30:31], 1.0 op_sel_hi:[1,1,0]
	v_pk_add_f32 v[36:37], v[32:33], -1.0 op_sel_hi:[1,0]
	v_pk_mul_f32 v[30:31], v[30:31], v[12:13]
	v_lshlrev_b32_e32 v12, 16, v21
	v_and_b32_e32 v13, 0xffff0000, v21
	v_pk_fma_f32 v[36:37], v[2:3], v[36:37], 1.0 op_sel_hi:[1,1,0]
	v_cvt_pk_f16_f32 v10, v9, v18
	v_mul_f32_e32 v29, v24, v9
	v_mul_f32_e32 v25, v25, v18
	v_mul_f32_e32 v35, v32, v28
	v_pk_mul_f32 v[36:37], v[36:37], v[12:13]
	v_mul_f32_e32 v9, v33, v34
	v_cvt_pk_f16_f32 v20, v29, v25
	v_cvt_pk_f16_f32 v22, v30, v31
	v_cvt_pk_f16_f32 v21, v35, v9
	v_cvt_pk_f16_f32 v23, v36, v37
	ds_write_b128 v70, v[4:7] offset:49152
	ds_write_b32 v70, v29 offset:49664
	ds_write_b32 v70, v25 offset:49668
	ds_write_b32 v70, v35 offset:49672
	ds_write_b32 v70, v9 offset:49676
	ds_write_b64 v70, v[30:31] offset:49920
	ds_write_b64 v70, v[36:37] offset:49928
	v_mul_f32_e32 v4, v4, v27
	v_mul_f32_e32 v5, v5, v26
	v_cvt_pk_f16_f32 v11, v28, v34
	v_and_b32_e32 v18, 0xffff0000, v19
	v_lshlrev_b32_e32 v19, 16, v19
	v_cvt_pk_f16_f32 v12, v27, v26
	v_fma_f32 v4, v30, v27, 0
	v_mov_b32_e32 v28, v31
	v_mov_b32_e32 v5, v180
	v_pk_mov_b32 v[20:21], v[18:19], v[26:27] op_sel:[1,0]
	v_pk_fma_f32 v[4:5], v[28:29], v[26:27], v[4:5]
	v_mov_b32_e32 v24, v36
	v_mul_f32_e32 v6, v6, v19
	v_mul_f32_e32 v7, v7, v18
	v_pk_fma_f32 v[4:5], v[24:25], v[20:21], v[4:5]
	v_mov_b32_e32 v34, v37
	v_cvt_pk_f16_f32 v13, v19, v18
	v_pk_fma_f32 v[4:5], v[34:35], v[18:19], v[4:5]
	v_mov_b32_e32 v6, v180
	v_mul_f32_e32 v7, v9, v18
	s_waitcnt vmcnt(0)
	v_lshlrev_b32_e32 v8, 16, v94
	v_mov_b32_dpp v6, v4 row_ror:1 row_mask:0xf bank_mask:0xf
	v_pk_add_f32 v[4:5], v[4:5], v[6:7]
	v_mov_b32_e32 v7, v180
	v_mov_b32_e32 v6, v180
	ds_write_b128 v70, v[10:13] offset:49408
	v_mov_b32_dpp v7, v5 row_ror:1 row_mask:0xf bank_mask:0xf
	v_mov_b32_dpp v6, v4 row_ror:2 row_mask:0xf bank_mask:0xf
	v_pk_add_f32 v[4:5], v[4:5], v[6:7]
	v_mov_b32_e32 v7, v180
	v_mov_b32_e32 v6, v180
	s_nop 0
	v_mov_b32_dpp v7, v5 row_ror:2 row_mask:0xf bank_mask:0xf
	v_mov_b32_dpp v6, v4 row_ror:4 row_mask:0xf bank_mask:0xf
	v_pk_add_f32 v[4:5], v[4:5], v[6:7]
	v_mov_b32_e32 v7, v180
	v_mov_b32_e32 v6, v180
	s_nop 0
	v_mov_b32_dpp v7, v5 row_ror:4 row_mask:0xf bank_mask:0xf
	v_mov_b32_dpp v6, v4 row_ror:8 row_mask:0xf bank_mask:0xf
	v_pk_add_f32 v[4:5], v[4:5], v[6:7]
	v_mov_b32_e32 v7, v180
	v_pk_mul_f32 v[10:11], v[4:5], v[8:9]
	s_nop 0
	v_mov_b32_dpp v7, v5 row_ror:8 row_mask:0xf bank_mask:0xf
	v_pk_add_f32 v[4:5], v[4:5], v[6:7]
	s_nop 0
	v_mov_b32_e32 v11, v5
	v_pk_mul_f32 v[4:5], v[10:11], s[10:11] op_sel_hi:[1,0]
	v_mov_b32_e32 v11, v180
	v_mov_b32_e32 v9, v4
	v_cndmask_b32_e64 v4, v71, v62, s[42:43]
	v_mov_b32_e32 v10, v5
	v_ashrrev_i32_e32 v5, 31, v4
	v_lshl_add_u64 v[4:5], v[4:5], 0, s[80:81]
	v_lshlrev_b64 v[18:19], 9, v[4:5]
	v_or_b32_e32 v18, s37, v18
	v_or_b32_e32 v4, v18, v14
	v_mov_b32_e32 v5, v19
	v_lshlrev_b64 v[12:13], 1, v[4:5]
	ds_write_b32 v59, v8 offset:3072
	v_lshl_add_u64 v[4:5], s[44:45], 0, v[12:13]
	v_lshl_add_u64 v[6:7], s[46:47], 0, v[12:13]
	v_lshl_add_u64 v[8:9], s[8:9], 0, v[12:13]
	v_lshl_add_u64 v[10:11], s[34:35], 0, v[12:13]
	v_lshl_add_u64 v[12:13], s[28:29], 0, v[12:13]
	v_lshl_add_u64 v[18:19], v[18:19], 1, v[16:17]
	global_load_dwordx2 v[12:13], v[12:13], off
	s_nop 0
	global_load_ushort v48, v[18:19], off
	v_cndmask_b32_e64 v18, v73, v72, s[42:43]
	v_ashrrev_i32_e32 v19, 31, v18
	v_lshl_add_u64 v[18:19], v[18:19], 0, s[80:81]
	v_lshlrev_b64 v[28:29], 9, v[18:19]
	v_or_b32_e32 v28, s37, v28
	v_or_b32_e32 v18, v28, v14
	v_mov_b32_e32 v19, v29
	v_lshlrev_b64 v[26:27], 1, v[18:19]
	v_lshl_add_u64 v[18:19], s[44:45], 0, v[26:27]
	v_lshl_add_u64 v[20:21], s[46:47], 0, v[26:27]
	v_lshl_add_u64 v[22:23], s[8:9], 0, v[26:27]
	v_lshl_add_u64 v[24:25], s[34:35], 0, v[26:27]
	v_lshl_add_u64 v[26:27], s[28:29], 0, v[26:27]
	v_lshl_add_u64 v[28:29], v[28:29], 1, v[16:17]
	global_load_dwordx2 v[26:27], v[26:27], off
	s_nop 0
	global_load_ushort v49, v[28:29], off
	v_cndmask_b32_e64 v28, v75, v74, s[42:43]
	v_ashrrev_i32_e32 v29, 31, v28
	v_lshl_add_u64 v[28:29], v[28:29], 0, s[80:81]
	v_lshlrev_b64 v[38:39], 9, v[28:29]
	v_or_b32_e32 v38, s37, v38
	v_or_b32_e32 v28, v38, v14
	v_mov_b32_e32 v29, v39
	v_lshlrev_b64 v[36:37], 1, v[28:29]
	v_lshl_add_u64 v[28:29], s[44:45], 0, v[36:37]
	v_lshl_add_u64 v[30:31], s[46:47], 0, v[36:37]
	v_lshl_add_u64 v[32:33], s[8:9], 0, v[36:37]
	v_lshl_add_u64 v[34:35], s[34:35], 0, v[36:37]
	v_lshl_add_u64 v[36:37], s[28:29], 0, v[36:37]
	v_lshl_add_u64 v[38:39], v[38:39], 1, v[16:17]
	global_load_dwordx2 v[36:37], v[36:37], off
	s_nop 0
	global_load_ushort v50, v[38:39], off
	v_cndmask_b32_e64 v38, v77, v76, s[42:43]
	v_ashrrev_i32_e32 v39, 31, v38
	v_lshl_add_u64 v[38:39], v[38:39], 0, s[80:81]
	v_lshlrev_b64 v[52:53], 9, v[38:39]
	v_or_b32_e32 v52, s37, v52
	v_or_b32_e32 v38, v52, v14
	v_mov_b32_e32 v39, v53
	v_lshlrev_b64 v[46:47], 1, v[38:39]
	v_lshl_add_u64 v[38:39], s[44:45], 0, v[46:47]
	v_lshl_add_u64 v[40:41], s[46:47], 0, v[46:47]
	v_lshl_add_u64 v[42:43], s[8:9], 0, v[46:47]
	v_lshl_add_u64 v[44:45], s[34:35], 0, v[46:47]
	v_lshl_add_u64 v[46:47], s[28:29], 0, v[46:47]
	v_lshl_add_u64 v[52:53], v[52:53], 1, v[16:17]
	global_load_dwordx2 v[4:5], v[4:5], off
	s_nop 0
	global_load_dwordx2 v[6:7], v[6:7], off
	s_nop 0
	global_load_dwordx2 v[8:9], v[8:9], off
	s_nop 0
	global_load_dwordx2 v[10:11], v[10:11], off
	s_nop 0
	global_load_dwordx2 v[18:19], v[18:19], off
	s_nop 0
	global_load_dwordx2 v[20:21], v[20:21], off
	s_nop 0
	global_load_dwordx2 v[22:23], v[22:23], off
	s_nop 0
	global_load_dwordx2 v[24:25], v[24:25], off
	s_nop 0
	global_load_dwordx2 v[28:29], v[28:29], off
	s_nop 0
	global_load_dwordx2 v[30:31], v[30:31], off
	s_nop 0
	global_load_dwordx2 v[32:33], v[32:33], off
	s_nop 0
	global_load_dwordx2 v[34:35], v[34:35], off
	s_nop 0
	global_load_dwordx2 v[38:39], v[38:39], off
	s_nop 0
	global_load_dwordx2 v[40:41], v[40:41], off
	s_nop 0
	global_load_dwordx2 v[42:43], v[42:43], off
	s_nop 0
	global_load_dwordx2 v[44:45], v[44:45], off
	s_nop 0
	global_load_dwordx2 v[46:47], v[46:47], off
	s_nop 0
	global_load_ushort v51, v[52:53], off
	s_waitcnt lgkmcnt(0)
	s_barrier
	v_mov_b32_e32 v52, v80
	s_branch .LBB0_61

.LBB0_61:
	s_cmpk_eq_i32 s4, 0xe040
	s_cbranch_scc1 .LBB0_63
	s_waitcnt vmcnt(0)
	v_cvt_f32_f16_e64 v54, -v12
	v_cvt_f32_f16_sdwa v55, -v12 dst_sel:DWORD dst_unused:UNUSED_PAD src0_sel:WORD_1
	v_cvt_f32_f16_e64 v56, -v13
	v_cvt_f32_f16_sdwa v57, -v13 dst_sel:DWORD dst_unused:UNUSED_PAD src0_sel:WORD_1
	s_waitcnt vmcnt(14)
	v_cvt_f32_f16_e32 v86, v10
	v_cvt_f32_f16_sdwa v87, v10 dst_sel:DWORD dst_unused:UNUSED_PAD src0_sel:WORD_1
	v_cvt_f32_f16_e32 v98, v11
	v_cvt_f32_f16_sdwa v99, v11 dst_sel:DWORD dst_unused:UNUSED_PAD src0_sel:WORD_1
	v_exp_f32_e32 v54, v54
	v_exp_f32_e32 v55, v55
	v_exp_f32_e32 v56, v56
	v_exp_f32_e32 v57, v57
	v_pk_add_f32 v[94:95], v[86:87], -1.0 op_sel_hi:[1,0]
	v_pk_add_f32 v[104:105], v[98:99], -1.0 op_sel_hi:[1,0]
	s_and_b32 s7, s5, 0x10000
	s_lshr_b32 s100, s7, 4
	v_add_u32_e32 v60, s100, v59
	v_lshlrev_b32_e32 v53, 16, v8
	v_and_b32_e32 v81, 0xffff0000, v8
	v_lshlrev_b32_e32 v83, 16, v9
	v_and_b32_e32 v92, 0xffff0000, v9
	v_lshlrev_b32_e32 v88, 16, v6
	v_and_b32_e32 v89, 0xffff0000, v6
	v_pk_fma_f32 v[94:95], v[0:1], v[94:95], 1.0 op_sel_hi:[1,1,0]
	v_lshlrev_b32_e32 v100, 16, v7
	v_and_b32_e32 v101, 0xffff0000, v7
	v_pk_fma_f32 v[104:105], v[2:3], v[104:105], 1.0 op_sel_hi:[1,1,0]
	v_lshlrev_b32_e32 v91, 16, v4
	v_and_b32_e32 v90, 0xffff0000, v4
	v_cvt_pk_f16_f32 v84, v53, v81
	v_mul_f32_e32 v93, v86, v53
	v_pk_mul_f32 v[94:95], v[94:95], v[88:89]
	v_mul_f32_e32 v97, v87, v81
	v_mul_f32_e32 v103, v98, v83
	v_pk_mul_f32 v[100:101], v[104:105], v[100:101]
	v_mul_f32_e32 v81, v99, v92
	v_add_u32_e32 v53, s7, v70
	v_cvt_pk_f16_f32 v86, v93, v97
	v_cvt_pk_f16_f32 v88, v94, v95
	v_cvt_pk_f16_f32 v87, v103, v81
	v_cvt_pk_f16_f32 v89, v100, v101
	ds_write_b128 v53, v[54:57]
	ds_write_b32 v53, v93 offset:512
	ds_write_b32 v53, v97 offset:516
	ds_write_b32 v53, v103 offset:520
	ds_write_b32 v53, v81 offset:524
	ds_write_b64 v53, v[94:95] offset:768
	ds_write_b64 v53, v[100:101] offset:776
	v_mul_f32_e32 v54, v54, v91
	v_mul_f32_e32 v55, v55, v90
	v_cvt_pk_f16_f32 v85, v83, v92
	v_and_b32_e32 v88, 0xffff0000, v5
	v_lshlrev_b32_e32 v89, 16, v5
	v_cvt_pk_f16_f32 v86, v91, v90
	v_fma_f32 v54, v94, v91, 0
	v_mov_b32_e32 v92, v95
	v_mov_b32_e32 v55, v180
	v_pk_mov_b32 v[98:99], v[88:89], v[90:91] op_sel:[1,0]
	v_pk_fma_f32 v[54:55], v[92:93], v[90:91], v[54:55]
	v_mov_b32_e32 v96, v100
	v_mul_f32_e32 v56, v56, v89
	v_mul_f32_e32 v57, v57, v88
	v_pk_fma_f32 v[54:55], v[96:97], v[98:99], v[54:55]
	v_mov_b32_e32 v102, v101
	v_cvt_pk_f16_f32 v87, v89, v88
	v_pk_fma_f32 v[54:55], v[102:103], v[88:89], v[54:55]
	v_mov_b32_e32 v56, v180
	v_mul_f32_e32 v57, v81, v88
	v_lshlrev_b32_e32 v82, 16, v48
	v_mov_b32_dpp v56, v54 row_ror:1 row_mask:0xf bank_mask:0xf
	v_pk_add_f32 v[54:55], v[54:55], v[56:57]
	v_mov_b32_e32 v57, v180
	v_mov_b32_e32 v56, v180
	ds_write_b128 v53, v[84:87] offset:256
	v_mov_b32_dpp v57, v55 row_ror:1 row_mask:0xf bank_mask:0xf
	v_mov_b32_dpp v56, v54 row_ror:2 row_mask:0xf bank_mask:0xf
	v_pk_add_f32 v[54:55], v[54:55], v[56:57]
	v_mov_b32_e32 v57, v180
	v_mov_b32_e32 v56, v180
	s_waitcnt vmcnt(10)
	v_cvt_f32_f16_e32 v86, v24
	v_mov_b32_dpp v57, v55 row_ror:2 row_mask:0xf bank_mask:0xf
	v_mov_b32_dpp v56, v54 row_ror:4 row_mask:0xf bank_mask:0xf
	v_pk_add_f32 v[54:55], v[54:55], v[56:57]
	v_mov_b32_e32 v57, v180
	v_mov_b32_e32 v56, v180
	v_cvt_f32_f16_sdwa v87, v24 dst_sel:DWORD dst_unused:UNUSED_PAD src0_sel:WORD_1
	v_mov_b32_dpp v57, v55 row_ror:4 row_mask:0xf bank_mask:0xf
	v_mov_b32_dpp v56, v54 row_ror:8 row_mask:0xf bank_mask:0xf
	v_pk_add_f32 v[54:55], v[54:55], v[56:57]
	v_mov_b32_e32 v57, v180
	v_pk_mul_f32 v[84:85], v[54:55], v[82:83]
	v_cvt_f32_f16_e32 v98, v25
	v_mov_b32_dpp v57, v55 row_ror:8 row_mask:0xf bank_mask:0xf
	v_pk_add_f32 v[54:55], v[54:55], v[56:57]
	v_cvt_f32_f16_e64 v56, -v27
	v_mov_b32_e32 v85, v55
	v_pk_mul_f32 v[54:55], v[84:85], s[10:11] op_sel_hi:[1,0]
	v_cvt_f32_f16_sdwa v57, -v27 dst_sel:DWORD dst_unused:UNUSED_PAD src0_sel:WORD_1
	v_mov_b32_e32 v83, v54
	v_mov_b32_e32 v84, v55
	v_cvt_f32_f16_e64 v54, -v26
	v_cvt_f32_f16_sdwa v55, -v26 dst_sel:DWORD dst_unused:UNUSED_PAD src0_sel:WORD_1
	v_cvt_f32_f16_sdwa v99, v25 dst_sel:DWORD dst_unused:UNUSED_PAD src0_sel:WORD_1
	v_exp_f32_e32 v56, v56
	v_exp_f32_e32 v54, v54
	v_exp_f32_e32 v55, v55
	v_exp_f32_e32 v57, v57
	v_mov_b32_e32 v85, v180
	v_pk_add_f32 v[94:95], v[86:87], -1.0 op_sel_hi:[1,0]
	v_pk_add_f32 v[104:105], v[98:99], -1.0 op_sel_hi:[1,0]
	ds_write_b32 v60, v82 offset:0
	v_lshlrev_b32_e32 v81, 16, v22
	v_and_b32_e32 v83, 0xffff0000, v22
	v_lshlrev_b32_e32 v92, 16, v23
	v_and_b32_e32 v96, 0xffff0000, v23
	v_lshlrev_b32_e32 v88, 16, v20
	v_and_b32_e32 v89, 0xffff0000, v20
	v_pk_fma_f32 v[94:95], v[0:1], v[94:95], 1.0 op_sel_hi:[1,1,0]
	v_lshlrev_b32_e32 v100, 16, v21
	v_and_b32_e32 v101, 0xffff0000, v21
	v_pk_fma_f32 v[104:105], v[2:3], v[104:105], 1.0 op_sel_hi:[1,1,0]
	v_lshlrev_b32_e32 v91, 16, v18
	v_and_b32_e32 v90, 0xffff0000, v18
	v_cvt_pk_f16_f32 v84, v81, v83
	v_mul_f32_e32 v93, v86, v81
	v_pk_mul_f32 v[94:95], v[94:95], v[88:89]
	v_mul_f32_e32 v97, v87, v83
	v_mul_f32_e32 v103, v98, v92
	v_pk_mul_f32 v[100:101], v[104:105], v[100:101]
	v_mul_f32_e32 v81, v99, v96
	v_cvt_pk_f16_f32 v86, v93, v97
	v_cvt_pk_f16_f32 v88, v94, v95
	v_cvt_pk_f16_f32 v87, v103, v81
	v_cvt_pk_f16_f32 v89, v100, v101
	ds_write_b128 v53, v[54:57] offset:16384
	ds_write_b32 v53, v93 offset:16896
	ds_write_b32 v53, v97 offset:16900
	ds_write_b32 v53, v103 offset:16904
	ds_write_b32 v53, v81 offset:16908
	ds_write_b64 v53, v[94:95] offset:17152
	ds_write_b64 v53, v[100:101] offset:17160
	v_mul_f32_e32 v54, v54, v91
	v_mul_f32_e32 v55, v55, v90
	v_cvt_pk_f16_f32 v85, v92, v96
	v_and_b32_e32 v88, 0xffff0000, v19
	v_lshlrev_b32_e32 v89, 16, v19
	v_cvt_pk_f16_f32 v86, v91, v90
	v_fma_f32 v54, v94, v91, 0
	v_mov_b32_e32 v92, v95
	v_mov_b32_e32 v55, v180
	v_pk_mov_b32 v[98:99], v[88:89], v[90:91] op_sel:[1,0]
	v_pk_fma_f32 v[54:55], v[92:93], v[90:91], v[54:55]
	v_mov_b32_e32 v96, v100
	v_mul_f32_e32 v56, v56, v89
	v_mul_f32_e32 v57, v57, v88
	v_pk_fma_f32 v[54:55], v[96:97], v[98:99], v[54:55]
	v_mov_b32_e32 v102, v101
	v_cvt_pk_f16_f32 v87, v89, v88
	v_pk_fma_f32 v[54:55], v[102:103], v[88:89], v[54:55]
	v_mov_b32_e32 v56, v180
	v_mul_f32_e32 v57, v81, v88
	v_lshlrev_b32_e32 v82, 16, v49
	v_mov_b32_dpp v56, v54 row_ror:1 row_mask:0xf bank_mask:0xf
	v_pk_add_f32 v[54:55], v[54:55], v[56:57]
	v_mov_b32_e32 v57, v180
	v_mov_b32_e32 v56, v180
	ds_write_b128 v53, v[84:87] offset:16640
	v_mov_b32_dpp v57, v55 row_ror:1 row_mask:0xf bank_mask:0xf
	v_mov_b32_dpp v56, v54 row_ror:2 row_mask:0xf bank_mask:0xf
	v_pk_add_f32 v[54:55], v[54:55], v[56:57]
	v_mov_b32_e32 v57, v180
	v_mov_b32_e32 v56, v180
	s_waitcnt vmcnt(6)
	v_cvt_f32_f16_e32 v86, v34
	v_mov_b32_dpp v57, v55 row_ror:2 row_mask:0xf bank_mask:0xf
	v_mov_b32_dpp v56, v54 row_ror:4 row_mask:0xf bank_mask:0xf
	v_pk_add_f32 v[54:55], v[54:55], v[56:57]
	v_mov_b32_e32 v57, v180
	v_mov_b32_e32 v56, v180
	v_cvt_f32_f16_sdwa v87, v34 dst_sel:DWORD dst_unused:UNUSED_PAD src0_sel:WORD_1
	v_mov_b32_dpp v57, v55 row_ror:4 row_mask:0xf bank_mask:0xf
	v_mov_b32_dpp v56, v54 row_ror:8 row_mask:0xf bank_mask:0xf
	v_pk_add_f32 v[54:55], v[54:55], v[56:57]
	v_mov_b32_e32 v57, v180
	v_pk_mul_f32 v[84:85], v[54:55], v[82:83]
	v_cvt_f32_f16_e32 v98, v35
	v_mov_b32_dpp v57, v55 row_ror:8 row_mask:0xf bank_mask:0xf
	v_pk_add_f32 v[54:55], v[54:55], v[56:57]
	v_cvt_f32_f16_e64 v56, -v37
	v_mov_b32_e32 v85, v55
	v_pk_mul_f32 v[54:55], v[84:85], s[10:11] op_sel_hi:[1,0]
	v_cvt_f32_f16_sdwa v57, -v37 dst_sel:DWORD dst_unused:UNUSED_PAD src0_sel:WORD_1
	v_mov_b32_e32 v83, v54
	v_mov_b32_e32 v84, v55
	v_cvt_f32_f16_e64 v54, -v36
	v_cvt_f32_f16_sdwa v55, -v36 dst_sel:DWORD dst_unused:UNUSED_PAD src0_sel:WORD_1
	v_cvt_f32_f16_sdwa v99, v35 dst_sel:DWORD dst_unused:UNUSED_PAD src0_sel:WORD_1
	v_exp_f32_e32 v56, v56
	v_exp_f32_e32 v54, v54
	v_exp_f32_e32 v55, v55
	v_exp_f32_e32 v57, v57
	v_mov_b32_e32 v85, v180
	v_pk_add_f32 v[94:95], v[86:87], -1.0 op_sel_hi:[1,0]
	v_pk_add_f32 v[104:105], v[98:99], -1.0 op_sel_hi:[1,0]
	ds_write_b32 v60, v82 offset:1024
	v_lshlrev_b32_e32 v81, 16, v32
	v_and_b32_e32 v83, 0xffff0000, v32
	v_lshlrev_b32_e32 v92, 16, v33
	v_and_b32_e32 v96, 0xffff0000, v33
	v_lshlrev_b32_e32 v88, 16, v30
	v_and_b32_e32 v89, 0xffff0000, v30
	v_pk_fma_f32 v[94:95], v[0:1], v[94:95], 1.0 op_sel_hi:[1,1,0]
	v_lshlrev_b32_e32 v100, 16, v31
	v_and_b32_e32 v101, 0xffff0000, v31
	v_pk_fma_f32 v[104:105], v[2:3], v[104:105], 1.0 op_sel_hi:[1,1,0]
	v_lshlrev_b32_e32 v91, 16, v28
	v_and_b32_e32 v90, 0xffff0000, v28
	v_cvt_pk_f16_f32 v84, v81, v83
	v_mul_f32_e32 v93, v86, v81
	v_pk_mul_f32 v[94:95], v[94:95], v[88:89]
	v_mul_f32_e32 v97, v87, v83
	v_mul_f32_e32 v103, v98, v92
	v_pk_mul_f32 v[100:101], v[104:105], v[100:101]
	v_mul_f32_e32 v81, v99, v96
	v_cvt_pk_f16_f32 v86, v93, v97
	v_cvt_pk_f16_f32 v88, v94, v95
	v_cvt_pk_f16_f32 v87, v103, v81
	v_cvt_pk_f16_f32 v89, v100, v101
	ds_write_b128 v53, v[54:57] offset:32768
	ds_write_b32 v53, v93 offset:33280
	ds_write_b32 v53, v97 offset:33284
	ds_write_b32 v53, v103 offset:33288
	ds_write_b32 v53, v81 offset:33292
	ds_write_b64 v53, v[94:95] offset:33536
	ds_write_b64 v53, v[100:101] offset:33544
	v_mul_f32_e32 v54, v54, v91
	v_mul_f32_e32 v55, v55, v90
	v_cvt_pk_f16_f32 v85, v92, v96
	v_and_b32_e32 v88, 0xffff0000, v29
	v_lshlrev_b32_e32 v89, 16, v29
	v_cvt_pk_f16_f32 v86, v91, v90
	v_fma_f32 v54, v94, v91, 0
	v_mov_b32_e32 v92, v95
	v_mov_b32_e32 v55, v180
	v_pk_mov_b32 v[98:99], v[88:89], v[90:91] op_sel:[1,0]
	v_pk_fma_f32 v[54:55], v[92:93], v[90:91], v[54:55]
	v_mov_b32_e32 v96, v100
	v_mul_f32_e32 v56, v56, v89
	v_mul_f32_e32 v57, v57, v88
	v_pk_fma_f32 v[54:55], v[96:97], v[98:99], v[54:55]
	v_mov_b32_e32 v102, v101
	v_cvt_pk_f16_f32 v87, v89, v88
	v_pk_fma_f32 v[54:55], v[102:103], v[88:89], v[54:55]
	v_mov_b32_e32 v56, v180
	v_mul_f32_e32 v57, v81, v88
	v_lshlrev_b32_e32 v82, 16, v50
	v_mov_b32_dpp v56, v54 row_ror:1 row_mask:0xf bank_mask:0xf
	v_pk_add_f32 v[54:55], v[54:55], v[56:57]
	v_mov_b32_e32 v57, v180
	v_mov_b32_e32 v56, v180
	ds_write_b128 v53, v[84:87] offset:33024
	v_mov_b32_dpp v57, v55 row_ror:1 row_mask:0xf bank_mask:0xf
	v_mov_b32_dpp v56, v54 row_ror:2 row_mask:0xf bank_mask:0xf
	v_pk_add_f32 v[54:55], v[54:55], v[56:57]
	v_mov_b32_e32 v57, v180
	v_mov_b32_e32 v56, v180
	s_waitcnt vmcnt(2)
	v_cvt_f32_f16_e32 v86, v44
	v_mov_b32_dpp v57, v55 row_ror:2 row_mask:0xf bank_mask:0xf
	v_mov_b32_dpp v56, v54 row_ror:4 row_mask:0xf bank_mask:0xf
	v_pk_add_f32 v[54:55], v[54:55], v[56:57]
	v_mov_b32_e32 v57, v180
	v_mov_b32_e32 v56, v180
	v_cvt_f32_f16_sdwa v87, v44 dst_sel:DWORD dst_unused:UNUSED_PAD src0_sel:WORD_1
	v_mov_b32_dpp v57, v55 row_ror:4 row_mask:0xf bank_mask:0xf
	v_mov_b32_dpp v56, v54 row_ror:8 row_mask:0xf bank_mask:0xf
	v_pk_add_f32 v[54:55], v[54:55], v[56:57]
	v_mov_b32_e32 v57, v180
	v_pk_mul_f32 v[84:85], v[54:55], v[82:83]
	v_cvt_f32_f16_e32 v98, v45
	v_mov_b32_dpp v57, v55 row_ror:8 row_mask:0xf bank_mask:0xf
	v_pk_add_f32 v[54:55], v[54:55], v[56:57]
	s_waitcnt vmcnt(1)
	v_cvt_f32_f16_e64 v56, -v47
	v_mov_b32_e32 v85, v55
	v_pk_mul_f32 v[54:55], v[84:85], s[10:11] op_sel_hi:[1,0]
	v_cvt_f32_f16_sdwa v57, -v47 dst_sel:DWORD dst_unused:UNUSED_PAD src0_sel:WORD_1
	v_mov_b32_e32 v83, v54
	v_mov_b32_e32 v84, v55
	v_cvt_f32_f16_e64 v54, -v46
	v_cvt_f32_f16_sdwa v55, -v46 dst_sel:DWORD dst_unused:UNUSED_PAD src0_sel:WORD_1
	v_cvt_f32_f16_sdwa v99, v45 dst_sel:DWORD dst_unused:UNUSED_PAD src0_sel:WORD_1
	v_exp_f32_e32 v56, v56
	v_exp_f32_e32 v54, v54
	v_exp_f32_e32 v55, v55
	v_exp_f32_e32 v57, v57
	v_mov_b32_e32 v85, v180
	v_pk_add_f32 v[94:95], v[86:87], -1.0 op_sel_hi:[1,0]
	v_pk_add_f32 v[104:105], v[98:99], -1.0 op_sel_hi:[1,0]
	ds_write_b32 v60, v82 offset:2048
	v_lshlrev_b32_e32 v81, 16, v42
	v_and_b32_e32 v83, 0xffff0000, v42
	v_lshlrev_b32_e32 v92, 16, v43
	v_and_b32_e32 v96, 0xffff0000, v43
	v_lshlrev_b32_e32 v88, 16, v40
	v_and_b32_e32 v89, 0xffff0000, v40
	v_pk_fma_f32 v[94:95], v[0:1], v[94:95], 1.0 op_sel_hi:[1,1,0]
	v_lshlrev_b32_e32 v100, 16, v41
	v_and_b32_e32 v101, 0xffff0000, v41
	v_pk_fma_f32 v[104:105], v[2:3], v[104:105], 1.0 op_sel_hi:[1,1,0]
	v_lshlrev_b32_e32 v91, 16, v38
	v_and_b32_e32 v90, 0xffff0000, v38
	v_cvt_pk_f16_f32 v84, v81, v83
	v_mul_f32_e32 v93, v86, v81
	v_pk_mul_f32 v[94:95], v[94:95], v[88:89]
	v_mul_f32_e32 v97, v87, v83
	v_mul_f32_e32 v103, v98, v92
	v_pk_mul_f32 v[100:101], v[104:105], v[100:101]
	v_mul_f32_e32 v81, v99, v96
	v_cvt_pk_f16_f32 v86, v93, v97
	v_cvt_pk_f16_f32 v88, v94, v95
	v_cvt_pk_f16_f32 v87, v103, v81
	v_cvt_pk_f16_f32 v89, v100, v101
	ds_write_b128 v53, v[54:57] offset:49152
	ds_write_b32 v53, v93 offset:49664
	ds_write_b32 v53, v97 offset:49668
	ds_write_b32 v53, v103 offset:49672
	ds_write_b32 v53, v81 offset:49676
	ds_write_b64 v53, v[94:95] offset:49920
	ds_write_b64 v53, v[100:101] offset:49928
	v_mul_f32_e32 v54, v54, v91
	v_mul_f32_e32 v55, v55, v90
	v_cvt_pk_f16_f32 v85, v92, v96
	v_and_b32_e32 v88, 0xffff0000, v39
	v_lshlrev_b32_e32 v89, 16, v39
	v_cvt_pk_f16_f32 v86, v91, v90
	v_fma_f32 v54, v94, v91, 0
	v_mov_b32_e32 v92, v95
	v_mov_b32_e32 v55, v180
	v_pk_mov_b32 v[98:99], v[88:89], v[90:91] op_sel:[1,0]
	v_pk_fma_f32 v[54:55], v[92:93], v[90:91], v[54:55]
	v_mov_b32_e32 v96, v100
	v_mul_f32_e32 v56, v56, v89
	v_mul_f32_e32 v57, v57, v88
	v_pk_fma_f32 v[54:55], v[96:97], v[98:99], v[54:55]
	v_mov_b32_e32 v102, v101
	v_cvt_pk_f16_f32 v87, v89, v88
	v_pk_fma_f32 v[54:55], v[102:103], v[88:89], v[54:55]
	v_mov_b32_e32 v56, v180
	v_mul_f32_e32 v57, v81, v88
	s_waitcnt vmcnt(0)
	v_lshlrev_b32_e32 v82, 16, v51
	v_mov_b32_dpp v56, v54 row_ror:1 row_mask:0xf bank_mask:0xf
	v_pk_add_f32 v[54:55], v[54:55], v[56:57]
	v_mov_b32_e32 v57, v180
	v_mov_b32_e32 v56, v180
	ds_write_b128 v53, v[84:87] offset:49408
	v_mov_b32_dpp v57, v55 row_ror:1 row_mask:0xf bank_mask:0xf
	v_mov_b32_dpp v56, v54 row_ror:2 row_mask:0xf bank_mask:0xf
	v_pk_add_f32 v[54:55], v[54:55], v[56:57]
	v_mov_b32_e32 v57, v180
	v_mov_b32_e32 v56, v180
	s_nop 0
	v_mov_b32_dpp v57, v55 row_ror:2 row_mask:0xf bank_mask:0xf
	v_mov_b32_dpp v56, v54 row_ror:4 row_mask:0xf bank_mask:0xf
	v_pk_add_f32 v[54:55], v[54:55], v[56:57]
	v_mov_b32_e32 v57, v180
	v_mov_b32_e32 v56, v180
	s_nop 0
	v_mov_b32_dpp v57, v55 row_ror:4 row_mask:0xf bank_mask:0xf
	v_mov_b32_dpp v56, v54 row_ror:8 row_mask:0xf bank_mask:0xf
	v_pk_add_f32 v[54:55], v[54:55], v[56:57]
	v_mov_b32_e32 v57, v180
	v_pk_mul_f32 v[84:85], v[54:55], v[82:83]
	s_nop 0
	v_mov_b32_dpp v57, v55 row_ror:8 row_mask:0xf bank_mask:0xf
	v_pk_add_f32 v[54:55], v[54:55], v[56:57]
	s_nop 0
	v_mov_b32_e32 v85, v55
	v_pk_mul_f32 v[54:55], v[84:85], s[10:11] op_sel_hi:[1,0]
	v_mov_b32_e32 v85, v180
	v_mov_b32_e32 v83, v54
	v_mov_b32_e32 v84, v55
	ds_write_b32 v60, v82 offset:3072

	.amdhsa_kernel _Z10fwd_kernel6Params
		.amdhsa_group_segment_fixed_size 8704
		.amdhsa_private_segment_fixed_size 0
		.amdhsa_kernarg_size 536
		.amdhsa_user_sgpr_count 2
		.amdhsa_user_sgpr_dispatch_ptr 0
		.amdhsa_user_sgpr_queue_ptr 0
		.amdhsa_user_sgpr_kernarg_segment_ptr 1
		.amdhsa_user_sgpr_dispatch_id 0
		.amdhsa_user_sgpr_kernarg_preload_length 0
		.amdhsa_user_sgpr_kernarg_preload_offset 0
		.amdhsa_user_sgpr_private_segment_size 0
		.amdhsa_uses_dynamic_stack 0
		.amdhsa_enable_private_segment 0
		.amdhsa_system_sgpr_workgroup_id_x 1
		.amdhsa_system_sgpr_workgroup_id_y 0
		.amdhsa_system_sgpr_workgroup_id_z 0
		.amdhsa_system_sgpr_workgroup_info 0
		.amdhsa_system_vgpr_workitem_id 2
		.amdhsa_next_free_vgpr 244
		.amdhsa_next_free_sgpr 102
		.amdhsa_accum_offset 244
		.amdhsa_reserve_vcc 1
		.amdhsa_float_round_mode_32 0
		.amdhsa_float_round_mode_16_64 0
		.amdhsa_float_denorm_mode_32 3
		.amdhsa_float_denorm_mode_16_64 3
		.amdhsa_dx10_clamp 1
		.amdhsa_ieee_mode 1
		.amdhsa_fp16_overflow 0
		.amdhsa_tg_split 0
		.amdhsa_exception_fp_ieee_invalid_op 0
		.amdhsa_exception_fp_denorm_src 0
		.amdhsa_exception_fp_ieee_div_zero 0
		.amdhsa_exception_fp_ieee_overflow 0
		.amdhsa_exception_fp_ieee_underflow 0
		.amdhsa_exception_fp_ieee_inexact 0
		.amdhsa_exception_int_div_zero 0
	.end_amdhsa_kernel

amdhsa.kernels:
  - .agpr_count:     0
    .args:
      - .offset:         0
        .size:           280
        .value_kind:     by_value
      - .offset:         280
        .size:           4
        .value_kind:     hidden_block_count_x
      - .offset:         284
        .size:           4
        .value_kind:     hidden_block_count_y
      - .offset:         288
        .size:           4
        .value_kind:     hidden_block_count_z
      - .offset:         292
        .size:           2
        .value_kind:     hidden_group_size_x
      - .offset:         294
        .size:           2
        .value_kind:     hidden_group_size_y
      - .offset:         296
        .size:           2
        .value_kind:     hidden_group_size_z
      - .offset:         298
        .size:           2
        .value_kind:     hidden_remainder_x
      - .offset:         300
        .size:           2
        .value_kind:     hidden_remainder_y
      - .offset:         302
        .size:           2
        .value_kind:     hidden_remainder_z
      - .offset:         320
        .size:           8
        .value_kind:     hidden_global_offset_x
      - .offset:         328
        .size:           8
        .value_kind:     hidden_global_offset_y
      - .offset:         336
        .size:           8
        .value_kind:     hidden_global_offset_z
      - .offset:         344
        .size:           2
        .value_kind:     hidden_grid_dims
      - .offset:         368
        .size:           8
        .value_kind:     hidden_multigrid_sync_arg
      - .offset:         400
        .size:           4
        .value_kind:     hidden_dynamic_lds_size
    .group_segment_fixed_size: 8704
    .kernarg_segment_align: 8
    .kernarg_segment_size: 536
    .language:       OpenCL C
    .language_version:
      - 2
      - 0
    .max_flat_workgroup_size: 512
    .name:           _Z10fwd_kernel6Params
    .private_segment_fixed_size: 0
    .sgpr_count:     106
    .sgpr_spill_count: 205
    .symbol:         _Z10fwd_kernel6Params.kd
    .uniform_work_group_size: 1
    .uses_dynamic_stack: false
    .vgpr_count:     244
    .vgpr_spill_count: 0
    .wavefront_size: 64
